# all 16 GEMM K loops: As[0][0] LDS-DMA pair moved from the SP2(t) load segment to the head of the next SP1 segment (saddr form), SP2(t) wait vmcnt(6)
# speedup vs baseline: 1.0065x; 1.0044x over previous
.LBB0_289:
	ds_read_b128 v[170:173], v167
	ds_read_b128 v[174:177], v167 offset:1024
	ds_read_b128 v[178:181], v167 offset:2048
	ds_read_b128 v[182:185], v167 offset:3072
	ds_read_b128 v[186:189], v168
	ds_read_b128 v[190:193], v168 offset:1024
	ds_read_b128 v[194:197], v168 offset:2048
	ds_read_b128 v[198:201], v168 offset:3072
	s_add_u32 s26, s24, 0xfffc0080
	s_addc_u32 s27, s25, -1
	s_cmp_eq_u32 s54, 12
	s_cselect_b32 s29, s13, s27
	s_cselect_b32 s28, s50, s26
	s_cselect_b32 s27, s15, s53
	s_cselect_b32 s26, s51, s52
	v_lshl_add_u64 v[164:165], s[24:25], 0, v[158:159]
	s_add_i32 m0, s21, 0xc000
	ds_read_b128 v[210:213], v169
	ds_read_b128 v[214:217], v169 offset:1024
	ds_read_b128 v[218:221], v169 offset:2048
	ds_read_b128 v[222:225], v169 offset:3072
	ds_read_b128 v[226:229], v169 offset:4096
	ds_read_b128 v[230:233], v169 offset:5120
	ds_read_b128 v[234:237], v169 offset:6144
	ds_read_b128 v[238:241], v169 offset:7168
	global_load_lds_dwordx4 v[164:165], off
	v_lshl_add_u64 v[164:165], s[24:25], 0, v[156:157]
	s_add_i32 m0, s21, 0xe000
	s_nop 0
	global_load_lds_dwordx4 v[164:165], off
	s_waitcnt vmcnt(8)
	s_waitcnt lgkmcnt(0)
	s_barrier
	s_setprio 1
	s_waitcnt lgkmcnt(0)
	v_mfma_f32_16x16x32_bf16 v[124:127], v[170:173], v[210:213], v[124:127]
	v_mfma_f32_16x16x32_bf16 v[116:119], v[178:181], v[210:213], v[116:119]
	v_mfma_f32_16x16x32_bf16 v[108:111], v[170:173], v[218:221], v[108:111]
	v_mfma_f32_16x16x32_bf16 v[100:103], v[178:181], v[218:221], v[100:103]
	v_mfma_f32_16x16x32_bf16 v[92:95], v[170:173], v[226:229], v[92:95]
	v_mfma_f32_16x16x32_bf16 v[84:87], v[178:181], v[226:229], v[84:87]
	v_mfma_f32_16x16x32_bf16 v[76:79], v[170:173], v[234:237], v[76:79]
	v_mfma_f32_16x16x32_bf16 v[68:71], v[178:181], v[234:237], v[68:71]
	v_mfma_f32_16x16x32_bf16 v[124:127], v[174:177], v[214:217], v[124:127]
	v_mfma_f32_16x16x32_bf16 v[116:119], v[182:185], v[214:217], v[116:119]
	v_mfma_f32_16x16x32_bf16 v[108:111], v[174:177], v[222:225], v[108:111]
	v_mfma_f32_16x16x32_bf16 v[100:103], v[182:185], v[222:225], v[100:103]
	v_mfma_f32_16x16x32_bf16 v[92:95], v[174:177], v[230:233], v[92:95]
	v_mfma_f32_16x16x32_bf16 v[84:87], v[182:185], v[230:233], v[84:87]
	v_mfma_f32_16x16x32_bf16 v[76:79], v[174:177], v[238:241], v[76:79]
	v_mfma_f32_16x16x32_bf16 v[68:71], v[182:185], v[238:241], v[68:71]
	s_setprio 0
	s_setprio 1
	v_mfma_f32_16x16x32_bf16 v[120:123], v[186:189], v[210:213], v[120:123]
	v_mfma_f32_16x16x32_bf16 v[112:115], v[194:197], v[210:213], v[112:115]
	v_mfma_f32_16x16x32_bf16 v[104:107], v[186:189], v[218:221], v[104:107]
	v_mfma_f32_16x16x32_bf16 v[96:99], v[194:197], v[218:221], v[96:99]
	v_mfma_f32_16x16x32_bf16 v[88:91], v[186:189], v[226:229], v[88:91]
	v_mfma_f32_16x16x32_bf16 v[80:83], v[194:197], v[226:229], v[80:83]
	v_mfma_f32_16x16x32_bf16 v[72:75], v[186:189], v[234:237], v[72:75]
	v_mfma_f32_16x16x32_bf16 v[64:67], v[194:197], v[234:237], v[64:67]
	v_mfma_f32_16x16x32_bf16 v[120:123], v[190:193], v[214:217], v[120:123]
	v_mfma_f32_16x16x32_bf16 v[112:115], v[198:201], v[214:217], v[112:115]
	v_mfma_f32_16x16x32_bf16 v[104:107], v[190:193], v[222:225], v[104:107]
	v_mfma_f32_16x16x32_bf16 v[96:99], v[198:201], v[222:225], v[96:99]
	v_mfma_f32_16x16x32_bf16 v[88:91], v[190:193], v[230:233], v[88:91]
	v_mfma_f32_16x16x32_bf16 v[80:83], v[198:201], v[230:233], v[80:83]
	v_mfma_f32_16x16x32_bf16 v[72:75], v[190:193], v[238:241], v[72:75]
	v_mfma_f32_16x16x32_bf16 v[64:67], v[198:201], v[238:241], v[64:67]
	s_setprio 0
	s_barrier
	s_add_i32 s55, s48, s38
	v_lshl_add_u64 v[164:165], s[26:27], 0, v[134:135]
	s_mov_b32 m0, s55
	ds_read_b128 v[210:213], v169 offset:16384
	ds_read_b128 v[214:217], v169 offset:17408
	ds_read_b128 v[218:221], v169 offset:18432
	ds_read_b128 v[222:225], v169 offset:19456
	ds_read_b128 v[226:229], v169 offset:20480
	ds_read_b128 v[230:233], v169 offset:21504
	ds_read_b128 v[234:237], v169 offset:22528
	ds_read_b128 v[238:241], v169 offset:23552
	global_load_lds_dwordx4 v[164:165], off
	s_add_i32 m0, s55, 0x2000
	s_add_u32 s56, s26, 0x4000
	v_lshl_add_u64 v[164:165], s[26:27], 0, v[130:131]
	s_addc_u32 s57, s27, 0
	s_add_i32 s55, s49, s38
	global_load_lds_dwordx4 v[164:165], off
	v_lshl_add_u64 v[164:165], s[56:57], 0, v[134:135]
	s_mov_b32 m0, s55
	v_lshl_add_u64 v[242:243], s[28:29], 0, v[132:133]
	global_load_lds_dwordx4 v[164:165], off
	v_lshl_add_u64 v[164:165], s[56:57], 0, v[130:131]
	s_add_i32 m0, s55, 0x2000
	s_nop 0
	global_load_lds_dwordx4 v[164:165], off
	v_lshl_add_u64 v[164:165], s[28:29], 0, v[136:137]
	s_waitcnt vmcnt(6)
	s_waitcnt lgkmcnt(0)
	s_barrier
	s_setprio 1
	s_waitcnt lgkmcnt(0)
	v_mfma_f32_16x16x32_bf16 v[60:63], v[170:173], v[210:213], v[60:63]
	v_mfma_f32_16x16x32_bf16 v[52:55], v[178:181], v[210:213], v[52:55]
	v_mfma_f32_16x16x32_bf16 v[44:47], v[170:173], v[218:221], v[44:47]
	v_mfma_f32_16x16x32_bf16 v[36:39], v[178:181], v[218:221], v[36:39]
	v_mfma_f32_16x16x32_bf16 v[28:31], v[170:173], v[226:229], v[28:31]
	v_mfma_f32_16x16x32_bf16 v[20:23], v[178:181], v[226:229], v[20:23]
	v_mfma_f32_16x16x32_bf16 v[12:15], v[170:173], v[234:237], v[12:15]
	v_mfma_f32_16x16x32_bf16 v[4:7], v[178:181], v[234:237], v[4:7]
	v_mfma_f32_16x16x32_bf16 v[60:63], v[174:177], v[214:217], v[60:63]
	v_mfma_f32_16x16x32_bf16 v[52:55], v[182:185], v[214:217], v[52:55]
	v_mfma_f32_16x16x32_bf16 v[44:47], v[174:177], v[222:225], v[44:47]
	v_mfma_f32_16x16x32_bf16 v[36:39], v[182:185], v[222:225], v[36:39]
	v_mfma_f32_16x16x32_bf16 v[28:31], v[174:177], v[230:233], v[28:31]
	v_mfma_f32_16x16x32_bf16 v[20:23], v[182:185], v[230:233], v[20:23]
	v_mfma_f32_16x16x32_bf16 v[12:15], v[174:177], v[238:241], v[12:15]
	v_mfma_f32_16x16x32_bf16 v[4:7], v[182:185], v[238:241], v[4:7]
	s_setprio 0
	s_setprio 1
	v_mfma_f32_16x16x32_bf16 v[56:59], v[186:189], v[210:213], v[56:59]
	v_mfma_f32_16x16x32_bf16 v[48:51], v[194:197], v[210:213], v[48:51]
	v_mfma_f32_16x16x32_bf16 v[40:43], v[186:189], v[218:221], v[40:43]
	v_mfma_f32_16x16x32_bf16 v[32:35], v[194:197], v[218:221], v[32:35]
	v_mfma_f32_16x16x32_bf16 v[24:27], v[186:189], v[226:229], v[24:27]
	v_mfma_f32_16x16x32_bf16 v[16:19], v[194:197], v[226:229], v[16:19]
	v_mfma_f32_16x16x32_bf16 v[8:11], v[186:189], v[234:237], v[8:11]
	v_mfma_f32_16x16x32_bf16 v[0:3], v[194:197], v[234:237], v[0:3]
	v_mfma_f32_16x16x32_bf16 v[56:59], v[190:193], v[214:217], v[56:59]
	v_mfma_f32_16x16x32_bf16 v[48:51], v[198:201], v[214:217], v[48:51]
	v_mfma_f32_16x16x32_bf16 v[40:43], v[190:193], v[222:225], v[40:43]
	v_mfma_f32_16x16x32_bf16 v[32:35], v[198:201], v[222:225], v[32:35]
	v_mfma_f32_16x16x32_bf16 v[24:27], v[190:193], v[230:233], v[24:27]
	v_mfma_f32_16x16x32_bf16 v[16:19], v[198:201], v[230:233], v[16:19]
	v_mfma_f32_16x16x32_bf16 v[8:11], v[190:193], v[238:241], v[8:11]
	v_mfma_f32_16x16x32_bf16 v[0:3], v[198:201], v[238:241], v[0:3]
	s_setprio 0
	s_barrier
	s_mov_b32 m0, s21
	s_nop 0
	global_load_lds_dwordx4 v136, s[28:29]
	s_mov_b32 m0, s23
	s_nop 0
	global_load_lds_dwordx4 v132, s[28:29]
	s_add_i32 s55, 0, 0x18000
	s_add_i32 s56, 0, 0x1c000
	v_add_u32_e32 v182, s55, v129
	v_add_u32_e32 v198, s56, v129
	ds_read_b128 v[170:173], v182
	ds_read_b128 v[174:177], v182 offset:1024
	ds_read_b128 v[178:181], v182 offset:2048
	ds_read_b128 v[182:185], v182 offset:3072
	ds_read_b128 v[186:189], v198
	ds_read_b128 v[190:193], v198 offset:1024
	ds_read_b128 v[194:197], v198 offset:2048
	ds_read_b128 v[198:201], v198 offset:3072
	s_add_u32 s28, s28, 0x40000
	s_addc_u32 s29, s29, 0
	s_mov_b32 m0, s41
	v_lshl_add_u64 v[244:245], s[28:29], 0, v[136:137]
	ds_read_b128 v[210:213], v169 offset:32768
	ds_read_b128 v[214:217], v169 offset:33792
	ds_read_b128 v[218:221], v169 offset:34816
	ds_read_b128 v[222:225], v169 offset:35840
	ds_read_b128 v[226:229], v169 offset:36864
	ds_read_b128 v[230:233], v169 offset:37888
	ds_read_b128 v[234:237], v169 offset:38912
	ds_read_b128 v[238:241], v169 offset:39936
	global_load_lds_dwordx4 v[244:245], off
	v_lshl_add_u64 v[244:245], s[28:29], 0, v[132:133]
	s_mov_b32 m0, s42
	s_nop 0
	global_load_lds_dwordx4 v[244:245], off
	s_waitcnt vmcnt(8)
	s_waitcnt lgkmcnt(0)
	s_barrier
	s_setprio 1
	s_waitcnt lgkmcnt(0)
	v_mfma_f32_16x16x32_bf16 v[124:127], v[170:173], v[210:213], v[124:127]
	v_mfma_f32_16x16x32_bf16 v[116:119], v[178:181], v[210:213], v[116:119]
	v_mfma_f32_16x16x32_bf16 v[108:111], v[170:173], v[218:221], v[108:111]
	v_mfma_f32_16x16x32_bf16 v[100:103], v[178:181], v[218:221], v[100:103]
	v_mfma_f32_16x16x32_bf16 v[92:95], v[170:173], v[226:229], v[92:95]
	v_mfma_f32_16x16x32_bf16 v[84:87], v[178:181], v[226:229], v[84:87]
	v_mfma_f32_16x16x32_bf16 v[76:79], v[170:173], v[234:237], v[76:79]
	v_mfma_f32_16x16x32_bf16 v[68:71], v[178:181], v[234:237], v[68:71]
	v_mfma_f32_16x16x32_bf16 v[124:127], v[174:177], v[214:217], v[124:127]
	v_mfma_f32_16x16x32_bf16 v[116:119], v[182:185], v[214:217], v[116:119]
	v_mfma_f32_16x16x32_bf16 v[108:111], v[174:177], v[222:225], v[108:111]
	v_mfma_f32_16x16x32_bf16 v[100:103], v[182:185], v[222:225], v[100:103]
	v_mfma_f32_16x16x32_bf16 v[92:95], v[174:177], v[230:233], v[92:95]
	v_mfma_f32_16x16x32_bf16 v[84:87], v[182:185], v[230:233], v[84:87]
	v_mfma_f32_16x16x32_bf16 v[76:79], v[174:177], v[238:241], v[76:79]
	v_mfma_f32_16x16x32_bf16 v[68:71], v[182:185], v[238:241], v[68:71]
	s_setprio 0
	s_setprio 1
	v_mfma_f32_16x16x32_bf16 v[120:123], v[186:189], v[210:213], v[120:123]
	v_mfma_f32_16x16x32_bf16 v[112:115], v[194:197], v[210:213], v[112:115]
	v_mfma_f32_16x16x32_bf16 v[104:107], v[186:189], v[218:221], v[104:107]
	v_mfma_f32_16x16x32_bf16 v[96:99], v[194:197], v[218:221], v[96:99]
	v_mfma_f32_16x16x32_bf16 v[88:91], v[186:189], v[226:229], v[88:91]
	v_mfma_f32_16x16x32_bf16 v[80:83], v[194:197], v[226:229], v[80:83]
	v_mfma_f32_16x16x32_bf16 v[72:75], v[186:189], v[234:237], v[72:75]
	v_mfma_f32_16x16x32_bf16 v[64:67], v[194:197], v[234:237], v[64:67]
	v_mfma_f32_16x16x32_bf16 v[120:123], v[190:193], v[214:217], v[120:123]
	v_mfma_f32_16x16x32_bf16 v[112:115], v[198:201], v[214:217], v[112:115]
	v_mfma_f32_16x16x32_bf16 v[104:107], v[190:193], v[222:225], v[104:107]
	v_mfma_f32_16x16x32_bf16 v[96:99], v[198:201], v[222:225], v[96:99]
	v_mfma_f32_16x16x32_bf16 v[88:91], v[190:193], v[230:233], v[88:91]
	v_mfma_f32_16x16x32_bf16 v[80:83], v[198:201], v[230:233], v[80:83]
	v_mfma_f32_16x16x32_bf16 v[72:75], v[190:193], v[238:241], v[72:75]
	v_mfma_f32_16x16x32_bf16 v[64:67], v[198:201], v[238:241], v[64:67]
	s_setprio 0
	s_barrier
	s_add_u32 s28, s26, 0x8000
	s_addc_u32 s29, s27, 0
	s_add_i32 s55, s55, s38
	v_lshl_add_u64 v[244:245], s[28:29], 0, v[134:135]
	s_mov_b32 m0, s55
	ds_read_b128 v[210:213], v169 offset:49152
	ds_read_b128 v[214:217], v169 offset:50176
	ds_read_b128 v[218:221], v169 offset:51200
	ds_read_b128 v[222:225], v169 offset:52224
	ds_read_b128 v[226:229], v169 offset:53248
	ds_read_b128 v[230:233], v169 offset:54272
	ds_read_b128 v[234:237], v169 offset:55296
	ds_read_b128 v[238:241], v169 offset:56320
	global_load_lds_dwordx4 v[244:245], off
	s_add_i32 m0, s55, 0x2000
	s_add_u32 s26, s26, 0xc000
	v_lshl_add_u64 v[244:245], s[28:29], 0, v[130:131]
	s_addc_u32 s27, s27, 0
	s_add_i32 s28, s56, s38
	global_load_lds_dwordx4 v[244:245], off
	v_lshl_add_u64 v[244:245], s[26:27], 0, v[134:135]
	s_mov_b32 m0, s28
	v_lshl_add_u64 v[164:165], v[164:165], 0, s[8:9]
	global_load_lds_dwordx4 v[244:245], off
	v_lshl_add_u64 v[244:245], s[26:27], 0, v[130:131]
	s_add_i32 m0, s28, 0x2000
	s_nop 0
	global_load_lds_dwordx4 v[244:245], off
	s_mov_b32 m0, s45
	s_nop 0
	global_load_lds_dwordx4 v[164:165], off
	v_lshl_add_u64 v[164:165], v[242:243], 0, s[8:9]
	s_mov_b32 m0, s46
	s_nop 0
	global_load_lds_dwordx4 v[164:165], off
	s_waitcnt vmcnt(8)
	s_waitcnt lgkmcnt(0)
	s_barrier
	s_setprio 1
	s_waitcnt lgkmcnt(0)
	v_mfma_f32_16x16x32_bf16 v[60:63], v[170:173], v[210:213], v[60:63]
	v_mfma_f32_16x16x32_bf16 v[52:55], v[178:181], v[210:213], v[52:55]
	v_mfma_f32_16x16x32_bf16 v[44:47], v[170:173], v[218:221], v[44:47]
	v_mfma_f32_16x16x32_bf16 v[36:39], v[178:181], v[218:221], v[36:39]
	v_mfma_f32_16x16x32_bf16 v[28:31], v[170:173], v[226:229], v[28:31]
	v_mfma_f32_16x16x32_bf16 v[20:23], v[178:181], v[226:229], v[20:23]
	v_mfma_f32_16x16x32_bf16 v[12:15], v[170:173], v[234:237], v[12:15]
	v_mfma_f32_16x16x32_bf16 v[4:7], v[178:181], v[234:237], v[4:7]
	v_mfma_f32_16x16x32_bf16 v[60:63], v[174:177], v[214:217], v[60:63]
	v_mfma_f32_16x16x32_bf16 v[52:55], v[182:185], v[214:217], v[52:55]
	v_mfma_f32_16x16x32_bf16 v[44:47], v[174:177], v[222:225], v[44:47]
	v_mfma_f32_16x16x32_bf16 v[36:39], v[182:185], v[222:225], v[36:39]
	v_mfma_f32_16x16x32_bf16 v[28:31], v[174:177], v[230:233], v[28:31]
	v_mfma_f32_16x16x32_bf16 v[20:23], v[182:185], v[230:233], v[20:23]
	v_mfma_f32_16x16x32_bf16 v[12:15], v[174:177], v[238:241], v[12:15]
	v_mfma_f32_16x16x32_bf16 v[4:7], v[182:185], v[238:241], v[4:7]
	s_setprio 0
	s_setprio 1
	v_mfma_f32_16x16x32_bf16 v[56:59], v[186:189], v[210:213], v[56:59]
	v_mfma_f32_16x16x32_bf16 v[48:51], v[194:197], v[210:213], v[48:51]
	v_mfma_f32_16x16x32_bf16 v[40:43], v[186:189], v[218:221], v[40:43]
	v_mfma_f32_16x16x32_bf16 v[32:35], v[194:197], v[218:221], v[32:35]
	v_mfma_f32_16x16x32_bf16 v[24:27], v[186:189], v[226:229], v[24:27]
	v_mfma_f32_16x16x32_bf16 v[16:19], v[194:197], v[226:229], v[16:19]
	v_mfma_f32_16x16x32_bf16 v[8:11], v[186:189], v[234:237], v[8:11]
	v_mfma_f32_16x16x32_bf16 v[0:3], v[194:197], v[234:237], v[0:3]
	v_mfma_f32_16x16x32_bf16 v[56:59], v[190:193], v[214:217], v[56:59]
	v_mfma_f32_16x16x32_bf16 v[48:51], v[198:201], v[214:217], v[48:51]
	v_mfma_f32_16x16x32_bf16 v[40:43], v[190:193], v[222:225], v[40:43]
	v_mfma_f32_16x16x32_bf16 v[32:35], v[198:201], v[222:225], v[32:35]
	v_mfma_f32_16x16x32_bf16 v[24:27], v[190:193], v[230:233], v[24:27]
	v_mfma_f32_16x16x32_bf16 v[16:19], v[198:201], v[230:233], v[16:19]
	v_mfma_f32_16x16x32_bf16 v[8:11], v[190:193], v[238:241], v[8:11]
	v_mfma_f32_16x16x32_bf16 v[0:3], v[198:201], v[238:241], v[0:3]
	s_setprio 0
	s_barrier
	s_add_i32 s54, s54, 2
	s_add_u32 s52, s52, 0x10000
	s_addc_u32 s53, s53, 0
	s_add_u32 s24, s24, 0x100
	s_addc_u32 s25, s25, 0
	s_cmp_gt_u32 s54, 13
	s_cbranch_scc0 .LBB0_289
	s_and_b64 vcc, exec, s[10:11]
	s_cbranch_vccz .LBB0_292
	s_barrier

.LBB0_408:
	v_add_u32_e32 v168, s71, v182
	v_add_u32_e32 v204, s72, v182
	ds_read_b128 v[156:159], v168
	ds_read_b128 v[160:163], v168 offset:1024
	ds_read_b128 v[164:167], v168 offset:2048
	ds_read_b128 v[168:171], v168 offset:3072
	ds_read_b128 v[172:175], v204
	ds_read_b128 v[176:179], v204 offset:1024
	ds_read_b128 v[212:215], v204 offset:2048
	ds_read_b128 v[216:219], v204 offset:3072
	s_add_u32 s40, s38, 0x4000
	s_addc_u32 s41, s39, 0
	s_cmp_eq_u32 s49, 40
	s_cselect_b32 s44, s0, s40
	s_cselect_b32 s45, s1, s41
	s_cselect_b32 s42, s36, s47
	s_cselect_b32 s43, s37, s48
	s_add_u32 s40, s44, 0x8000
	s_addc_u32 s41, s45, 0
	v_lshl_add_u64 v[252:253], s[38:39], 0, v[150:151]
	s_add_i32 m0, s58, 0xc000
	ds_read_b128 v[220:223], v199
	ds_read_b128 v[224:227], v199 offset:1024
	ds_read_b128 v[228:231], v199 offset:2048
	ds_read_b128 v[232:235], v199 offset:3072
	ds_read_b128 v[236:239], v199 offset:4096
	ds_read_b128 v[240:243], v199 offset:5120
	ds_read_b128 v[244:247], v199 offset:6144
	ds_read_b128 v[248:251], v199 offset:7168
	global_load_lds_dwordx4 v[252:253], off
	v_lshl_add_u64 v[252:253], s[38:39], 0, v[148:149]
	s_add_i32 m0, s58, 0xe000
	s_nop 0
	global_load_lds_dwordx4 v[252:253], off
	s_waitcnt vmcnt(8)
	s_waitcnt lgkmcnt(0)
	s_barrier
	s_setprio 1
	s_waitcnt lgkmcnt(0)
	v_mfma_f32_16x16x32_bf16 v[124:127], v[156:159], v[220:223], v[124:127]
	v_mfma_f32_16x16x32_bf16 v[120:123], v[164:167], v[220:223], v[120:123]
	v_mfma_f32_16x16x32_bf16 v[116:119], v[156:159], v[228:231], v[116:119]
	v_mfma_f32_16x16x32_bf16 v[108:111], v[164:167], v[228:231], v[108:111]
	v_mfma_f32_16x16x32_bf16 v[92:95], v[156:159], v[236:239], v[92:95]
	v_mfma_f32_16x16x32_bf16 v[88:91], v[164:167], v[236:239], v[88:91]
	v_mfma_f32_16x16x32_bf16 v[84:87], v[156:159], v[244:247], v[84:87]
	v_mfma_f32_16x16x32_bf16 v[76:79], v[164:167], v[244:247], v[76:79]
	v_mfma_f32_16x16x32_bf16 v[124:127], v[160:163], v[224:227], v[124:127]
	v_mfma_f32_16x16x32_bf16 v[120:123], v[168:171], v[224:227], v[120:123]
	v_mfma_f32_16x16x32_bf16 v[116:119], v[160:163], v[232:235], v[116:119]
	v_mfma_f32_16x16x32_bf16 v[108:111], v[168:171], v[232:235], v[108:111]
	v_mfma_f32_16x16x32_bf16 v[92:95], v[160:163], v[240:243], v[92:95]
	v_mfma_f32_16x16x32_bf16 v[88:91], v[168:171], v[240:243], v[88:91]
	v_mfma_f32_16x16x32_bf16 v[84:87], v[160:163], v[248:251], v[84:87]
	v_mfma_f32_16x16x32_bf16 v[76:79], v[168:171], v[248:251], v[76:79]
	s_setprio 0
	s_setprio 1
	v_mfma_f32_16x16x32_bf16 v[112:115], v[172:175], v[220:223], v[112:115]
	v_mfma_f32_16x16x32_bf16 v[104:107], v[212:215], v[220:223], v[104:107]
	v_mfma_f32_16x16x32_bf16 v[100:103], v[172:175], v[228:231], v[100:103]
	v_mfma_f32_16x16x32_bf16 v[96:99], v[212:215], v[228:231], v[96:99]
	v_mfma_f32_16x16x32_bf16 v[80:83], v[172:175], v[236:239], v[80:83]
	v_mfma_f32_16x16x32_bf16 v[72:75], v[212:215], v[236:239], v[72:75]
	v_mfma_f32_16x16x32_bf16 v[68:71], v[172:175], v[244:247], v[68:71]
	v_mfma_f32_16x16x32_bf16 v[64:67], v[212:215], v[244:247], v[64:67]
	v_mfma_f32_16x16x32_bf16 v[112:115], v[176:179], v[224:227], v[112:115]
	v_mfma_f32_16x16x32_bf16 v[104:107], v[216:219], v[224:227], v[104:107]
	v_mfma_f32_16x16x32_bf16 v[100:103], v[176:179], v[232:235], v[100:103]
	v_mfma_f32_16x16x32_bf16 v[96:99], v[216:219], v[232:235], v[96:99]
	v_mfma_f32_16x16x32_bf16 v[80:83], v[176:179], v[240:243], v[80:83]
	v_mfma_f32_16x16x32_bf16 v[72:75], v[216:219], v[240:243], v[72:75]
	v_mfma_f32_16x16x32_bf16 v[68:71], v[176:179], v[248:251], v[68:71]
	v_mfma_f32_16x16x32_bf16 v[64:67], v[216:219], v[248:251], v[64:67]
	s_setprio 0
	s_barrier
	s_add_i32 s50, s71, s57
	v_lshl_add_u64 v[252:253], s[42:43], 0, v[128:129]
	s_mov_b32 m0, s50
	ds_read_b128 v[220:223], v199 offset:16384
	ds_read_b128 v[224:227], v199 offset:17408
	ds_read_b128 v[228:231], v199 offset:18432
	ds_read_b128 v[232:235], v199 offset:19456
	ds_read_b128 v[236:239], v199 offset:20480
	ds_read_b128 v[240:243], v199 offset:21504
	ds_read_b128 v[244:247], v199 offset:22528
	ds_read_b128 v[248:251], v199 offset:23552
	global_load_lds_dwordx4 v[252:253], off
	s_add_i32 m0, s50, 0x2000
	s_add_u32 s50, s42, 0x4000
	v_lshl_add_u64 v[252:253], s[42:43], 0, v[130:131]
	s_addc_u32 s51, s43, 0
	s_add_i32 s52, s72, s57
	global_load_lds_dwordx4 v[252:253], off
	v_lshl_add_u64 v[252:253], s[50:51], 0, v[128:129]
	s_mov_b32 m0, s52
	s_nop 0
	global_load_lds_dwordx4 v[252:253], off
	v_lshl_add_u64 v[252:253], s[50:51], 0, v[130:131]
	s_add_i32 m0, s52, 0x2000
	s_nop 0
	global_load_lds_dwordx4 v[252:253], off
	v_lshl_add_u64 v[252:253], s[44:45], 0, v[128:129]
	v_lshl_add_u64 v[252:253], s[44:45], 0, v[130:131]
	s_waitcnt vmcnt(6)
	s_waitcnt lgkmcnt(0)
	s_barrier
	s_setprio 1
	s_waitcnt lgkmcnt(0)
	v_mfma_f32_16x16x32_bf16 v[60:63], v[156:159], v[220:223], v[60:63]
	v_mfma_f32_16x16x32_bf16 v[56:59], v[164:167], v[220:223], v[56:59]
	v_mfma_f32_16x16x32_bf16 v[52:55], v[156:159], v[228:231], v[52:55]
	v_mfma_f32_16x16x32_bf16 v[44:47], v[164:167], v[228:231], v[44:47]
	v_mfma_f32_16x16x32_bf16 v[32:35], v[156:159], v[236:239], v[32:35]
	v_mfma_f32_16x16x32_bf16 v[24:27], v[164:167], v[236:239], v[24:27]
	v_mfma_f32_16x16x32_bf16 v[20:23], v[156:159], v[244:247], v[20:23]
	v_mfma_f32_16x16x32_bf16 v[12:15], v[164:167], v[244:247], v[12:15]
	v_mfma_f32_16x16x32_bf16 v[60:63], v[160:163], v[224:227], v[60:63]
	v_mfma_f32_16x16x32_bf16 v[56:59], v[168:171], v[224:227], v[56:59]
	v_mfma_f32_16x16x32_bf16 v[52:55], v[160:163], v[232:235], v[52:55]
	v_mfma_f32_16x16x32_bf16 v[44:47], v[168:171], v[232:235], v[44:47]
	v_mfma_f32_16x16x32_bf16 v[32:35], v[160:163], v[240:243], v[32:35]
	v_mfma_f32_16x16x32_bf16 v[24:27], v[168:171], v[240:243], v[24:27]
	v_mfma_f32_16x16x32_bf16 v[20:23], v[160:163], v[248:251], v[20:23]
	v_mfma_f32_16x16x32_bf16 v[12:15], v[168:171], v[248:251], v[12:15]
	s_setprio 0
	s_setprio 1
	v_mfma_f32_16x16x32_bf16 v[48:51], v[172:175], v[220:223], v[48:51]
	v_mfma_f32_16x16x32_bf16 v[40:43], v[212:215], v[220:223], v[40:43]
	v_mfma_f32_16x16x32_bf16 v[36:39], v[172:175], v[228:231], v[36:39]
	v_mfma_f32_16x16x32_bf16 v[28:31], v[212:215], v[228:231], v[28:31]
	v_mfma_f32_16x16x32_bf16 v[16:19], v[172:175], v[236:239], v[16:19]
	v_mfma_f32_16x16x32_bf16 v[8:11], v[212:215], v[236:239], v[8:11]
	v_mfma_f32_16x16x32_bf16 v[4:7], v[172:175], v[244:247], v[4:7]
	v_mfma_f32_16x16x32_bf16 v[0:3], v[212:215], v[244:247], v[0:3]
	v_mfma_f32_16x16x32_bf16 v[48:51], v[176:179], v[224:227], v[48:51]
	v_mfma_f32_16x16x32_bf16 v[40:43], v[216:219], v[224:227], v[40:43]
	v_mfma_f32_16x16x32_bf16 v[36:39], v[176:179], v[232:235], v[36:39]
	v_mfma_f32_16x16x32_bf16 v[28:31], v[216:219], v[232:235], v[28:31]
	v_mfma_f32_16x16x32_bf16 v[16:19], v[176:179], v[240:243], v[16:19]
	v_mfma_f32_16x16x32_bf16 v[8:11], v[216:219], v[240:243], v[8:11]
	v_mfma_f32_16x16x32_bf16 v[4:7], v[176:179], v[248:251], v[4:7]
	v_mfma_f32_16x16x32_bf16 v[0:3], v[216:219], v[248:251], v[0:3]
	s_setprio 0
	s_barrier
	s_mov_b32 m0, s58
	s_nop 0
	global_load_lds_dwordx4 v128, s[44:45]
	s_mov_b32 m0, s59
	s_nop 0
	global_load_lds_dwordx4 v130, s[44:45]
	s_add_i32 s50, 0, 0x18000
	s_add_i32 s51, 0, 0x1c000
	v_add_u32_e32 v168, s50, v182
	v_add_u32_e32 v204, s51, v182
	ds_read_b128 v[156:159], v168
	ds_read_b128 v[160:163], v168 offset:1024
	ds_read_b128 v[164:167], v168 offset:2048
	ds_read_b128 v[168:171], v168 offset:3072
	ds_read_b128 v[172:175], v204
	ds_read_b128 v[176:179], v204 offset:1024
	ds_read_b128 v[212:215], v204 offset:2048
	ds_read_b128 v[216:219], v204 offset:3072
	s_add_u32 s44, s44, 0x4000
	s_addc_u32 s45, s45, 0
	s_mov_b32 m0, s60
	v_lshl_add_u64 v[252:253], s[44:45], 0, v[128:129]
	ds_read_b128 v[220:223], v199 offset:32768
	ds_read_b128 v[224:227], v199 offset:33792
	ds_read_b128 v[228:231], v199 offset:34816
	ds_read_b128 v[232:235], v199 offset:35840
	ds_read_b128 v[236:239], v199 offset:36864
	ds_read_b128 v[240:243], v199 offset:37888
	ds_read_b128 v[244:247], v199 offset:38912
	ds_read_b128 v[248:251], v199 offset:39936
	global_load_lds_dwordx4 v[252:253], off
	v_lshl_add_u64 v[252:253], s[44:45], 0, v[130:131]
	s_mov_b32 m0, s61
	s_nop 0
	global_load_lds_dwordx4 v[252:253], off
	s_waitcnt vmcnt(8)
	s_waitcnt lgkmcnt(0)
	s_barrier
	s_setprio 1
	s_waitcnt lgkmcnt(0)
	v_mfma_f32_16x16x32_bf16 v[124:127], v[156:159], v[220:223], v[124:127]
	v_mfma_f32_16x16x32_bf16 v[120:123], v[164:167], v[220:223], v[120:123]
	v_mfma_f32_16x16x32_bf16 v[116:119], v[156:159], v[228:231], v[116:119]
	v_mfma_f32_16x16x32_bf16 v[108:111], v[164:167], v[228:231], v[108:111]
	v_mfma_f32_16x16x32_bf16 v[92:95], v[156:159], v[236:239], v[92:95]
	v_mfma_f32_16x16x32_bf16 v[88:91], v[164:167], v[236:239], v[88:91]
	v_mfma_f32_16x16x32_bf16 v[84:87], v[156:159], v[244:247], v[84:87]
	v_mfma_f32_16x16x32_bf16 v[76:79], v[164:167], v[244:247], v[76:79]
	v_mfma_f32_16x16x32_bf16 v[124:127], v[160:163], v[224:227], v[124:127]
	v_mfma_f32_16x16x32_bf16 v[120:123], v[168:171], v[224:227], v[120:123]
	v_mfma_f32_16x16x32_bf16 v[116:119], v[160:163], v[232:235], v[116:119]
	v_mfma_f32_16x16x32_bf16 v[108:111], v[168:171], v[232:235], v[108:111]
	v_mfma_f32_16x16x32_bf16 v[92:95], v[160:163], v[240:243], v[92:95]
	v_mfma_f32_16x16x32_bf16 v[88:91], v[168:171], v[240:243], v[88:91]
	v_mfma_f32_16x16x32_bf16 v[84:87], v[160:163], v[248:251], v[84:87]
	v_mfma_f32_16x16x32_bf16 v[76:79], v[168:171], v[248:251], v[76:79]
	s_setprio 0
	s_setprio 1
	v_mfma_f32_16x16x32_bf16 v[112:115], v[172:175], v[220:223], v[112:115]
	v_mfma_f32_16x16x32_bf16 v[104:107], v[212:215], v[220:223], v[104:107]
	v_mfma_f32_16x16x32_bf16 v[100:103], v[172:175], v[228:231], v[100:103]
	v_mfma_f32_16x16x32_bf16 v[96:99], v[212:215], v[228:231], v[96:99]
	v_mfma_f32_16x16x32_bf16 v[80:83], v[172:175], v[236:239], v[80:83]
	v_mfma_f32_16x16x32_bf16 v[72:75], v[212:215], v[236:239], v[72:75]
	v_mfma_f32_16x16x32_bf16 v[68:71], v[172:175], v[244:247], v[68:71]
	v_mfma_f32_16x16x32_bf16 v[64:67], v[212:215], v[244:247], v[64:67]
	v_mfma_f32_16x16x32_bf16 v[112:115], v[176:179], v[224:227], v[112:115]
	v_mfma_f32_16x16x32_bf16 v[104:107], v[216:219], v[224:227], v[104:107]
	v_mfma_f32_16x16x32_bf16 v[100:103], v[176:179], v[232:235], v[100:103]
	v_mfma_f32_16x16x32_bf16 v[96:99], v[216:219], v[232:235], v[96:99]
	v_mfma_f32_16x16x32_bf16 v[80:83], v[176:179], v[240:243], v[80:83]
	v_mfma_f32_16x16x32_bf16 v[72:75], v[216:219], v[240:243], v[72:75]
	v_mfma_f32_16x16x32_bf16 v[68:71], v[176:179], v[248:251], v[68:71]
	v_mfma_f32_16x16x32_bf16 v[64:67], v[216:219], v[248:251], v[64:67]
	s_setprio 0
	s_barrier
	s_add_u32 s44, s42, 0x8000
	s_addc_u32 s45, s43, 0
	s_add_i32 s50, s50, s57
	v_lshl_add_u64 v[252:253], s[44:45], 0, v[128:129]
	s_mov_b32 m0, s50
	ds_read_b128 v[220:223], v199 offset:49152
	ds_read_b128 v[224:227], v199 offset:50176
	ds_read_b128 v[228:231], v199 offset:51200
	ds_read_b128 v[232:235], v199 offset:52224
	ds_read_b128 v[236:239], v199 offset:53248
	ds_read_b128 v[240:243], v199 offset:54272
	ds_read_b128 v[244:247], v199 offset:55296
	ds_read_b128 v[248:251], v199 offset:56320
	global_load_lds_dwordx4 v[252:253], off
	s_add_i32 m0, s50, 0x2000
	s_add_u32 s42, s42, 0xc000
	v_lshl_add_u64 v[252:253], s[44:45], 0, v[130:131]
	s_addc_u32 s43, s43, 0
	s_add_i32 s44, s51, s57
	global_load_lds_dwordx4 v[252:253], off
	v_lshl_add_u64 v[252:253], s[42:43], 0, v[128:129]
	s_mov_b32 m0, s44
	s_nop 0
	global_load_lds_dwordx4 v[252:253], off
	v_lshl_add_u64 v[252:253], s[42:43], 0, v[130:131]
	s_add_i32 m0, s44, 0x2000
	s_nop 0
	global_load_lds_dwordx4 v[252:253], off
	v_lshl_add_u64 v[252:253], s[40:41], 0, v[128:129]
	s_mov_b32 m0, s67
	s_nop 0
	global_load_lds_dwordx4 v[252:253], off
	v_lshl_add_u64 v[252:253], s[40:41], 0, v[130:131]
	s_mov_b32 m0, s68
	s_nop 0
	global_load_lds_dwordx4 v[252:253], off
	s_waitcnt vmcnt(8)
	s_waitcnt lgkmcnt(0)
	s_barrier
	s_setprio 1
	s_waitcnt lgkmcnt(0)
	v_mfma_f32_16x16x32_bf16 v[60:63], v[156:159], v[220:223], v[60:63]
	v_mfma_f32_16x16x32_bf16 v[56:59], v[164:167], v[220:223], v[56:59]
	v_mfma_f32_16x16x32_bf16 v[52:55], v[156:159], v[228:231], v[52:55]
	v_mfma_f32_16x16x32_bf16 v[44:47], v[164:167], v[228:231], v[44:47]
	v_mfma_f32_16x16x32_bf16 v[32:35], v[156:159], v[236:239], v[32:35]
	v_mfma_f32_16x16x32_bf16 v[24:27], v[164:167], v[236:239], v[24:27]
	v_mfma_f32_16x16x32_bf16 v[20:23], v[156:159], v[244:247], v[20:23]
	v_mfma_f32_16x16x32_bf16 v[12:15], v[164:167], v[244:247], v[12:15]
	v_mfma_f32_16x16x32_bf16 v[60:63], v[160:163], v[224:227], v[60:63]
	v_mfma_f32_16x16x32_bf16 v[56:59], v[168:171], v[224:227], v[56:59]
	v_mfma_f32_16x16x32_bf16 v[52:55], v[160:163], v[232:235], v[52:55]
	v_mfma_f32_16x16x32_bf16 v[44:47], v[168:171], v[232:235], v[44:47]
	v_mfma_f32_16x16x32_bf16 v[32:35], v[160:163], v[240:243], v[32:35]
	v_mfma_f32_16x16x32_bf16 v[24:27], v[168:171], v[240:243], v[24:27]
	v_mfma_f32_16x16x32_bf16 v[20:23], v[160:163], v[248:251], v[20:23]
	v_mfma_f32_16x16x32_bf16 v[12:15], v[168:171], v[248:251], v[12:15]
	s_setprio 0
	s_setprio 1
	v_mfma_f32_16x16x32_bf16 v[48:51], v[172:175], v[220:223], v[48:51]
	v_mfma_f32_16x16x32_bf16 v[40:43], v[212:215], v[220:223], v[40:43]
	v_mfma_f32_16x16x32_bf16 v[36:39], v[172:175], v[228:231], v[36:39]
	v_mfma_f32_16x16x32_bf16 v[28:31], v[212:215], v[228:231], v[28:31]
	v_mfma_f32_16x16x32_bf16 v[16:19], v[172:175], v[236:239], v[16:19]
	v_mfma_f32_16x16x32_bf16 v[8:11], v[212:215], v[236:239], v[8:11]
	v_mfma_f32_16x16x32_bf16 v[4:7], v[172:175], v[244:247], v[4:7]
	v_mfma_f32_16x16x32_bf16 v[0:3], v[212:215], v[244:247], v[0:3]
	v_mfma_f32_16x16x32_bf16 v[48:51], v[176:179], v[224:227], v[48:51]
	v_mfma_f32_16x16x32_bf16 v[40:43], v[216:219], v[224:227], v[40:43]
	v_mfma_f32_16x16x32_bf16 v[36:39], v[176:179], v[232:235], v[36:39]
	v_mfma_f32_16x16x32_bf16 v[28:31], v[216:219], v[232:235], v[28:31]
	v_mfma_f32_16x16x32_bf16 v[16:19], v[176:179], v[240:243], v[16:19]
	v_mfma_f32_16x16x32_bf16 v[8:11], v[216:219], v[240:243], v[8:11]
	v_mfma_f32_16x16x32_bf16 v[4:7], v[176:179], v[248:251], v[4:7]
	v_mfma_f32_16x16x32_bf16 v[0:3], v[216:219], v[248:251], v[0:3]
	s_setprio 0
	s_barrier
	s_add_i32 s49, s49, 2
	s_add_u32 s47, s47, 0x10000
	s_addc_u32 s48, s48, 0
	s_add_u32 s38, s38, 0x10000
	s_addc_u32 s39, s39, 0
	s_cmp_gt_u32 s49, 41
	s_cbranch_scc0 .LBB0_408
	s_and_b64 vcc, exec, s[14:15]
	s_cbranch_vccz .LBB0_411
	s_barrier

.LBB0_492:
	ds_read_b128 v[128:131], v212
	ds_read_b128 v[132:135], v212 offset:1024
	ds_read_b128 v[136:139], v212 offset:2048
	ds_read_b128 v[140:143], v212 offset:3072
	ds_read_b128 v[144:147], v213
	ds_read_b128 v[148:151], v213 offset:1024
	ds_read_b128 v[152:155], v213 offset:2048
	ds_read_b128 v[156:159], v213 offset:3072
	s_add_u32 s34, s30, 0xfffc0080
	s_addc_u32 s35, s31, -1
	s_cmp_eq_u32 s39, 12
	s_cselect_b32 s37, s1, s35
	s_cselect_b32 s36, s7, s34
	s_cselect_b32 s35, s10, s38
	s_cselect_b32 s34, s23, s25
	v_lshl_add_u64 v[200:201], s[30:31], 0, v[190:191]
	s_add_i32 m0, s47, 0xc000
	ds_read_b128 v[160:163], v214
	ds_read_b128 v[164:167], v214 offset:1024
	ds_read_b128 v[196:199], v214 offset:2048
	ds_read_b128 v[216:219], v214 offset:3072
	ds_read_b128 v[220:223], v214 offset:4096
	ds_read_b128 v[224:227], v214 offset:5120
	ds_read_b128 v[228:231], v214 offset:6144
	ds_read_b128 v[232:235], v214 offset:7168
	global_load_lds_dwordx4 v[200:201], off
	v_lshl_add_u64 v[200:201], s[30:31], 0, v[188:189]
	s_add_i32 m0, s47, 0xe000
	s_nop 0
	global_load_lds_dwordx4 v[200:201], off
	s_waitcnt vmcnt(8)
	s_waitcnt lgkmcnt(0)
	s_barrier
	s_setprio 1
	s_waitcnt lgkmcnt(0)
	v_mfma_f32_16x16x32_bf16 v[124:127], v[128:131], v[160:163], v[124:127]
	v_mfma_f32_16x16x32_bf16 v[120:123], v[136:139], v[160:163], v[120:123]
	v_mfma_f32_16x16x32_bf16 v[116:119], v[128:131], v[196:199], v[116:119]
	v_mfma_f32_16x16x32_bf16 v[112:115], v[136:139], v[196:199], v[112:115]
	v_mfma_f32_16x16x32_bf16 v[108:111], v[128:131], v[220:223], v[108:111]
	v_mfma_f32_16x16x32_bf16 v[104:107], v[136:139], v[220:223], v[104:107]
	v_mfma_f32_16x16x32_bf16 v[100:103], v[128:131], v[228:231], v[100:103]
	v_mfma_f32_16x16x32_bf16 v[96:99], v[136:139], v[228:231], v[96:99]
	v_mfma_f32_16x16x32_bf16 v[124:127], v[132:135], v[164:167], v[124:127]
	v_mfma_f32_16x16x32_bf16 v[120:123], v[140:143], v[164:167], v[120:123]
	v_mfma_f32_16x16x32_bf16 v[116:119], v[132:135], v[216:219], v[116:119]
	v_mfma_f32_16x16x32_bf16 v[112:115], v[140:143], v[216:219], v[112:115]
	v_mfma_f32_16x16x32_bf16 v[108:111], v[132:135], v[224:227], v[108:111]
	v_mfma_f32_16x16x32_bf16 v[104:107], v[140:143], v[224:227], v[104:107]
	v_mfma_f32_16x16x32_bf16 v[100:103], v[132:135], v[232:235], v[100:103]
	v_mfma_f32_16x16x32_bf16 v[96:99], v[140:143], v[232:235], v[96:99]
	s_setprio 0
	s_setprio 1
	v_mfma_f32_16x16x32_bf16 v[60:63], v[144:147], v[160:163], v[60:63]
	v_mfma_f32_16x16x32_bf16 v[56:59], v[152:155], v[160:163], v[56:59]
	v_mfma_f32_16x16x32_bf16 v[52:55], v[144:147], v[196:199], v[52:55]
	v_mfma_f32_16x16x32_bf16 v[48:51], v[152:155], v[196:199], v[48:51]
	v_mfma_f32_16x16x32_bf16 v[44:47], v[144:147], v[220:223], v[44:47]
	v_mfma_f32_16x16x32_bf16 v[40:43], v[152:155], v[220:223], v[40:43]
	v_mfma_f32_16x16x32_bf16 v[36:39], v[144:147], v[228:231], v[36:39]
	v_mfma_f32_16x16x32_bf16 v[32:35], v[152:155], v[228:231], v[32:35]
	v_mfma_f32_16x16x32_bf16 v[60:63], v[148:151], v[164:167], v[60:63]
	v_mfma_f32_16x16x32_bf16 v[56:59], v[156:159], v[164:167], v[56:59]
	v_mfma_f32_16x16x32_bf16 v[52:55], v[148:151], v[216:219], v[52:55]
	v_mfma_f32_16x16x32_bf16 v[48:51], v[156:159], v[216:219], v[48:51]
	v_mfma_f32_16x16x32_bf16 v[44:47], v[148:151], v[224:227], v[44:47]
	v_mfma_f32_16x16x32_bf16 v[40:43], v[156:159], v[224:227], v[40:43]
	v_mfma_f32_16x16x32_bf16 v[36:39], v[148:151], v[232:235], v[36:39]
	v_mfma_f32_16x16x32_bf16 v[32:35], v[156:159], v[232:235], v[32:35]
	s_setprio 0
	s_barrier
	s_add_i32 s66, s61, s46
	v_lshl_add_u64 v[200:201], s[34:35], 0, v[172:173]
	s_mov_b32 m0, s66
	ds_read_b128 v[160:163], v214 offset:16384
	ds_read_b128 v[164:167], v214 offset:17408
	ds_read_b128 v[196:199], v214 offset:18432
	ds_read_b128 v[216:219], v214 offset:19456
	ds_read_b128 v[220:223], v214 offset:20480
	ds_read_b128 v[224:227], v214 offset:21504
	ds_read_b128 v[228:231], v214 offset:22528
	ds_read_b128 v[232:235], v214 offset:23552
	global_load_lds_dwordx4 v[200:201], off
	s_add_i32 m0, s66, 0x2000
	s_add_u32 s66, s34, 0x4000
	v_lshl_add_u64 v[200:201], s[34:35], 0, v[176:177]
	s_addc_u32 s67, s35, 0
	s_add_i32 s68, s62, s46
	global_load_lds_dwordx4 v[200:201], off
	v_lshl_add_u64 v[200:201], s[66:67], 0, v[172:173]
	s_mov_b32 m0, s68
	v_lshl_add_u64 v[236:237], s[36:37], 0, v[174:175]
	global_load_lds_dwordx4 v[200:201], off
	v_lshl_add_u64 v[200:201], s[66:67], 0, v[176:177]
	s_add_i32 m0, s68, 0x2000
	s_nop 0
	global_load_lds_dwordx4 v[200:201], off
	v_lshl_add_u64 v[200:201], s[36:37], 0, v[170:171]
	s_waitcnt vmcnt(6)
	s_waitcnt lgkmcnt(0)
	s_barrier
	s_setprio 1
	s_waitcnt lgkmcnt(0)
	v_mfma_f32_16x16x32_bf16 v[92:95], v[128:131], v[160:163], v[92:95]
	v_mfma_f32_16x16x32_bf16 v[88:91], v[136:139], v[160:163], v[88:91]
	v_mfma_f32_16x16x32_bf16 v[84:87], v[128:131], v[196:199], v[84:87]
	v_mfma_f32_16x16x32_bf16 v[80:83], v[136:139], v[196:199], v[80:83]
	v_mfma_f32_16x16x32_bf16 v[76:79], v[128:131], v[220:223], v[76:79]
	v_mfma_f32_16x16x32_bf16 v[72:75], v[136:139], v[220:223], v[72:75]
	v_mfma_f32_16x16x32_bf16 v[68:71], v[128:131], v[228:231], v[68:71]
	v_mfma_f32_16x16x32_bf16 v[64:67], v[136:139], v[228:231], v[64:67]
	v_mfma_f32_16x16x32_bf16 v[92:95], v[132:135], v[164:167], v[92:95]
	v_mfma_f32_16x16x32_bf16 v[88:91], v[140:143], v[164:167], v[88:91]
	v_mfma_f32_16x16x32_bf16 v[84:87], v[132:135], v[216:219], v[84:87]
	v_mfma_f32_16x16x32_bf16 v[80:83], v[140:143], v[216:219], v[80:83]
	v_mfma_f32_16x16x32_bf16 v[76:79], v[132:135], v[224:227], v[76:79]
	v_mfma_f32_16x16x32_bf16 v[72:75], v[140:143], v[224:227], v[72:75]
	v_mfma_f32_16x16x32_bf16 v[68:71], v[132:135], v[232:235], v[68:71]
	v_mfma_f32_16x16x32_bf16 v[64:67], v[140:143], v[232:235], v[64:67]
	s_setprio 0
	s_setprio 1
	v_mfma_f32_16x16x32_bf16 v[28:31], v[144:147], v[160:163], v[28:31]
	v_mfma_f32_16x16x32_bf16 v[24:27], v[152:155], v[160:163], v[24:27]
	v_mfma_f32_16x16x32_bf16 v[20:23], v[144:147], v[196:199], v[20:23]
	v_mfma_f32_16x16x32_bf16 v[16:19], v[152:155], v[196:199], v[16:19]
	v_mfma_f32_16x16x32_bf16 v[12:15], v[144:147], v[220:223], v[12:15]
	v_mfma_f32_16x16x32_bf16 v[8:11], v[152:155], v[220:223], v[8:11]
	v_mfma_f32_16x16x32_bf16 v[4:7], v[144:147], v[228:231], v[4:7]
	v_mfma_f32_16x16x32_bf16 v[0:3], v[152:155], v[228:231], v[0:3]
	v_mfma_f32_16x16x32_bf16 v[28:31], v[148:151], v[164:167], v[28:31]
	v_mfma_f32_16x16x32_bf16 v[24:27], v[156:159], v[164:167], v[24:27]
	v_mfma_f32_16x16x32_bf16 v[20:23], v[148:151], v[216:219], v[20:23]
	v_mfma_f32_16x16x32_bf16 v[16:19], v[156:159], v[216:219], v[16:19]
	v_mfma_f32_16x16x32_bf16 v[12:15], v[148:151], v[224:227], v[12:15]
	v_mfma_f32_16x16x32_bf16 v[8:11], v[156:159], v[224:227], v[8:11]
	v_mfma_f32_16x16x32_bf16 v[4:7], v[148:151], v[232:235], v[4:7]
	v_mfma_f32_16x16x32_bf16 v[0:3], v[156:159], v[232:235], v[0:3]
	s_setprio 0
	s_barrier
	s_mov_b32 m0, s47
	s_nop 0
	global_load_lds_dwordx4 v170, s[36:37]
	s_mov_b32 m0, s48
	s_nop 0
	global_load_lds_dwordx4 v174, s[36:37]
	s_add_i32 s66, 0, 0x18000
	s_add_i32 s67, 0, 0x1c000
	v_add_u32_e32 v140, s66, v210
	v_add_u32_e32 v156, s67, v210
	ds_read_b128 v[128:131], v140
	ds_read_b128 v[132:135], v140 offset:1024
	ds_read_b128 v[136:139], v140 offset:2048
	ds_read_b128 v[140:143], v140 offset:3072
	ds_read_b128 v[144:147], v156
	ds_read_b128 v[148:151], v156 offset:1024
	ds_read_b128 v[152:155], v156 offset:2048
	ds_read_b128 v[156:159], v156 offset:3072
	s_add_u32 s36, s36, 0x40000
	s_addc_u32 s37, s37, 0
	s_mov_b32 m0, s49
	v_lshl_add_u64 v[238:239], s[36:37], 0, v[170:171]
	ds_read_b128 v[160:163], v214 offset:32768
	ds_read_b128 v[164:167], v214 offset:33792
	ds_read_b128 v[196:199], v214 offset:34816
	ds_read_b128 v[216:219], v214 offset:35840
	ds_read_b128 v[220:223], v214 offset:36864
	ds_read_b128 v[224:227], v214 offset:37888
	ds_read_b128 v[228:231], v214 offset:38912
	ds_read_b128 v[232:235], v214 offset:39936
	global_load_lds_dwordx4 v[238:239], off
	v_lshl_add_u64 v[238:239], s[36:37], 0, v[174:175]
	s_mov_b32 m0, s50
	s_nop 0
	global_load_lds_dwordx4 v[238:239], off
	s_waitcnt vmcnt(8)
	s_waitcnt lgkmcnt(0)
	s_barrier
	s_setprio 1
	s_waitcnt lgkmcnt(0)
	v_mfma_f32_16x16x32_bf16 v[124:127], v[128:131], v[160:163], v[124:127]
	v_mfma_f32_16x16x32_bf16 v[120:123], v[136:139], v[160:163], v[120:123]
	v_mfma_f32_16x16x32_bf16 v[116:119], v[128:131], v[196:199], v[116:119]
	v_mfma_f32_16x16x32_bf16 v[112:115], v[136:139], v[196:199], v[112:115]
	v_mfma_f32_16x16x32_bf16 v[108:111], v[128:131], v[220:223], v[108:111]
	v_mfma_f32_16x16x32_bf16 v[104:107], v[136:139], v[220:223], v[104:107]
	v_mfma_f32_16x16x32_bf16 v[100:103], v[128:131], v[228:231], v[100:103]
	v_mfma_f32_16x16x32_bf16 v[96:99], v[136:139], v[228:231], v[96:99]
	v_mfma_f32_16x16x32_bf16 v[124:127], v[132:135], v[164:167], v[124:127]
	v_mfma_f32_16x16x32_bf16 v[120:123], v[140:143], v[164:167], v[120:123]
	v_mfma_f32_16x16x32_bf16 v[116:119], v[132:135], v[216:219], v[116:119]
	v_mfma_f32_16x16x32_bf16 v[112:115], v[140:143], v[216:219], v[112:115]
	v_mfma_f32_16x16x32_bf16 v[108:111], v[132:135], v[224:227], v[108:111]
	v_mfma_f32_16x16x32_bf16 v[104:107], v[140:143], v[224:227], v[104:107]
	v_mfma_f32_16x16x32_bf16 v[100:103], v[132:135], v[232:235], v[100:103]
	v_mfma_f32_16x16x32_bf16 v[96:99], v[140:143], v[232:235], v[96:99]
	s_setprio 0
	s_setprio 1
	v_mfma_f32_16x16x32_bf16 v[60:63], v[144:147], v[160:163], v[60:63]
	v_mfma_f32_16x16x32_bf16 v[56:59], v[152:155], v[160:163], v[56:59]
	v_mfma_f32_16x16x32_bf16 v[52:55], v[144:147], v[196:199], v[52:55]
	v_mfma_f32_16x16x32_bf16 v[48:51], v[152:155], v[196:199], v[48:51]
	v_mfma_f32_16x16x32_bf16 v[44:47], v[144:147], v[220:223], v[44:47]
	v_mfma_f32_16x16x32_bf16 v[40:43], v[152:155], v[220:223], v[40:43]
	v_mfma_f32_16x16x32_bf16 v[36:39], v[144:147], v[228:231], v[36:39]
	v_mfma_f32_16x16x32_bf16 v[32:35], v[152:155], v[228:231], v[32:35]
	v_mfma_f32_16x16x32_bf16 v[60:63], v[148:151], v[164:167], v[60:63]
	v_mfma_f32_16x16x32_bf16 v[56:59], v[156:159], v[164:167], v[56:59]
	v_mfma_f32_16x16x32_bf16 v[52:55], v[148:151], v[216:219], v[52:55]
	v_mfma_f32_16x16x32_bf16 v[48:51], v[156:159], v[216:219], v[48:51]
	v_mfma_f32_16x16x32_bf16 v[44:47], v[148:151], v[224:227], v[44:47]
	v_mfma_f32_16x16x32_bf16 v[40:43], v[156:159], v[224:227], v[40:43]
	v_mfma_f32_16x16x32_bf16 v[36:39], v[148:151], v[232:235], v[36:39]
	v_mfma_f32_16x16x32_bf16 v[32:35], v[156:159], v[232:235], v[32:35]
	s_setprio 0
	s_barrier
	s_add_u32 s36, s34, 0x8000
	s_addc_u32 s37, s35, 0
	s_add_i32 s66, s66, s46
	v_lshl_add_u64 v[238:239], s[36:37], 0, v[172:173]
	s_mov_b32 m0, s66
	ds_read_b128 v[160:163], v214 offset:49152
	ds_read_b128 v[164:167], v214 offset:50176
	ds_read_b128 v[196:199], v214 offset:51200
	ds_read_b128 v[216:219], v214 offset:52224
	ds_read_b128 v[220:223], v214 offset:53248
	ds_read_b128 v[224:227], v214 offset:54272
	ds_read_b128 v[228:231], v214 offset:55296
	ds_read_b128 v[232:235], v214 offset:56320
	global_load_lds_dwordx4 v[238:239], off
	s_add_i32 m0, s66, 0x2000
	s_add_u32 s34, s34, 0xc000
	v_lshl_add_u64 v[238:239], s[36:37], 0, v[176:177]
	s_addc_u32 s35, s35, 0
	s_add_i32 s36, s67, s46
	global_load_lds_dwordx4 v[238:239], off
	v_lshl_add_u64 v[238:239], s[34:35], 0, v[172:173]
	s_mov_b32 m0, s36
	v_lshl_add_u64 v[200:201], v[200:201], 0, s[16:17]
	global_load_lds_dwordx4 v[238:239], off
	v_lshl_add_u64 v[238:239], s[34:35], 0, v[176:177]
	s_add_i32 m0, s36, 0x2000
	s_nop 0
	global_load_lds_dwordx4 v[238:239], off
	s_mov_b32 m0, s55
	s_nop 0
	global_load_lds_dwordx4 v[200:201], off
	v_lshl_add_u64 v[200:201], v[236:237], 0, s[16:17]
	s_mov_b32 m0, s56
	s_nop 0
	global_load_lds_dwordx4 v[200:201], off
	s_waitcnt vmcnt(8)
	s_waitcnt lgkmcnt(0)
	s_barrier
	s_setprio 1
	s_waitcnt lgkmcnt(0)
	v_mfma_f32_16x16x32_bf16 v[92:95], v[128:131], v[160:163], v[92:95]
	v_mfma_f32_16x16x32_bf16 v[88:91], v[136:139], v[160:163], v[88:91]
	v_mfma_f32_16x16x32_bf16 v[84:87], v[128:131], v[196:199], v[84:87]
	v_mfma_f32_16x16x32_bf16 v[80:83], v[136:139], v[196:199], v[80:83]
	v_mfma_f32_16x16x32_bf16 v[76:79], v[128:131], v[220:223], v[76:79]
	v_mfma_f32_16x16x32_bf16 v[72:75], v[136:139], v[220:223], v[72:75]
	v_mfma_f32_16x16x32_bf16 v[68:71], v[128:131], v[228:231], v[68:71]
	v_mfma_f32_16x16x32_bf16 v[64:67], v[136:139], v[228:231], v[64:67]
	v_mfma_f32_16x16x32_bf16 v[92:95], v[132:135], v[164:167], v[92:95]
	v_mfma_f32_16x16x32_bf16 v[88:91], v[140:143], v[164:167], v[88:91]
	v_mfma_f32_16x16x32_bf16 v[84:87], v[132:135], v[216:219], v[84:87]
	v_mfma_f32_16x16x32_bf16 v[80:83], v[140:143], v[216:219], v[80:83]
	v_mfma_f32_16x16x32_bf16 v[76:79], v[132:135], v[224:227], v[76:79]
	v_mfma_f32_16x16x32_bf16 v[72:75], v[140:143], v[224:227], v[72:75]
	v_mfma_f32_16x16x32_bf16 v[68:71], v[132:135], v[232:235], v[68:71]
	v_mfma_f32_16x16x32_bf16 v[64:67], v[140:143], v[232:235], v[64:67]
	s_setprio 0
	s_setprio 1
	v_mfma_f32_16x16x32_bf16 v[28:31], v[144:147], v[160:163], v[28:31]
	v_mfma_f32_16x16x32_bf16 v[24:27], v[152:155], v[160:163], v[24:27]
	v_mfma_f32_16x16x32_bf16 v[20:23], v[144:147], v[196:199], v[20:23]
	v_mfma_f32_16x16x32_bf16 v[16:19], v[152:155], v[196:199], v[16:19]
	v_mfma_f32_16x16x32_bf16 v[12:15], v[144:147], v[220:223], v[12:15]
	v_mfma_f32_16x16x32_bf16 v[8:11], v[152:155], v[220:223], v[8:11]
	v_mfma_f32_16x16x32_bf16 v[4:7], v[144:147], v[228:231], v[4:7]
	v_mfma_f32_16x16x32_bf16 v[0:3], v[152:155], v[228:231], v[0:3]
	v_mfma_f32_16x16x32_bf16 v[28:31], v[148:151], v[164:167], v[28:31]
	v_mfma_f32_16x16x32_bf16 v[24:27], v[156:159], v[164:167], v[24:27]
	v_mfma_f32_16x16x32_bf16 v[20:23], v[148:151], v[216:219], v[20:23]
	v_mfma_f32_16x16x32_bf16 v[16:19], v[156:159], v[216:219], v[16:19]
	v_mfma_f32_16x16x32_bf16 v[12:15], v[148:151], v[224:227], v[12:15]
	v_mfma_f32_16x16x32_bf16 v[8:11], v[156:159], v[224:227], v[8:11]
	v_mfma_f32_16x16x32_bf16 v[4:7], v[148:151], v[232:235], v[4:7]
	v_mfma_f32_16x16x32_bf16 v[0:3], v[156:159], v[232:235], v[0:3]
	s_setprio 0
	s_barrier
	s_add_i32 s39, s39, 2
	s_add_u32 s25, s25, 0x10000
	s_addc_u32 s38, s38, 0
	s_add_u32 s30, s30, 0x100
	s_addc_u32 s31, s31, 0
	s_cmp_gt_u32 s39, 13
	s_cbranch_scc0 .LBB0_492
	s_and_b64 vcc, exec, s[18:19]
	s_cbranch_vccz .LBB0_503
	s_barrier
	v_lshl_add_u32 v216, s0, 8, v169
	s_cmp_gt_i32 s6, 4
	s_mov_b64 s[0:1], -1
	s_cbranch_scc1 .LBB0_504

.LBB0_1071:
	ds_read_b128 v[128:131], v170
	ds_read_b128 v[148:151], v170 offset:1024
	ds_read_b128 v[152:155], v170 offset:2048
	ds_read_b128 v[174:177], v170 offset:3072
	ds_read_b128 v[178:181], v171
	ds_read_b128 v[182:185], v171 offset:1024
	ds_read_b128 v[186:189], v171 offset:2048
	ds_read_b128 v[190:193], v171 offset:3072
	s_add_u32 s30, s28, 0xfffe0080
	s_addc_u32 s31, s29, -1
	s_cmp_eq_u32 s56, 4
	s_cselect_b32 s35, s17, s31
	s_cselect_b32 s34, s52, s30
	s_cselect_b32 s31, s19, s55
	s_cselect_b32 s30, s53, s54
	v_lshl_add_u64 v[234:235], s[28:29], 0, v[142:143]
	s_add_i32 m0, s25, 0xc000
	ds_read_b128 v[194:197], v172
	ds_read_b128 v[198:201], v172 offset:1024
	ds_read_b128 v[210:213], v172 offset:2048
	ds_read_b128 v[214:217], v172 offset:3072
	ds_read_b128 v[218:221], v172 offset:4096
	ds_read_b128 v[222:225], v172 offset:5120
	ds_read_b128 v[226:229], v172 offset:6144
	ds_read_b128 v[230:233], v172 offset:7168
	global_load_lds_dwordx4 v[234:235], off
	v_lshl_add_u64 v[234:235], s[28:29], 0, v[140:141]
	s_add_i32 m0, s25, 0xe000
	s_nop 0
	global_load_lds_dwordx4 v[234:235], off
	s_waitcnt vmcnt(8)
	s_waitcnt lgkmcnt(0)
	s_barrier
	s_setprio 1
	s_waitcnt lgkmcnt(0)
	v_mfma_f32_16x16x32_bf16 v[124:127], v[128:131], v[194:197], v[124:127]
	v_mfma_f32_16x16x32_bf16 v[120:123], v[152:155], v[194:197], v[120:123]
	v_mfma_f32_16x16x32_bf16 v[116:119], v[128:131], v[210:213], v[116:119]
	v_mfma_f32_16x16x32_bf16 v[112:115], v[152:155], v[210:213], v[112:115]
	v_mfma_f32_16x16x32_bf16 v[92:95], v[128:131], v[218:221], v[92:95]
	v_mfma_f32_16x16x32_bf16 v[88:91], v[152:155], v[218:221], v[88:91]
	v_mfma_f32_16x16x32_bf16 v[84:87], v[128:131], v[226:229], v[84:87]
	v_mfma_f32_16x16x32_bf16 v[72:75], v[152:155], v[226:229], v[72:75]
	v_mfma_f32_16x16x32_bf16 v[124:127], v[148:151], v[198:201], v[124:127]
	v_mfma_f32_16x16x32_bf16 v[120:123], v[174:177], v[198:201], v[120:123]
	v_mfma_f32_16x16x32_bf16 v[116:119], v[148:151], v[214:217], v[116:119]
	v_mfma_f32_16x16x32_bf16 v[112:115], v[174:177], v[214:217], v[112:115]
	v_mfma_f32_16x16x32_bf16 v[92:95], v[148:151], v[222:225], v[92:95]
	v_mfma_f32_16x16x32_bf16 v[88:91], v[174:177], v[222:225], v[88:91]
	v_mfma_f32_16x16x32_bf16 v[84:87], v[148:151], v[230:233], v[84:87]
	v_mfma_f32_16x16x32_bf16 v[72:75], v[174:177], v[230:233], v[72:75]
	s_setprio 0
	s_setprio 1
	v_mfma_f32_16x16x32_bf16 v[108:111], v[178:181], v[194:197], v[108:111]
	v_mfma_f32_16x16x32_bf16 v[104:107], v[186:189], v[194:197], v[104:107]
	v_mfma_f32_16x16x32_bf16 v[100:103], v[178:181], v[210:213], v[100:103]
	v_mfma_f32_16x16x32_bf16 v[96:99], v[186:189], v[210:213], v[96:99]
	v_mfma_f32_16x16x32_bf16 v[80:83], v[178:181], v[218:221], v[80:83]
	v_mfma_f32_16x16x32_bf16 v[76:79], v[186:189], v[218:221], v[76:79]
	v_mfma_f32_16x16x32_bf16 v[68:71], v[178:181], v[226:229], v[68:71]
	v_mfma_f32_16x16x32_bf16 v[64:67], v[186:189], v[226:229], v[64:67]
	v_mfma_f32_16x16x32_bf16 v[108:111], v[182:185], v[198:201], v[108:111]
	v_mfma_f32_16x16x32_bf16 v[104:107], v[190:193], v[198:201], v[104:107]
	v_mfma_f32_16x16x32_bf16 v[100:103], v[182:185], v[214:217], v[100:103]
	v_mfma_f32_16x16x32_bf16 v[96:99], v[190:193], v[214:217], v[96:99]
	v_mfma_f32_16x16x32_bf16 v[80:83], v[182:185], v[222:225], v[80:83]
	v_mfma_f32_16x16x32_bf16 v[76:79], v[190:193], v[222:225], v[76:79]
	v_mfma_f32_16x16x32_bf16 v[68:71], v[182:185], v[230:233], v[68:71]
	v_mfma_f32_16x16x32_bf16 v[64:67], v[190:193], v[230:233], v[64:67]
	s_setprio 0
	s_barrier
	s_add_i32 s57, s49, s42
	v_lshl_add_u64 v[234:235], s[30:31], 0, v[134:135]
	s_mov_b32 m0, s57
	ds_read_b128 v[194:197], v172 offset:16384
	ds_read_b128 v[198:201], v172 offset:17408
	ds_read_b128 v[210:213], v172 offset:18432
	ds_read_b128 v[214:217], v172 offset:19456
	ds_read_b128 v[218:221], v172 offset:20480
	ds_read_b128 v[222:225], v172 offset:21504
	ds_read_b128 v[226:229], v172 offset:22528
	ds_read_b128 v[230:233], v172 offset:23552
	global_load_lds_dwordx4 v[234:235], off
	s_add_i32 m0, s57, 0x2000
	s_add_u32 s58, s30, 0x4000
	v_lshl_add_u64 v[234:235], s[30:31], 0, v[138:139]
	s_addc_u32 s59, s31, 0
	s_add_i32 s57, s50, s42
	global_load_lds_dwordx4 v[234:235], off
	v_lshl_add_u64 v[234:235], s[58:59], 0, v[134:135]
	s_mov_b32 m0, s57
	v_lshl_add_u64 v[236:237], s[34:35], 0, v[136:137]
	global_load_lds_dwordx4 v[234:235], off
	v_lshl_add_u64 v[234:235], s[58:59], 0, v[138:139]
	s_add_i32 m0, s57, 0x2000
	s_nop 0
	global_load_lds_dwordx4 v[234:235], off
	v_lshl_add_u64 v[234:235], s[34:35], 0, v[132:133]
	s_waitcnt vmcnt(6)
	s_waitcnt lgkmcnt(0)
	s_barrier
	s_setprio 1
	s_waitcnt lgkmcnt(0)
	v_mfma_f32_16x16x32_bf16 v[60:63], v[128:131], v[194:197], v[60:63]
	v_mfma_f32_16x16x32_bf16 v[56:59], v[152:155], v[194:197], v[56:59]
	v_mfma_f32_16x16x32_bf16 v[48:51], v[128:131], v[210:213], v[48:51]
	v_mfma_f32_16x16x32_bf16 v[40:43], v[152:155], v[210:213], v[40:43]
	v_mfma_f32_16x16x32_bf16 v[32:35], v[128:131], v[218:221], v[32:35]
	v_mfma_f32_16x16x32_bf16 v[24:27], v[152:155], v[218:221], v[24:27]
	v_mfma_f32_16x16x32_bf16 v[16:19], v[128:131], v[226:229], v[16:19]
	v_mfma_f32_16x16x32_bf16 v[8:11], v[152:155], v[226:229], v[8:11]
	v_mfma_f32_16x16x32_bf16 v[60:63], v[148:151], v[198:201], v[60:63]
	v_mfma_f32_16x16x32_bf16 v[56:59], v[174:177], v[198:201], v[56:59]
	v_mfma_f32_16x16x32_bf16 v[48:51], v[148:151], v[214:217], v[48:51]
	v_mfma_f32_16x16x32_bf16 v[40:43], v[174:177], v[214:217], v[40:43]
	v_mfma_f32_16x16x32_bf16 v[32:35], v[148:151], v[222:225], v[32:35]
	v_mfma_f32_16x16x32_bf16 v[24:27], v[174:177], v[222:225], v[24:27]
	v_mfma_f32_16x16x32_bf16 v[16:19], v[148:151], v[230:233], v[16:19]
	v_mfma_f32_16x16x32_bf16 v[8:11], v[174:177], v[230:233], v[8:11]
	s_setprio 0
	s_setprio 1
	v_mfma_f32_16x16x32_bf16 v[52:55], v[178:181], v[194:197], v[52:55]
	v_mfma_f32_16x16x32_bf16 v[44:47], v[186:189], v[194:197], v[44:47]
	v_mfma_f32_16x16x32_bf16 v[36:39], v[178:181], v[210:213], v[36:39]
	v_mfma_f32_16x16x32_bf16 v[28:31], v[186:189], v[210:213], v[28:31]
	v_mfma_f32_16x16x32_bf16 v[20:23], v[178:181], v[218:221], v[20:23]
	v_mfma_f32_16x16x32_bf16 v[12:15], v[186:189], v[218:221], v[12:15]
	v_mfma_f32_16x16x32_bf16 v[4:7], v[178:181], v[226:229], v[4:7]
	v_mfma_f32_16x16x32_bf16 v[0:3], v[186:189], v[226:229], v[0:3]
	v_mfma_f32_16x16x32_bf16 v[52:55], v[182:185], v[198:201], v[52:55]
	v_mfma_f32_16x16x32_bf16 v[44:47], v[190:193], v[198:201], v[44:47]
	v_mfma_f32_16x16x32_bf16 v[36:39], v[182:185], v[214:217], v[36:39]
	v_mfma_f32_16x16x32_bf16 v[28:31], v[190:193], v[214:217], v[28:31]
	v_mfma_f32_16x16x32_bf16 v[20:23], v[182:185], v[222:225], v[20:23]
	v_mfma_f32_16x16x32_bf16 v[12:15], v[190:193], v[222:225], v[12:15]
	v_mfma_f32_16x16x32_bf16 v[4:7], v[182:185], v[230:233], v[4:7]
	v_mfma_f32_16x16x32_bf16 v[0:3], v[190:193], v[230:233], v[0:3]
	s_setprio 0
	s_barrier
	s_mov_b32 m0, s25
	s_nop 0
	global_load_lds_dwordx4 v132, s[34:35]
	s_mov_b32 m0, s27
	s_nop 0
	global_load_lds_dwordx4 v136, s[34:35]
	s_add_i32 s57, 0, 0x18000
	v_add_u32_e32 v173, s57, v168
	s_add_i32 s58, 0, 0x1c000
	ds_read_b128 v[128:131], v173
	ds_read_b128 v[148:151], v173 offset:1024
	ds_read_b128 v[152:155], v173 offset:2048
	ds_read_b128 v[174:177], v173 offset:3072
	v_add_u32_e32 v173, s58, v168
	ds_read_b128 v[178:181], v173
	ds_read_b128 v[182:185], v173 offset:1024
	ds_read_b128 v[186:189], v173 offset:2048
	ds_read_b128 v[190:193], v173 offset:3072
	s_add_u32 s34, s34, 0x20000
	s_addc_u32 s35, s35, 0
	s_mov_b32 m0, s43
	v_lshl_add_u64 v[238:239], s[34:35], 0, v[132:133]
	ds_read_b128 v[194:197], v172 offset:32768
	ds_read_b128 v[198:201], v172 offset:33792
	ds_read_b128 v[210:213], v172 offset:34816
	ds_read_b128 v[214:217], v172 offset:35840
	ds_read_b128 v[218:221], v172 offset:36864
	ds_read_b128 v[222:225], v172 offset:37888
	ds_read_b128 v[226:229], v172 offset:38912
	ds_read_b128 v[230:233], v172 offset:39936
	global_load_lds_dwordx4 v[238:239], off
	v_lshl_add_u64 v[238:239], s[34:35], 0, v[136:137]
	s_mov_b32 m0, s44
	s_nop 0
	global_load_lds_dwordx4 v[238:239], off
	s_waitcnt vmcnt(8)
	s_waitcnt lgkmcnt(0)
	s_barrier
	s_setprio 1
	s_waitcnt lgkmcnt(0)
	v_mfma_f32_16x16x32_bf16 v[124:127], v[128:131], v[194:197], v[124:127]
	v_mfma_f32_16x16x32_bf16 v[120:123], v[152:155], v[194:197], v[120:123]
	v_mfma_f32_16x16x32_bf16 v[116:119], v[128:131], v[210:213], v[116:119]
	v_mfma_f32_16x16x32_bf16 v[112:115], v[152:155], v[210:213], v[112:115]
	v_mfma_f32_16x16x32_bf16 v[92:95], v[128:131], v[218:221], v[92:95]
	v_mfma_f32_16x16x32_bf16 v[88:91], v[152:155], v[218:221], v[88:91]
	v_mfma_f32_16x16x32_bf16 v[84:87], v[128:131], v[226:229], v[84:87]
	v_mfma_f32_16x16x32_bf16 v[72:75], v[152:155], v[226:229], v[72:75]
	v_mfma_f32_16x16x32_bf16 v[124:127], v[148:151], v[198:201], v[124:127]
	v_mfma_f32_16x16x32_bf16 v[120:123], v[174:177], v[198:201], v[120:123]
	v_mfma_f32_16x16x32_bf16 v[116:119], v[148:151], v[214:217], v[116:119]
	v_mfma_f32_16x16x32_bf16 v[112:115], v[174:177], v[214:217], v[112:115]
	v_mfma_f32_16x16x32_bf16 v[92:95], v[148:151], v[222:225], v[92:95]
	v_mfma_f32_16x16x32_bf16 v[88:91], v[174:177], v[222:225], v[88:91]
	v_mfma_f32_16x16x32_bf16 v[84:87], v[148:151], v[230:233], v[84:87]
	v_mfma_f32_16x16x32_bf16 v[72:75], v[174:177], v[230:233], v[72:75]
	s_setprio 0
	s_setprio 1
	v_mfma_f32_16x16x32_bf16 v[108:111], v[178:181], v[194:197], v[108:111]
	v_mfma_f32_16x16x32_bf16 v[104:107], v[186:189], v[194:197], v[104:107]
	v_mfma_f32_16x16x32_bf16 v[100:103], v[178:181], v[210:213], v[100:103]
	v_mfma_f32_16x16x32_bf16 v[96:99], v[186:189], v[210:213], v[96:99]
	v_mfma_f32_16x16x32_bf16 v[80:83], v[178:181], v[218:221], v[80:83]
	v_mfma_f32_16x16x32_bf16 v[76:79], v[186:189], v[218:221], v[76:79]
	v_mfma_f32_16x16x32_bf16 v[68:71], v[178:181], v[226:229], v[68:71]
	v_mfma_f32_16x16x32_bf16 v[64:67], v[186:189], v[226:229], v[64:67]
	v_mfma_f32_16x16x32_bf16 v[108:111], v[182:185], v[198:201], v[108:111]
	v_mfma_f32_16x16x32_bf16 v[104:107], v[190:193], v[198:201], v[104:107]
	v_mfma_f32_16x16x32_bf16 v[100:103], v[182:185], v[214:217], v[100:103]
	v_mfma_f32_16x16x32_bf16 v[96:99], v[190:193], v[214:217], v[96:99]
	v_mfma_f32_16x16x32_bf16 v[80:83], v[182:185], v[222:225], v[80:83]
	v_mfma_f32_16x16x32_bf16 v[76:79], v[190:193], v[222:225], v[76:79]
	v_mfma_f32_16x16x32_bf16 v[68:71], v[182:185], v[230:233], v[68:71]
	v_mfma_f32_16x16x32_bf16 v[64:67], v[190:193], v[230:233], v[64:67]
	s_setprio 0
	s_barrier
	s_add_u32 s34, s30, 0x8000
	s_addc_u32 s35, s31, 0
	s_add_i32 s57, s57, s42
	v_lshl_add_u64 v[238:239], s[34:35], 0, v[134:135]
	s_mov_b32 m0, s57
	ds_read_b128 v[194:197], v172 offset:49152
	ds_read_b128 v[198:201], v172 offset:50176
	ds_read_b128 v[210:213], v172 offset:51200
	ds_read_b128 v[214:217], v172 offset:52224
	ds_read_b128 v[218:221], v172 offset:53248
	ds_read_b128 v[222:225], v172 offset:54272
	ds_read_b128 v[226:229], v172 offset:55296
	ds_read_b128 v[230:233], v172 offset:56320
	global_load_lds_dwordx4 v[238:239], off
	s_add_i32 m0, s57, 0x2000
	s_add_u32 s30, s30, 0xc000
	v_lshl_add_u64 v[238:239], s[34:35], 0, v[138:139]
	s_addc_u32 s31, s31, 0
	s_add_i32 s34, s58, s42
	global_load_lds_dwordx4 v[238:239], off
	v_lshl_add_u64 v[238:239], s[30:31], 0, v[134:135]
	s_mov_b32 m0, s34
	v_lshl_add_u64 v[234:235], v[234:235], 0, s[12:13]
	global_load_lds_dwordx4 v[238:239], off
	v_lshl_add_u64 v[238:239], s[30:31], 0, v[138:139]
	s_add_i32 m0, s34, 0x2000
	s_nop 0
	global_load_lds_dwordx4 v[238:239], off
	s_mov_b32 m0, s46
	s_nop 0
	global_load_lds_dwordx4 v[234:235], off
	v_lshl_add_u64 v[234:235], v[236:237], 0, s[12:13]
	s_mov_b32 m0, s47
	s_nop 0
	global_load_lds_dwordx4 v[234:235], off
	s_waitcnt vmcnt(8)
	s_waitcnt lgkmcnt(0)
	s_barrier
	s_setprio 1
	s_waitcnt lgkmcnt(0)
	v_mfma_f32_16x16x32_bf16 v[60:63], v[128:131], v[194:197], v[60:63]
	v_mfma_f32_16x16x32_bf16 v[56:59], v[152:155], v[194:197], v[56:59]
	v_mfma_f32_16x16x32_bf16 v[48:51], v[128:131], v[210:213], v[48:51]
	v_mfma_f32_16x16x32_bf16 v[40:43], v[152:155], v[210:213], v[40:43]
	v_mfma_f32_16x16x32_bf16 v[32:35], v[128:131], v[218:221], v[32:35]
	v_mfma_f32_16x16x32_bf16 v[24:27], v[152:155], v[218:221], v[24:27]
	v_mfma_f32_16x16x32_bf16 v[16:19], v[128:131], v[226:229], v[16:19]
	v_mfma_f32_16x16x32_bf16 v[8:11], v[152:155], v[226:229], v[8:11]
	v_mfma_f32_16x16x32_bf16 v[60:63], v[148:151], v[198:201], v[60:63]
	v_mfma_f32_16x16x32_bf16 v[56:59], v[174:177], v[198:201], v[56:59]
	v_mfma_f32_16x16x32_bf16 v[48:51], v[148:151], v[214:217], v[48:51]
	v_mfma_f32_16x16x32_bf16 v[40:43], v[174:177], v[214:217], v[40:43]
	v_mfma_f32_16x16x32_bf16 v[32:35], v[148:151], v[222:225], v[32:35]
	v_mfma_f32_16x16x32_bf16 v[24:27], v[174:177], v[222:225], v[24:27]
	v_mfma_f32_16x16x32_bf16 v[16:19], v[148:151], v[230:233], v[16:19]
	v_mfma_f32_16x16x32_bf16 v[8:11], v[174:177], v[230:233], v[8:11]
	s_setprio 0
	s_setprio 1
	v_mfma_f32_16x16x32_bf16 v[52:55], v[178:181], v[194:197], v[52:55]
	v_mfma_f32_16x16x32_bf16 v[44:47], v[186:189], v[194:197], v[44:47]
	v_mfma_f32_16x16x32_bf16 v[36:39], v[178:181], v[210:213], v[36:39]
	v_mfma_f32_16x16x32_bf16 v[28:31], v[186:189], v[210:213], v[28:31]
	v_mfma_f32_16x16x32_bf16 v[20:23], v[178:181], v[218:221], v[20:23]
	v_mfma_f32_16x16x32_bf16 v[12:15], v[186:189], v[218:221], v[12:15]
	v_mfma_f32_16x16x32_bf16 v[4:7], v[178:181], v[226:229], v[4:7]
	v_mfma_f32_16x16x32_bf16 v[0:3], v[186:189], v[226:229], v[0:3]
	v_mfma_f32_16x16x32_bf16 v[52:55], v[182:185], v[198:201], v[52:55]
	v_mfma_f32_16x16x32_bf16 v[44:47], v[190:193], v[198:201], v[44:47]
	v_mfma_f32_16x16x32_bf16 v[36:39], v[182:185], v[214:217], v[36:39]
	v_mfma_f32_16x16x32_bf16 v[28:31], v[190:193], v[214:217], v[28:31]
	v_mfma_f32_16x16x32_bf16 v[20:23], v[182:185], v[222:225], v[20:23]
	v_mfma_f32_16x16x32_bf16 v[12:15], v[190:193], v[222:225], v[12:15]
	v_mfma_f32_16x16x32_bf16 v[4:7], v[182:185], v[230:233], v[4:7]
	v_mfma_f32_16x16x32_bf16 v[0:3], v[190:193], v[230:233], v[0:3]
	s_setprio 0
	s_barrier
	s_add_i32 s56, s56, 2
	s_add_u32 s54, s54, 0x10000
	s_addc_u32 s55, s55, 0
	s_add_u32 s28, s28, 0x100
	s_addc_u32 s29, s29, 0
	s_cmp_gt_u32 s56, 5
	s_cbranch_scc0 .LBB0_1071
	s_and_b64 vcc, exec, s[14:15]
	s_cbranch_vccz .LBB0_1074
	s_barrier

.LBB0_1095:
	ds_read_b128 v[144:147], v155
	ds_read_b128 v[148:151], v155 offset:1024
	ds_read_b128 v[158:161], v155 offset:2048
	ds_read_b128 v[162:165], v155 offset:3072
	ds_read_b128 v[166:169], v156
	ds_read_b128 v[170:173], v156 offset:1024
	ds_read_b128 v[174:177], v156 offset:2048
	ds_read_b128 v[178:181], v156 offset:3072
	s_add_u32 s28, s26, 0xfffe0080
	s_addc_u32 s29, s27, -1
	s_cmp_eq_u32 s54, 4
	s_cselect_b32 s31, s15, s29
	s_cselect_b32 s30, s50, s28
	s_cselect_b32 s29, s17, s53
	s_cselect_b32 s28, s51, s52
	v_lshl_add_u64 v[222:223], s[26:27], 0, v[130:131]
	s_add_i32 m0, s23, 0xc000
	ds_read_b128 v[182:185], v157
	ds_read_b128 v[186:189], v157 offset:1024
	ds_read_b128 v[190:193], v157 offset:2048
	ds_read_b128 v[194:197], v157 offset:3072
	ds_read_b128 v[198:201], v157 offset:4096
	ds_read_b128 v[210:213], v157 offset:5120
	ds_read_b128 v[214:217], v157 offset:6144
	ds_read_b128 v[218:221], v157 offset:7168
	global_load_lds_dwordx4 v[222:223], off
	v_lshl_add_u64 v[222:223], s[26:27], 0, v[128:129]
	s_add_i32 m0, s23, 0xe000
	s_nop 0
	global_load_lds_dwordx4 v[222:223], off
	s_waitcnt vmcnt(8)
	s_waitcnt lgkmcnt(0)
	s_barrier
	s_setprio 1
	s_waitcnt lgkmcnt(0)
	v_mfma_f32_16x16x32_bf16 v[124:127], v[144:147], v[182:185], v[124:127]
	v_mfma_f32_16x16x32_bf16 v[120:123], v[158:161], v[182:185], v[120:123]
	v_mfma_f32_16x16x32_bf16 v[112:115], v[144:147], v[190:193], v[112:115]
	v_mfma_f32_16x16x32_bf16 v[104:107], v[158:161], v[190:193], v[104:107]
	v_mfma_f32_16x16x32_bf16 v[92:95], v[144:147], v[198:201], v[92:95]
	v_mfma_f32_16x16x32_bf16 v[88:91], v[158:161], v[198:201], v[88:91]
	v_mfma_f32_16x16x32_bf16 v[80:83], v[144:147], v[214:217], v[80:83]
	v_mfma_f32_16x16x32_bf16 v[72:75], v[158:161], v[214:217], v[72:75]
	v_mfma_f32_16x16x32_bf16 v[124:127], v[148:151], v[186:189], v[124:127]
	v_mfma_f32_16x16x32_bf16 v[120:123], v[162:165], v[186:189], v[120:123]
	v_mfma_f32_16x16x32_bf16 v[112:115], v[148:151], v[194:197], v[112:115]
	v_mfma_f32_16x16x32_bf16 v[104:107], v[162:165], v[194:197], v[104:107]
	v_mfma_f32_16x16x32_bf16 v[92:95], v[148:151], v[210:213], v[92:95]
	v_mfma_f32_16x16x32_bf16 v[88:91], v[162:165], v[210:213], v[88:91]
	v_mfma_f32_16x16x32_bf16 v[80:83], v[148:151], v[218:221], v[80:83]
	v_mfma_f32_16x16x32_bf16 v[72:75], v[162:165], v[218:221], v[72:75]
	s_setprio 0
	s_setprio 1
	v_mfma_f32_16x16x32_bf16 v[116:119], v[166:169], v[182:185], v[116:119]
	v_mfma_f32_16x16x32_bf16 v[108:111], v[174:177], v[182:185], v[108:111]
	v_mfma_f32_16x16x32_bf16 v[100:103], v[166:169], v[190:193], v[100:103]
	v_mfma_f32_16x16x32_bf16 v[96:99], v[174:177], v[190:193], v[96:99]
	v_mfma_f32_16x16x32_bf16 v[84:87], v[166:169], v[198:201], v[84:87]
	v_mfma_f32_16x16x32_bf16 v[76:79], v[174:177], v[198:201], v[76:79]
	v_mfma_f32_16x16x32_bf16 v[68:71], v[166:169], v[214:217], v[68:71]
	v_mfma_f32_16x16x32_bf16 v[64:67], v[174:177], v[214:217], v[64:67]
	v_mfma_f32_16x16x32_bf16 v[116:119], v[170:173], v[186:189], v[116:119]
	v_mfma_f32_16x16x32_bf16 v[108:111], v[178:181], v[186:189], v[108:111]
	v_mfma_f32_16x16x32_bf16 v[100:103], v[170:173], v[194:197], v[100:103]
	v_mfma_f32_16x16x32_bf16 v[96:99], v[178:181], v[194:197], v[96:99]
	v_mfma_f32_16x16x32_bf16 v[84:87], v[170:173], v[210:213], v[84:87]
	v_mfma_f32_16x16x32_bf16 v[76:79], v[178:181], v[210:213], v[76:79]
	v_mfma_f32_16x16x32_bf16 v[68:71], v[170:173], v[218:221], v[68:71]
	v_mfma_f32_16x16x32_bf16 v[64:67], v[178:181], v[218:221], v[64:67]
	s_setprio 0
	s_barrier
	s_add_i32 s55, s47, s40
	v_lshl_add_u64 v[222:223], s[28:29], 0, v[134:135]
	s_mov_b32 m0, s55
	ds_read_b128 v[182:185], v157 offset:16384
	ds_read_b128 v[186:189], v157 offset:17408
	ds_read_b128 v[190:193], v157 offset:18432
	ds_read_b128 v[194:197], v157 offset:19456
	ds_read_b128 v[198:201], v157 offset:20480
	ds_read_b128 v[210:213], v157 offset:21504
	ds_read_b128 v[214:217], v157 offset:22528
	ds_read_b128 v[218:221], v157 offset:23552
	global_load_lds_dwordx4 v[222:223], off
	s_add_i32 m0, s55, 0x2000
	s_add_u32 s56, s28, 0x4000
	v_lshl_add_u64 v[222:223], s[28:29], 0, v[138:139]
	s_addc_u32 s57, s29, 0
	s_add_i32 s55, s48, s40
	global_load_lds_dwordx4 v[222:223], off
	v_lshl_add_u64 v[222:223], s[56:57], 0, v[134:135]
	s_mov_b32 m0, s55
	v_lshl_add_u64 v[224:225], s[30:31], 0, v[136:137]
	global_load_lds_dwordx4 v[222:223], off
	v_lshl_add_u64 v[222:223], s[56:57], 0, v[138:139]
	s_add_i32 m0, s55, 0x2000
	s_nop 0
	global_load_lds_dwordx4 v[222:223], off
	v_lshl_add_u64 v[222:223], s[30:31], 0, v[132:133]
	s_waitcnt vmcnt(6)
	s_waitcnt lgkmcnt(0)
	s_barrier
	s_setprio 1
	s_waitcnt lgkmcnt(0)
	v_mfma_f32_16x16x32_bf16 v[60:63], v[144:147], v[182:185], v[60:63]
	v_mfma_f32_16x16x32_bf16 v[56:59], v[158:161], v[182:185], v[56:59]
	v_mfma_f32_16x16x32_bf16 v[48:51], v[144:147], v[190:193], v[48:51]
	v_mfma_f32_16x16x32_bf16 v[40:43], v[158:161], v[190:193], v[40:43]
	v_mfma_f32_16x16x32_bf16 v[28:31], v[144:147], v[198:201], v[28:31]
	v_mfma_f32_16x16x32_bf16 v[24:27], v[158:161], v[198:201], v[24:27]
	v_mfma_f32_16x16x32_bf16 v[16:19], v[144:147], v[214:217], v[16:19]
	v_mfma_f32_16x16x32_bf16 v[8:11], v[158:161], v[214:217], v[8:11]
	v_mfma_f32_16x16x32_bf16 v[60:63], v[148:151], v[186:189], v[60:63]
	v_mfma_f32_16x16x32_bf16 v[56:59], v[162:165], v[186:189], v[56:59]
	v_mfma_f32_16x16x32_bf16 v[48:51], v[148:151], v[194:197], v[48:51]
	v_mfma_f32_16x16x32_bf16 v[40:43], v[162:165], v[194:197], v[40:43]
	v_mfma_f32_16x16x32_bf16 v[28:31], v[148:151], v[210:213], v[28:31]
	v_mfma_f32_16x16x32_bf16 v[24:27], v[162:165], v[210:213], v[24:27]
	v_mfma_f32_16x16x32_bf16 v[16:19], v[148:151], v[218:221], v[16:19]
	v_mfma_f32_16x16x32_bf16 v[8:11], v[162:165], v[218:221], v[8:11]
	s_setprio 0
	s_setprio 1
	v_mfma_f32_16x16x32_bf16 v[52:55], v[166:169], v[182:185], v[52:55]
	v_mfma_f32_16x16x32_bf16 v[44:47], v[174:177], v[182:185], v[44:47]
	v_mfma_f32_16x16x32_bf16 v[36:39], v[166:169], v[190:193], v[36:39]
	v_mfma_f32_16x16x32_bf16 v[32:35], v[174:177], v[190:193], v[32:35]
	v_mfma_f32_16x16x32_bf16 v[20:23], v[166:169], v[198:201], v[20:23]
	v_mfma_f32_16x16x32_bf16 v[12:15], v[174:177], v[198:201], v[12:15]
	v_mfma_f32_16x16x32_bf16 v[4:7], v[166:169], v[214:217], v[4:7]
	v_mfma_f32_16x16x32_bf16 v[0:3], v[174:177], v[214:217], v[0:3]
	v_mfma_f32_16x16x32_bf16 v[52:55], v[170:173], v[186:189], v[52:55]
	v_mfma_f32_16x16x32_bf16 v[44:47], v[178:181], v[186:189], v[44:47]
	v_mfma_f32_16x16x32_bf16 v[36:39], v[170:173], v[194:197], v[36:39]
	v_mfma_f32_16x16x32_bf16 v[32:35], v[178:181], v[194:197], v[32:35]
	v_mfma_f32_16x16x32_bf16 v[20:23], v[170:173], v[210:213], v[20:23]
	v_mfma_f32_16x16x32_bf16 v[12:15], v[178:181], v[210:213], v[12:15]
	v_mfma_f32_16x16x32_bf16 v[4:7], v[170:173], v[218:221], v[4:7]
	v_mfma_f32_16x16x32_bf16 v[0:3], v[178:181], v[218:221], v[0:3]
	s_setprio 0
	s_barrier
	s_mov_b32 m0, s23
	s_nop 0
	global_load_lds_dwordx4 v132, s[30:31]
	s_mov_b32 m0, s25
	s_nop 0
	global_load_lds_dwordx4 v136, s[30:31]
	s_add_i32 s55, 0, 0x18000
	s_add_i32 s56, 0, 0x1c000
	v_add_u32_e32 v162, s55, v153
	v_add_u32_e32 v178, s56, v153
	ds_read_b128 v[144:147], v162
	ds_read_b128 v[148:151], v162 offset:1024
	ds_read_b128 v[158:161], v162 offset:2048
	ds_read_b128 v[162:165], v162 offset:3072
	ds_read_b128 v[166:169], v178
	ds_read_b128 v[170:173], v178 offset:1024
	ds_read_b128 v[174:177], v178 offset:2048
	ds_read_b128 v[178:181], v178 offset:3072
	s_add_u32 s30, s30, 0x20000
	s_addc_u32 s31, s31, 0
	s_mov_b32 m0, s41
	v_lshl_add_u64 v[226:227], s[30:31], 0, v[132:133]
	ds_read_b128 v[182:185], v157 offset:32768
	ds_read_b128 v[186:189], v157 offset:33792
	ds_read_b128 v[190:193], v157 offset:34816
	ds_read_b128 v[194:197], v157 offset:35840
	ds_read_b128 v[198:201], v157 offset:36864
	ds_read_b128 v[210:213], v157 offset:37888
	ds_read_b128 v[214:217], v157 offset:38912
	ds_read_b128 v[218:221], v157 offset:39936
	global_load_lds_dwordx4 v[226:227], off
	v_lshl_add_u64 v[226:227], s[30:31], 0, v[136:137]
	s_mov_b32 m0, s42
	s_nop 0
	global_load_lds_dwordx4 v[226:227], off
	s_waitcnt vmcnt(8)
	s_waitcnt lgkmcnt(0)
	s_barrier
	s_setprio 1
	s_waitcnt lgkmcnt(0)
	v_mfma_f32_16x16x32_bf16 v[124:127], v[144:147], v[182:185], v[124:127]
	v_mfma_f32_16x16x32_bf16 v[120:123], v[158:161], v[182:185], v[120:123]
	v_mfma_f32_16x16x32_bf16 v[112:115], v[144:147], v[190:193], v[112:115]
	v_mfma_f32_16x16x32_bf16 v[104:107], v[158:161], v[190:193], v[104:107]
	v_mfma_f32_16x16x32_bf16 v[92:95], v[144:147], v[198:201], v[92:95]
	v_mfma_f32_16x16x32_bf16 v[88:91], v[158:161], v[198:201], v[88:91]
	v_mfma_f32_16x16x32_bf16 v[80:83], v[144:147], v[214:217], v[80:83]
	v_mfma_f32_16x16x32_bf16 v[72:75], v[158:161], v[214:217], v[72:75]
	v_mfma_f32_16x16x32_bf16 v[124:127], v[148:151], v[186:189], v[124:127]
	v_mfma_f32_16x16x32_bf16 v[120:123], v[162:165], v[186:189], v[120:123]
	v_mfma_f32_16x16x32_bf16 v[112:115], v[148:151], v[194:197], v[112:115]
	v_mfma_f32_16x16x32_bf16 v[104:107], v[162:165], v[194:197], v[104:107]
	v_mfma_f32_16x16x32_bf16 v[92:95], v[148:151], v[210:213], v[92:95]
	v_mfma_f32_16x16x32_bf16 v[88:91], v[162:165], v[210:213], v[88:91]
	v_mfma_f32_16x16x32_bf16 v[80:83], v[148:151], v[218:221], v[80:83]
	v_mfma_f32_16x16x32_bf16 v[72:75], v[162:165], v[218:221], v[72:75]
	s_setprio 0
	s_setprio 1
	v_mfma_f32_16x16x32_bf16 v[116:119], v[166:169], v[182:185], v[116:119]
	v_mfma_f32_16x16x32_bf16 v[108:111], v[174:177], v[182:185], v[108:111]
	v_mfma_f32_16x16x32_bf16 v[100:103], v[166:169], v[190:193], v[100:103]
	v_mfma_f32_16x16x32_bf16 v[96:99], v[174:177], v[190:193], v[96:99]
	v_mfma_f32_16x16x32_bf16 v[84:87], v[166:169], v[198:201], v[84:87]
	v_mfma_f32_16x16x32_bf16 v[76:79], v[174:177], v[198:201], v[76:79]
	v_mfma_f32_16x16x32_bf16 v[68:71], v[166:169], v[214:217], v[68:71]
	v_mfma_f32_16x16x32_bf16 v[64:67], v[174:177], v[214:217], v[64:67]
	v_mfma_f32_16x16x32_bf16 v[116:119], v[170:173], v[186:189], v[116:119]
	v_mfma_f32_16x16x32_bf16 v[108:111], v[178:181], v[186:189], v[108:111]
	v_mfma_f32_16x16x32_bf16 v[100:103], v[170:173], v[194:197], v[100:103]
	v_mfma_f32_16x16x32_bf16 v[96:99], v[178:181], v[194:197], v[96:99]
	v_mfma_f32_16x16x32_bf16 v[84:87], v[170:173], v[210:213], v[84:87]
	v_mfma_f32_16x16x32_bf16 v[76:79], v[178:181], v[210:213], v[76:79]
	v_mfma_f32_16x16x32_bf16 v[68:71], v[170:173], v[218:221], v[68:71]
	v_mfma_f32_16x16x32_bf16 v[64:67], v[178:181], v[218:221], v[64:67]
	s_setprio 0
	s_barrier
	s_add_u32 s30, s28, 0x8000
	s_addc_u32 s31, s29, 0
	s_add_i32 s55, s55, s40
	v_lshl_add_u64 v[226:227], s[30:31], 0, v[134:135]
	s_mov_b32 m0, s55
	ds_read_b128 v[182:185], v157 offset:49152
	ds_read_b128 v[186:189], v157 offset:50176
	ds_read_b128 v[190:193], v157 offset:51200
	ds_read_b128 v[194:197], v157 offset:52224
	ds_read_b128 v[198:201], v157 offset:53248
	ds_read_b128 v[210:213], v157 offset:54272
	ds_read_b128 v[214:217], v157 offset:55296
	ds_read_b128 v[218:221], v157 offset:56320
	global_load_lds_dwordx4 v[226:227], off
	s_add_i32 m0, s55, 0x2000
	s_add_u32 s28, s28, 0xc000
	v_lshl_add_u64 v[226:227], s[30:31], 0, v[138:139]
	s_addc_u32 s29, s29, 0
	s_add_i32 s30, s56, s40
	global_load_lds_dwordx4 v[226:227], off
	v_lshl_add_u64 v[226:227], s[28:29], 0, v[134:135]
	s_mov_b32 m0, s30
	v_lshl_add_u64 v[222:223], v[222:223], 0, s[8:9]
	global_load_lds_dwordx4 v[226:227], off
	v_lshl_add_u64 v[226:227], s[28:29], 0, v[138:139]
	s_add_i32 m0, s30, 0x2000
	s_nop 0
	global_load_lds_dwordx4 v[226:227], off
	s_mov_b32 m0, s44
	s_nop 0
	global_load_lds_dwordx4 v[222:223], off
	v_lshl_add_u64 v[222:223], v[224:225], 0, s[8:9]
	s_mov_b32 m0, s45
	s_nop 0
	global_load_lds_dwordx4 v[222:223], off
	s_waitcnt vmcnt(8)
	s_waitcnt lgkmcnt(0)
	s_barrier
	s_setprio 1
	s_waitcnt lgkmcnt(0)
	v_mfma_f32_16x16x32_bf16 v[60:63], v[144:147], v[182:185], v[60:63]
	v_mfma_f32_16x16x32_bf16 v[56:59], v[158:161], v[182:185], v[56:59]
	v_mfma_f32_16x16x32_bf16 v[48:51], v[144:147], v[190:193], v[48:51]
	v_mfma_f32_16x16x32_bf16 v[40:43], v[158:161], v[190:193], v[40:43]
	v_mfma_f32_16x16x32_bf16 v[28:31], v[144:147], v[198:201], v[28:31]
	v_mfma_f32_16x16x32_bf16 v[24:27], v[158:161], v[198:201], v[24:27]
	v_mfma_f32_16x16x32_bf16 v[16:19], v[144:147], v[214:217], v[16:19]
	v_mfma_f32_16x16x32_bf16 v[8:11], v[158:161], v[214:217], v[8:11]
	v_mfma_f32_16x16x32_bf16 v[60:63], v[148:151], v[186:189], v[60:63]
	v_mfma_f32_16x16x32_bf16 v[56:59], v[162:165], v[186:189], v[56:59]
	v_mfma_f32_16x16x32_bf16 v[48:51], v[148:151], v[194:197], v[48:51]
	v_mfma_f32_16x16x32_bf16 v[40:43], v[162:165], v[194:197], v[40:43]
	v_mfma_f32_16x16x32_bf16 v[28:31], v[148:151], v[210:213], v[28:31]
	v_mfma_f32_16x16x32_bf16 v[24:27], v[162:165], v[210:213], v[24:27]
	v_mfma_f32_16x16x32_bf16 v[16:19], v[148:151], v[218:221], v[16:19]
	v_mfma_f32_16x16x32_bf16 v[8:11], v[162:165], v[218:221], v[8:11]
	s_setprio 0
	s_setprio 1
	v_mfma_f32_16x16x32_bf16 v[52:55], v[166:169], v[182:185], v[52:55]
	v_mfma_f32_16x16x32_bf16 v[44:47], v[174:177], v[182:185], v[44:47]
	v_mfma_f32_16x16x32_bf16 v[36:39], v[166:169], v[190:193], v[36:39]
	v_mfma_f32_16x16x32_bf16 v[32:35], v[174:177], v[190:193], v[32:35]
	v_mfma_f32_16x16x32_bf16 v[20:23], v[166:169], v[198:201], v[20:23]
	v_mfma_f32_16x16x32_bf16 v[12:15], v[174:177], v[198:201], v[12:15]
	v_mfma_f32_16x16x32_bf16 v[4:7], v[166:169], v[214:217], v[4:7]
	v_mfma_f32_16x16x32_bf16 v[0:3], v[174:177], v[214:217], v[0:3]
	v_mfma_f32_16x16x32_bf16 v[52:55], v[170:173], v[186:189], v[52:55]
	v_mfma_f32_16x16x32_bf16 v[44:47], v[178:181], v[186:189], v[44:47]
	v_mfma_f32_16x16x32_bf16 v[36:39], v[170:173], v[194:197], v[36:39]
	v_mfma_f32_16x16x32_bf16 v[32:35], v[178:181], v[194:197], v[32:35]
	v_mfma_f32_16x16x32_bf16 v[20:23], v[170:173], v[210:213], v[20:23]
	v_mfma_f32_16x16x32_bf16 v[12:15], v[178:181], v[210:213], v[12:15]
	v_mfma_f32_16x16x32_bf16 v[4:7], v[170:173], v[218:221], v[4:7]
	v_mfma_f32_16x16x32_bf16 v[0:3], v[178:181], v[218:221], v[0:3]
	s_setprio 0
	s_barrier
	s_add_i32 s54, s54, 2
	s_add_u32 s52, s52, 0x10000
	s_addc_u32 s53, s53, 0
	s_add_u32 s26, s26, 0x100
	s_addc_u32 s27, s27, 0
	s_cmp_gt_u32 s54, 5
	s_cbranch_scc0 .LBB0_1095
	s_and_b64 vcc, exec, s[10:11]
	s_cbranch_vccz .LBB0_1098
	s_barrier

.LBB0_1171:
	v_add_u32_e32 v168, s77, v182
	v_add_u32_e32 v204, s78, v182
	ds_read_b128 v[156:159], v168
	ds_read_b128 v[160:163], v168 offset:1024
	ds_read_b128 v[164:167], v168 offset:2048
	ds_read_b128 v[168:171], v168 offset:3072
	ds_read_b128 v[172:175], v204
	ds_read_b128 v[176:179], v204 offset:1024
	ds_read_b128 v[212:215], v204 offset:2048
	ds_read_b128 v[216:219], v204 offset:3072
	s_add_u32 s48, s46, 0xfffc0080
	s_addc_u32 s49, s47, -1
	s_cmp_eq_u32 s54, 12
	s_cselect_b32 s51, s35, s49
	s_cselect_b32 s50, s43, s48
	s_cselect_b32 s49, s37, s53
	s_cselect_b32 s48, s45, s52
	v_lshl_add_u64 v[252:253], s[46:47], 0, v[154:155]
	s_add_i32 m0, s65, 0xc000
	ds_read_b128 v[220:223], v199
	ds_read_b128 v[224:227], v199 offset:1024
	ds_read_b128 v[228:231], v199 offset:2048
	ds_read_b128 v[232:235], v199 offset:3072
	ds_read_b128 v[236:239], v199 offset:4096
	ds_read_b128 v[240:243], v199 offset:5120
	ds_read_b128 v[244:247], v199 offset:6144
	ds_read_b128 v[248:251], v199 offset:7168
	global_load_lds_dwordx4 v[252:253], off
	v_lshl_add_u64 v[252:253], s[46:47], 0, v[152:153]
	s_add_i32 m0, s65, 0xe000
	s_nop 0
	global_load_lds_dwordx4 v[252:253], off
	s_waitcnt vmcnt(8)
	s_waitcnt lgkmcnt(0)
	s_barrier
	s_setprio 1
	s_waitcnt lgkmcnt(0)
	v_mfma_f32_16x16x32_bf16 v[124:127], v[156:159], v[220:223], v[124:127]
	v_mfma_f32_16x16x32_bf16 v[120:123], v[164:167], v[220:223], v[120:123]
	v_mfma_f32_16x16x32_bf16 v[116:119], v[156:159], v[228:231], v[116:119]
	v_mfma_f32_16x16x32_bf16 v[112:115], v[164:167], v[228:231], v[112:115]
	v_mfma_f32_16x16x32_bf16 v[92:95], v[156:159], v[236:239], v[92:95]
	v_mfma_f32_16x16x32_bf16 v[88:91], v[164:167], v[236:239], v[88:91]
	v_mfma_f32_16x16x32_bf16 v[84:87], v[156:159], v[244:247], v[84:87]
	v_mfma_f32_16x16x32_bf16 v[80:83], v[164:167], v[244:247], v[80:83]
	v_mfma_f32_16x16x32_bf16 v[124:127], v[160:163], v[224:227], v[124:127]
	v_mfma_f32_16x16x32_bf16 v[120:123], v[168:171], v[224:227], v[120:123]
	v_mfma_f32_16x16x32_bf16 v[116:119], v[160:163], v[232:235], v[116:119]
	v_mfma_f32_16x16x32_bf16 v[112:115], v[168:171], v[232:235], v[112:115]
	v_mfma_f32_16x16x32_bf16 v[92:95], v[160:163], v[240:243], v[92:95]
	v_mfma_f32_16x16x32_bf16 v[88:91], v[168:171], v[240:243], v[88:91]
	v_mfma_f32_16x16x32_bf16 v[84:87], v[160:163], v[248:251], v[84:87]
	v_mfma_f32_16x16x32_bf16 v[80:83], v[168:171], v[248:251], v[80:83]
	s_setprio 0
	s_setprio 1
	v_mfma_f32_16x16x32_bf16 v[108:111], v[172:175], v[220:223], v[108:111]
	v_mfma_f32_16x16x32_bf16 v[104:107], v[212:215], v[220:223], v[104:107]
	v_mfma_f32_16x16x32_bf16 v[100:103], v[172:175], v[228:231], v[100:103]
	v_mfma_f32_16x16x32_bf16 v[96:99], v[212:215], v[228:231], v[96:99]
	v_mfma_f32_16x16x32_bf16 v[76:79], v[172:175], v[236:239], v[76:79]
	v_mfma_f32_16x16x32_bf16 v[72:75], v[212:215], v[236:239], v[72:75]
	v_mfma_f32_16x16x32_bf16 v[68:71], v[172:175], v[244:247], v[68:71]
	v_mfma_f32_16x16x32_bf16 v[64:67], v[212:215], v[244:247], v[64:67]
	v_mfma_f32_16x16x32_bf16 v[108:111], v[176:179], v[224:227], v[108:111]
	v_mfma_f32_16x16x32_bf16 v[104:107], v[216:219], v[224:227], v[104:107]
	v_mfma_f32_16x16x32_bf16 v[100:103], v[176:179], v[232:235], v[100:103]
	v_mfma_f32_16x16x32_bf16 v[96:99], v[216:219], v[232:235], v[96:99]
	v_mfma_f32_16x16x32_bf16 v[76:79], v[176:179], v[240:243], v[76:79]
	v_mfma_f32_16x16x32_bf16 v[72:75], v[216:219], v[240:243], v[72:75]
	v_mfma_f32_16x16x32_bf16 v[68:71], v[176:179], v[248:251], v[68:71]
	v_mfma_f32_16x16x32_bf16 v[64:67], v[216:219], v[248:251], v[64:67]
	s_setprio 0
	s_barrier
	s_add_i32 s55, s77, s64
	v_lshl_add_u64 v[252:253], s[48:49], 0, v[130:131]
	s_mov_b32 m0, s55
	ds_read_b128 v[220:223], v199 offset:16384
	ds_read_b128 v[224:227], v199 offset:17408
	ds_read_b128 v[228:231], v199 offset:18432
	ds_read_b128 v[232:235], v199 offset:19456
	ds_read_b128 v[236:239], v199 offset:20480
	ds_read_b128 v[240:243], v199 offset:21504
	ds_read_b128 v[244:247], v199 offset:22528
	ds_read_b128 v[248:251], v199 offset:23552
	global_load_lds_dwordx4 v[252:253], off
	s_add_i32 m0, s55, 0x2000
	s_add_u32 s56, s48, 0x4000
	v_lshl_add_u64 v[252:253], s[48:49], 0, v[134:135]
	s_addc_u32 s57, s49, 0
	s_add_i32 s55, s78, s64
	global_load_lds_dwordx4 v[252:253], off
	v_lshl_add_u64 v[252:253], s[56:57], 0, v[130:131]
	s_mov_b32 m0, s55
	v_lshl_add_u64 v[204:205], s[50:51], 0, v[132:133]
	global_load_lds_dwordx4 v[252:253], off
	v_lshl_add_u64 v[252:253], s[56:57], 0, v[134:135]
	s_add_i32 m0, s55, 0x2000
	s_nop 0
	global_load_lds_dwordx4 v[252:253], off
	v_lshl_add_u64 v[252:253], s[50:51], 0, v[128:129]
	s_waitcnt vmcnt(6)
	s_waitcnt lgkmcnt(0)
	s_barrier
	s_setprio 1
	s_waitcnt lgkmcnt(0)
	v_mfma_f32_16x16x32_bf16 v[60:63], v[156:159], v[220:223], v[60:63]
	v_mfma_f32_16x16x32_bf16 v[56:59], v[164:167], v[220:223], v[56:59]
	v_mfma_f32_16x16x32_bf16 v[52:55], v[156:159], v[228:231], v[52:55]
	v_mfma_f32_16x16x32_bf16 v[48:51], v[164:167], v[228:231], v[48:51]
	v_mfma_f32_16x16x32_bf16 v[28:31], v[156:159], v[236:239], v[28:31]
	v_mfma_f32_16x16x32_bf16 v[24:27], v[164:167], v[236:239], v[24:27]
	v_mfma_f32_16x16x32_bf16 v[20:23], v[156:159], v[244:247], v[20:23]
	v_mfma_f32_16x16x32_bf16 v[12:15], v[164:167], v[244:247], v[12:15]
	v_mfma_f32_16x16x32_bf16 v[60:63], v[160:163], v[224:227], v[60:63]
	v_mfma_f32_16x16x32_bf16 v[56:59], v[168:171], v[224:227], v[56:59]
	v_mfma_f32_16x16x32_bf16 v[52:55], v[160:163], v[232:235], v[52:55]
	v_mfma_f32_16x16x32_bf16 v[48:51], v[168:171], v[232:235], v[48:51]
	v_mfma_f32_16x16x32_bf16 v[28:31], v[160:163], v[240:243], v[28:31]
	v_mfma_f32_16x16x32_bf16 v[24:27], v[168:171], v[240:243], v[24:27]
	v_mfma_f32_16x16x32_bf16 v[20:23], v[160:163], v[248:251], v[20:23]
	v_mfma_f32_16x16x32_bf16 v[12:15], v[168:171], v[248:251], v[12:15]
	s_setprio 0
	s_setprio 1
	v_mfma_f32_16x16x32_bf16 v[44:47], v[172:175], v[220:223], v[44:47]
	v_mfma_f32_16x16x32_bf16 v[40:43], v[212:215], v[220:223], v[40:43]
	v_mfma_f32_16x16x32_bf16 v[36:39], v[172:175], v[228:231], v[36:39]
	v_mfma_f32_16x16x32_bf16 v[32:35], v[212:215], v[228:231], v[32:35]
	v_mfma_f32_16x16x32_bf16 v[16:19], v[172:175], v[236:239], v[16:19]
	v_mfma_f32_16x16x32_bf16 v[8:11], v[212:215], v[236:239], v[8:11]
	v_mfma_f32_16x16x32_bf16 v[4:7], v[172:175], v[244:247], v[4:7]
	v_mfma_f32_16x16x32_bf16 v[0:3], v[212:215], v[244:247], v[0:3]
	v_mfma_f32_16x16x32_bf16 v[44:47], v[176:179], v[224:227], v[44:47]
	v_mfma_f32_16x16x32_bf16 v[40:43], v[216:219], v[224:227], v[40:43]
	v_mfma_f32_16x16x32_bf16 v[36:39], v[176:179], v[232:235], v[36:39]
	v_mfma_f32_16x16x32_bf16 v[32:35], v[216:219], v[232:235], v[32:35]
	v_mfma_f32_16x16x32_bf16 v[16:19], v[176:179], v[240:243], v[16:19]
	v_mfma_f32_16x16x32_bf16 v[8:11], v[216:219], v[240:243], v[8:11]
	v_mfma_f32_16x16x32_bf16 v[4:7], v[176:179], v[248:251], v[4:7]
	v_mfma_f32_16x16x32_bf16 v[0:3], v[216:219], v[248:251], v[0:3]
	s_setprio 0
	s_barrier
	s_mov_b32 m0, s65
	s_nop 0
	global_load_lds_dwordx4 v128, s[50:51]
	s_mov_b32 m0, s66
	s_nop 0
	global_load_lds_dwordx4 v132, s[50:51]
	s_add_i32 s55, 0, 0x18000
	s_add_i32 s56, 0, 0x1c000
	v_add_u32_e32 v168, s55, v182
	v_add_u32_e32 v206, s56, v182
	ds_read_b128 v[156:159], v168
	ds_read_b128 v[160:163], v168 offset:1024
	ds_read_b128 v[164:167], v168 offset:2048
	ds_read_b128 v[168:171], v168 offset:3072
	ds_read_b128 v[172:175], v206
	ds_read_b128 v[176:179], v206 offset:1024
	ds_read_b128 v[212:215], v206 offset:2048
	ds_read_b128 v[216:219], v206 offset:3072
	s_add_u32 s50, s50, 0x40000
	s_addc_u32 s51, s51, 0
	s_mov_b32 m0, s67
	v_lshl_add_u64 v[206:207], s[50:51], 0, v[128:129]
	ds_read_b128 v[220:223], v199 offset:32768
	ds_read_b128 v[224:227], v199 offset:33792
	ds_read_b128 v[228:231], v199 offset:34816
	ds_read_b128 v[232:235], v199 offset:35840
	ds_read_b128 v[236:239], v199 offset:36864
	ds_read_b128 v[240:243], v199 offset:37888
	ds_read_b128 v[244:247], v199 offset:38912
	ds_read_b128 v[248:251], v199 offset:39936
	global_load_lds_dwordx4 v[206:207], off
	v_lshl_add_u64 v[206:207], s[50:51], 0, v[132:133]
	s_mov_b32 m0, s68
	s_nop 0
	global_load_lds_dwordx4 v[206:207], off
	s_waitcnt vmcnt(8)
	s_waitcnt lgkmcnt(0)
	s_barrier
	s_setprio 1
	s_waitcnt lgkmcnt(0)
	v_mfma_f32_16x16x32_bf16 v[124:127], v[156:159], v[220:223], v[124:127]
	v_mfma_f32_16x16x32_bf16 v[120:123], v[164:167], v[220:223], v[120:123]
	v_mfma_f32_16x16x32_bf16 v[116:119], v[156:159], v[228:231], v[116:119]
	v_mfma_f32_16x16x32_bf16 v[112:115], v[164:167], v[228:231], v[112:115]
	v_mfma_f32_16x16x32_bf16 v[92:95], v[156:159], v[236:239], v[92:95]
	v_mfma_f32_16x16x32_bf16 v[88:91], v[164:167], v[236:239], v[88:91]
	v_mfma_f32_16x16x32_bf16 v[84:87], v[156:159], v[244:247], v[84:87]
	v_mfma_f32_16x16x32_bf16 v[80:83], v[164:167], v[244:247], v[80:83]
	v_mfma_f32_16x16x32_bf16 v[124:127], v[160:163], v[224:227], v[124:127]
	v_mfma_f32_16x16x32_bf16 v[120:123], v[168:171], v[224:227], v[120:123]
	v_mfma_f32_16x16x32_bf16 v[116:119], v[160:163], v[232:235], v[116:119]
	v_mfma_f32_16x16x32_bf16 v[112:115], v[168:171], v[232:235], v[112:115]
	v_mfma_f32_16x16x32_bf16 v[92:95], v[160:163], v[240:243], v[92:95]
	v_mfma_f32_16x16x32_bf16 v[88:91], v[168:171], v[240:243], v[88:91]
	v_mfma_f32_16x16x32_bf16 v[84:87], v[160:163], v[248:251], v[84:87]
	v_mfma_f32_16x16x32_bf16 v[80:83], v[168:171], v[248:251], v[80:83]
	s_setprio 0
	s_setprio 1
	v_mfma_f32_16x16x32_bf16 v[108:111], v[172:175], v[220:223], v[108:111]
	v_mfma_f32_16x16x32_bf16 v[104:107], v[212:215], v[220:223], v[104:107]
	v_mfma_f32_16x16x32_bf16 v[100:103], v[172:175], v[228:231], v[100:103]
	v_mfma_f32_16x16x32_bf16 v[96:99], v[212:215], v[228:231], v[96:99]
	v_mfma_f32_16x16x32_bf16 v[76:79], v[172:175], v[236:239], v[76:79]
	v_mfma_f32_16x16x32_bf16 v[72:75], v[212:215], v[236:239], v[72:75]
	v_mfma_f32_16x16x32_bf16 v[68:71], v[172:175], v[244:247], v[68:71]
	v_mfma_f32_16x16x32_bf16 v[64:67], v[212:215], v[244:247], v[64:67]
	v_mfma_f32_16x16x32_bf16 v[108:111], v[176:179], v[224:227], v[108:111]
	v_mfma_f32_16x16x32_bf16 v[104:107], v[216:219], v[224:227], v[104:107]
	v_mfma_f32_16x16x32_bf16 v[100:103], v[176:179], v[232:235], v[100:103]
	v_mfma_f32_16x16x32_bf16 v[96:99], v[216:219], v[232:235], v[96:99]
	v_mfma_f32_16x16x32_bf16 v[76:79], v[176:179], v[240:243], v[76:79]
	v_mfma_f32_16x16x32_bf16 v[72:75], v[216:219], v[240:243], v[72:75]
	v_mfma_f32_16x16x32_bf16 v[68:71], v[176:179], v[248:251], v[68:71]
	v_mfma_f32_16x16x32_bf16 v[64:67], v[216:219], v[248:251], v[64:67]
	s_setprio 0
	s_barrier
	s_add_u32 s50, s48, 0x8000
	s_addc_u32 s51, s49, 0
	s_add_i32 s55, s55, s64
	v_lshl_add_u64 v[206:207], s[50:51], 0, v[130:131]
	s_mov_b32 m0, s55
	ds_read_b128 v[220:223], v199 offset:49152
	ds_read_b128 v[224:227], v199 offset:50176
	ds_read_b128 v[228:231], v199 offset:51200
	ds_read_b128 v[232:235], v199 offset:52224
	ds_read_b128 v[236:239], v199 offset:53248
	ds_read_b128 v[240:243], v199 offset:54272
	ds_read_b128 v[244:247], v199 offset:55296
	ds_read_b128 v[248:251], v199 offset:56320
	global_load_lds_dwordx4 v[206:207], off
	s_add_i32 m0, s55, 0x2000
	s_add_u32 s48, s48, 0xc000
	v_lshl_add_u64 v[206:207], s[50:51], 0, v[134:135]
	s_addc_u32 s49, s49, 0
	s_add_i32 s50, s56, s64
	global_load_lds_dwordx4 v[206:207], off
	v_lshl_add_u64 v[206:207], s[48:49], 0, v[130:131]
	s_mov_b32 m0, s50
	v_lshl_add_u64 v[204:205], v[204:205], 0, s[14:15]
	global_load_lds_dwordx4 v[206:207], off
	v_lshl_add_u64 v[206:207], s[48:49], 0, v[134:135]
	s_add_i32 m0, s50, 0x2000
	s_nop 0
	global_load_lds_dwordx4 v[206:207], off
	v_lshl_add_u64 v[206:207], v[252:253], 0, s[14:15]
	s_mov_b32 m0, s74
	s_nop 0
	global_load_lds_dwordx4 v[206:207], off
	s_mov_b32 m0, s75
	s_nop 0
	global_load_lds_dwordx4 v[204:205], off
	s_waitcnt vmcnt(8)
	s_waitcnt lgkmcnt(0)
	s_barrier
	s_setprio 1
	s_waitcnt lgkmcnt(0)
	v_mfma_f32_16x16x32_bf16 v[60:63], v[156:159], v[220:223], v[60:63]
	v_mfma_f32_16x16x32_bf16 v[56:59], v[164:167], v[220:223], v[56:59]
	v_mfma_f32_16x16x32_bf16 v[52:55], v[156:159], v[228:231], v[52:55]
	v_mfma_f32_16x16x32_bf16 v[48:51], v[164:167], v[228:231], v[48:51]
	v_mfma_f32_16x16x32_bf16 v[28:31], v[156:159], v[236:239], v[28:31]
	v_mfma_f32_16x16x32_bf16 v[24:27], v[164:167], v[236:239], v[24:27]
	v_mfma_f32_16x16x32_bf16 v[20:23], v[156:159], v[244:247], v[20:23]
	v_mfma_f32_16x16x32_bf16 v[12:15], v[164:167], v[244:247], v[12:15]
	v_mfma_f32_16x16x32_bf16 v[60:63], v[160:163], v[224:227], v[60:63]
	v_mfma_f32_16x16x32_bf16 v[56:59], v[168:171], v[224:227], v[56:59]
	v_mfma_f32_16x16x32_bf16 v[52:55], v[160:163], v[232:235], v[52:55]
	v_mfma_f32_16x16x32_bf16 v[48:51], v[168:171], v[232:235], v[48:51]
	v_mfma_f32_16x16x32_bf16 v[28:31], v[160:163], v[240:243], v[28:31]
	v_mfma_f32_16x16x32_bf16 v[24:27], v[168:171], v[240:243], v[24:27]
	v_mfma_f32_16x16x32_bf16 v[20:23], v[160:163], v[248:251], v[20:23]
	v_mfma_f32_16x16x32_bf16 v[12:15], v[168:171], v[248:251], v[12:15]
	s_setprio 0
	s_setprio 1
	v_mfma_f32_16x16x32_bf16 v[44:47], v[172:175], v[220:223], v[44:47]
	v_mfma_f32_16x16x32_bf16 v[40:43], v[212:215], v[220:223], v[40:43]
	v_mfma_f32_16x16x32_bf16 v[36:39], v[172:175], v[228:231], v[36:39]
	v_mfma_f32_16x16x32_bf16 v[32:35], v[212:215], v[228:231], v[32:35]
	v_mfma_f32_16x16x32_bf16 v[16:19], v[172:175], v[236:239], v[16:19]
	v_mfma_f32_16x16x32_bf16 v[8:11], v[212:215], v[236:239], v[8:11]
	v_mfma_f32_16x16x32_bf16 v[4:7], v[172:175], v[244:247], v[4:7]
	v_mfma_f32_16x16x32_bf16 v[0:3], v[212:215], v[244:247], v[0:3]
	v_mfma_f32_16x16x32_bf16 v[44:47], v[176:179], v[224:227], v[44:47]
	v_mfma_f32_16x16x32_bf16 v[40:43], v[216:219], v[224:227], v[40:43]
	v_mfma_f32_16x16x32_bf16 v[36:39], v[176:179], v[232:235], v[36:39]
	v_mfma_f32_16x16x32_bf16 v[32:35], v[216:219], v[232:235], v[32:35]
	v_mfma_f32_16x16x32_bf16 v[16:19], v[176:179], v[240:243], v[16:19]
	v_mfma_f32_16x16x32_bf16 v[8:11], v[216:219], v[240:243], v[8:11]
	v_mfma_f32_16x16x32_bf16 v[4:7], v[176:179], v[248:251], v[4:7]
	v_mfma_f32_16x16x32_bf16 v[0:3], v[216:219], v[248:251], v[0:3]
	s_setprio 0
	s_barrier
	s_add_i32 s54, s54, 2
	s_add_u32 s52, s52, 0x10000
	s_addc_u32 s53, s53, 0
	s_add_u32 s46, s46, 0x100
	s_addc_u32 s47, s47, 0
	s_cmp_gt_u32 s54, 13
	s_cbranch_scc0 .LBB0_1171
	s_and_b64 vcc, exec, s[18:19]
	s_cbranch_vccz .LBB0_1174
	s_barrier

.LBB0_1253:
	ds_read_b128 v[170:173], v167
	ds_read_b128 v[174:177], v167 offset:1024
	ds_read_b128 v[178:181], v167 offset:2048
	ds_read_b128 v[182:185], v167 offset:3072
	ds_read_b128 v[186:189], v168
	ds_read_b128 v[190:193], v168 offset:1024
	ds_read_b128 v[194:197], v168 offset:2048
	ds_read_b128 v[198:201], v168 offset:3072
	s_add_u32 s26, s24, 0xfffc0080
	s_addc_u32 s27, s25, -1
	s_cmp_eq_u32 s54, 12
	s_cselect_b32 s29, s11, s27
	s_cselect_b32 s28, s50, s26
	s_cselect_b32 s27, s13, s53
	s_cselect_b32 s26, s51, s52
	v_lshl_add_u64 v[164:165], s[24:25], 0, v[158:159]
	s_add_i32 m0, s21, 0xc000
	ds_read_b128 v[210:213], v169
	ds_read_b128 v[214:217], v169 offset:1024
	ds_read_b128 v[218:221], v169 offset:2048
	ds_read_b128 v[222:225], v169 offset:3072
	ds_read_b128 v[226:229], v169 offset:4096
	ds_read_b128 v[230:233], v169 offset:5120
	ds_read_b128 v[234:237], v169 offset:6144
	ds_read_b128 v[238:241], v169 offset:7168
	global_load_lds_dwordx4 v[164:165], off
	v_lshl_add_u64 v[164:165], s[24:25], 0, v[156:157]
	s_add_i32 m0, s21, 0xe000
	s_nop 0
	global_load_lds_dwordx4 v[164:165], off
	s_waitcnt vmcnt(8)
	s_waitcnt lgkmcnt(0)
	s_barrier
	s_setprio 1
	s_waitcnt lgkmcnt(0)
	v_mfma_f32_16x16x32_bf16 v[124:127], v[170:173], v[210:213], v[124:127]
	v_mfma_f32_16x16x32_bf16 v[116:119], v[178:181], v[210:213], v[116:119]
	v_mfma_f32_16x16x32_bf16 v[108:111], v[170:173], v[218:221], v[108:111]
	v_mfma_f32_16x16x32_bf16 v[100:103], v[178:181], v[218:221], v[100:103]
	v_mfma_f32_16x16x32_bf16 v[92:95], v[170:173], v[226:229], v[92:95]
	v_mfma_f32_16x16x32_bf16 v[84:87], v[178:181], v[226:229], v[84:87]
	v_mfma_f32_16x16x32_bf16 v[76:79], v[170:173], v[234:237], v[76:79]
	v_mfma_f32_16x16x32_bf16 v[68:71], v[178:181], v[234:237], v[68:71]
	v_mfma_f32_16x16x32_bf16 v[124:127], v[174:177], v[214:217], v[124:127]
	v_mfma_f32_16x16x32_bf16 v[116:119], v[182:185], v[214:217], v[116:119]
	v_mfma_f32_16x16x32_bf16 v[108:111], v[174:177], v[222:225], v[108:111]
	v_mfma_f32_16x16x32_bf16 v[100:103], v[182:185], v[222:225], v[100:103]
	v_mfma_f32_16x16x32_bf16 v[92:95], v[174:177], v[230:233], v[92:95]
	v_mfma_f32_16x16x32_bf16 v[84:87], v[182:185], v[230:233], v[84:87]
	v_mfma_f32_16x16x32_bf16 v[76:79], v[174:177], v[238:241], v[76:79]
	v_mfma_f32_16x16x32_bf16 v[68:71], v[182:185], v[238:241], v[68:71]
	s_setprio 0
	s_setprio 1
	v_mfma_f32_16x16x32_bf16 v[120:123], v[186:189], v[210:213], v[120:123]
	v_mfma_f32_16x16x32_bf16 v[112:115], v[194:197], v[210:213], v[112:115]
	v_mfma_f32_16x16x32_bf16 v[104:107], v[186:189], v[218:221], v[104:107]
	v_mfma_f32_16x16x32_bf16 v[96:99], v[194:197], v[218:221], v[96:99]
	v_mfma_f32_16x16x32_bf16 v[88:91], v[186:189], v[226:229], v[88:91]
	v_mfma_f32_16x16x32_bf16 v[80:83], v[194:197], v[226:229], v[80:83]
	v_mfma_f32_16x16x32_bf16 v[72:75], v[186:189], v[234:237], v[72:75]
	v_mfma_f32_16x16x32_bf16 v[64:67], v[194:197], v[234:237], v[64:67]
	v_mfma_f32_16x16x32_bf16 v[120:123], v[190:193], v[214:217], v[120:123]
	v_mfma_f32_16x16x32_bf16 v[112:115], v[198:201], v[214:217], v[112:115]
	v_mfma_f32_16x16x32_bf16 v[104:107], v[190:193], v[222:225], v[104:107]
	v_mfma_f32_16x16x32_bf16 v[96:99], v[198:201], v[222:225], v[96:99]
	v_mfma_f32_16x16x32_bf16 v[88:91], v[190:193], v[230:233], v[88:91]
	v_mfma_f32_16x16x32_bf16 v[80:83], v[198:201], v[230:233], v[80:83]
	v_mfma_f32_16x16x32_bf16 v[72:75], v[190:193], v[238:241], v[72:75]
	v_mfma_f32_16x16x32_bf16 v[64:67], v[198:201], v[238:241], v[64:67]
	s_setprio 0
	s_barrier
	s_add_i32 s55, s48, s35
	v_lshl_add_u64 v[164:165], s[26:27], 0, v[134:135]
	s_mov_b32 m0, s55
	ds_read_b128 v[210:213], v169 offset:16384
	ds_read_b128 v[214:217], v169 offset:17408
	ds_read_b128 v[218:221], v169 offset:18432
	ds_read_b128 v[222:225], v169 offset:19456
	ds_read_b128 v[226:229], v169 offset:20480
	ds_read_b128 v[230:233], v169 offset:21504
	ds_read_b128 v[234:237], v169 offset:22528
	ds_read_b128 v[238:241], v169 offset:23552
	global_load_lds_dwordx4 v[164:165], off
	s_add_i32 m0, s55, 0x2000
	s_add_u32 s56, s26, 0x4000
	v_lshl_add_u64 v[164:165], s[26:27], 0, v[130:131]
	s_addc_u32 s57, s27, 0
	s_add_i32 s55, s49, s35
	global_load_lds_dwordx4 v[164:165], off
	v_lshl_add_u64 v[164:165], s[56:57], 0, v[134:135]
	s_mov_b32 m0, s55
	v_lshl_add_u64 v[204:205], s[28:29], 0, v[132:133]
	global_load_lds_dwordx4 v[164:165], off
	v_lshl_add_u64 v[164:165], s[56:57], 0, v[130:131]
	s_add_i32 m0, s55, 0x2000
	s_nop 0
	global_load_lds_dwordx4 v[164:165], off
	v_lshl_add_u64 v[164:165], s[28:29], 0, v[136:137]
	s_waitcnt vmcnt(6)
	s_waitcnt lgkmcnt(0)
	s_barrier
	s_setprio 1
	s_waitcnt lgkmcnt(0)
	v_mfma_f32_16x16x32_bf16 v[60:63], v[170:173], v[210:213], v[60:63]
	v_mfma_f32_16x16x32_bf16 v[52:55], v[178:181], v[210:213], v[52:55]
	v_mfma_f32_16x16x32_bf16 v[44:47], v[170:173], v[218:221], v[44:47]
	v_mfma_f32_16x16x32_bf16 v[36:39], v[178:181], v[218:221], v[36:39]
	v_mfma_f32_16x16x32_bf16 v[28:31], v[170:173], v[226:229], v[28:31]
	v_mfma_f32_16x16x32_bf16 v[20:23], v[178:181], v[226:229], v[20:23]
	v_mfma_f32_16x16x32_bf16 v[12:15], v[170:173], v[234:237], v[12:15]
	v_mfma_f32_16x16x32_bf16 v[4:7], v[178:181], v[234:237], v[4:7]
	v_mfma_f32_16x16x32_bf16 v[60:63], v[174:177], v[214:217], v[60:63]
	v_mfma_f32_16x16x32_bf16 v[52:55], v[182:185], v[214:217], v[52:55]
	v_mfma_f32_16x16x32_bf16 v[44:47], v[174:177], v[222:225], v[44:47]
	v_mfma_f32_16x16x32_bf16 v[36:39], v[182:185], v[222:225], v[36:39]
	v_mfma_f32_16x16x32_bf16 v[28:31], v[174:177], v[230:233], v[28:31]
	v_mfma_f32_16x16x32_bf16 v[20:23], v[182:185], v[230:233], v[20:23]
	v_mfma_f32_16x16x32_bf16 v[12:15], v[174:177], v[238:241], v[12:15]
	v_mfma_f32_16x16x32_bf16 v[4:7], v[182:185], v[238:241], v[4:7]
	s_setprio 0
	s_setprio 1
	v_mfma_f32_16x16x32_bf16 v[56:59], v[186:189], v[210:213], v[56:59]
	v_mfma_f32_16x16x32_bf16 v[48:51], v[194:197], v[210:213], v[48:51]
	v_mfma_f32_16x16x32_bf16 v[40:43], v[186:189], v[218:221], v[40:43]
	v_mfma_f32_16x16x32_bf16 v[32:35], v[194:197], v[218:221], v[32:35]
	v_mfma_f32_16x16x32_bf16 v[24:27], v[186:189], v[226:229], v[24:27]
	v_mfma_f32_16x16x32_bf16 v[16:19], v[194:197], v[226:229], v[16:19]
	v_mfma_f32_16x16x32_bf16 v[8:11], v[186:189], v[234:237], v[8:11]
	v_mfma_f32_16x16x32_bf16 v[0:3], v[194:197], v[234:237], v[0:3]
	v_mfma_f32_16x16x32_bf16 v[56:59], v[190:193], v[214:217], v[56:59]
	v_mfma_f32_16x16x32_bf16 v[48:51], v[198:201], v[214:217], v[48:51]
	v_mfma_f32_16x16x32_bf16 v[40:43], v[190:193], v[222:225], v[40:43]
	v_mfma_f32_16x16x32_bf16 v[32:35], v[198:201], v[222:225], v[32:35]
	v_mfma_f32_16x16x32_bf16 v[24:27], v[190:193], v[230:233], v[24:27]
	v_mfma_f32_16x16x32_bf16 v[16:19], v[198:201], v[230:233], v[16:19]
	v_mfma_f32_16x16x32_bf16 v[8:11], v[190:193], v[238:241], v[8:11]
	v_mfma_f32_16x16x32_bf16 v[0:3], v[198:201], v[238:241], v[0:3]
	s_setprio 0
	s_barrier
	s_mov_b32 m0, s21
	s_nop 0
	global_load_lds_dwordx4 v136, s[28:29]
	s_mov_b32 m0, s23
	s_nop 0
	global_load_lds_dwordx4 v132, s[28:29]
	s_add_i32 s55, 0, 0x18000
	s_add_i32 s56, 0, 0x1c000
	v_add_u32_e32 v182, s55, v129
	v_add_u32_e32 v198, s56, v129
	ds_read_b128 v[170:173], v182
	ds_read_b128 v[174:177], v182 offset:1024
	ds_read_b128 v[178:181], v182 offset:2048
	ds_read_b128 v[182:185], v182 offset:3072
	ds_read_b128 v[186:189], v198
	ds_read_b128 v[190:193], v198 offset:1024
	ds_read_b128 v[194:197], v198 offset:2048
	ds_read_b128 v[198:201], v198 offset:3072
	s_add_u32 s28, s28, 0x40000
	s_addc_u32 s29, s29, 0
	s_mov_b32 m0, s39
	v_lshl_add_u64 v[206:207], s[28:29], 0, v[136:137]
	ds_read_b128 v[210:213], v169 offset:32768
	ds_read_b128 v[214:217], v169 offset:33792
	ds_read_b128 v[218:221], v169 offset:34816
	ds_read_b128 v[222:225], v169 offset:35840
	ds_read_b128 v[226:229], v169 offset:36864
	ds_read_b128 v[230:233], v169 offset:37888
	ds_read_b128 v[234:237], v169 offset:38912
	ds_read_b128 v[238:241], v169 offset:39936
	global_load_lds_dwordx4 v[206:207], off
	v_lshl_add_u64 v[206:207], s[28:29], 0, v[132:133]
	s_mov_b32 m0, s40
	s_nop 0
	global_load_lds_dwordx4 v[206:207], off
	s_waitcnt vmcnt(8)
	s_waitcnt lgkmcnt(0)
	s_barrier
	s_setprio 1
	s_waitcnt lgkmcnt(0)
	v_mfma_f32_16x16x32_bf16 v[124:127], v[170:173], v[210:213], v[124:127]
	v_mfma_f32_16x16x32_bf16 v[116:119], v[178:181], v[210:213], v[116:119]
	v_mfma_f32_16x16x32_bf16 v[108:111], v[170:173], v[218:221], v[108:111]
	v_mfma_f32_16x16x32_bf16 v[100:103], v[178:181], v[218:221], v[100:103]
	v_mfma_f32_16x16x32_bf16 v[92:95], v[170:173], v[226:229], v[92:95]
	v_mfma_f32_16x16x32_bf16 v[84:87], v[178:181], v[226:229], v[84:87]
	v_mfma_f32_16x16x32_bf16 v[76:79], v[170:173], v[234:237], v[76:79]
	v_mfma_f32_16x16x32_bf16 v[68:71], v[178:181], v[234:237], v[68:71]
	v_mfma_f32_16x16x32_bf16 v[124:127], v[174:177], v[214:217], v[124:127]
	v_mfma_f32_16x16x32_bf16 v[116:119], v[182:185], v[214:217], v[116:119]
	v_mfma_f32_16x16x32_bf16 v[108:111], v[174:177], v[222:225], v[108:111]
	v_mfma_f32_16x16x32_bf16 v[100:103], v[182:185], v[222:225], v[100:103]
	v_mfma_f32_16x16x32_bf16 v[92:95], v[174:177], v[230:233], v[92:95]
	v_mfma_f32_16x16x32_bf16 v[84:87], v[182:185], v[230:233], v[84:87]
	v_mfma_f32_16x16x32_bf16 v[76:79], v[174:177], v[238:241], v[76:79]
	v_mfma_f32_16x16x32_bf16 v[68:71], v[182:185], v[238:241], v[68:71]
	s_setprio 0
	s_setprio 1
	v_mfma_f32_16x16x32_bf16 v[120:123], v[186:189], v[210:213], v[120:123]
	v_mfma_f32_16x16x32_bf16 v[112:115], v[194:197], v[210:213], v[112:115]
	v_mfma_f32_16x16x32_bf16 v[104:107], v[186:189], v[218:221], v[104:107]
	v_mfma_f32_16x16x32_bf16 v[96:99], v[194:197], v[218:221], v[96:99]
	v_mfma_f32_16x16x32_bf16 v[88:91], v[186:189], v[226:229], v[88:91]
	v_mfma_f32_16x16x32_bf16 v[80:83], v[194:197], v[226:229], v[80:83]
	v_mfma_f32_16x16x32_bf16 v[72:75], v[186:189], v[234:237], v[72:75]
	v_mfma_f32_16x16x32_bf16 v[64:67], v[194:197], v[234:237], v[64:67]
	v_mfma_f32_16x16x32_bf16 v[120:123], v[190:193], v[214:217], v[120:123]
	v_mfma_f32_16x16x32_bf16 v[112:115], v[198:201], v[214:217], v[112:115]
	v_mfma_f32_16x16x32_bf16 v[104:107], v[190:193], v[222:225], v[104:107]
	v_mfma_f32_16x16x32_bf16 v[96:99], v[198:201], v[222:225], v[96:99]
	v_mfma_f32_16x16x32_bf16 v[88:91], v[190:193], v[230:233], v[88:91]
	v_mfma_f32_16x16x32_bf16 v[80:83], v[198:201], v[230:233], v[80:83]
	v_mfma_f32_16x16x32_bf16 v[72:75], v[190:193], v[238:241], v[72:75]
	v_mfma_f32_16x16x32_bf16 v[64:67], v[198:201], v[238:241], v[64:67]
	s_setprio 0
	s_barrier
	s_add_u32 s28, s26, 0x8000
	s_addc_u32 s29, s27, 0
	s_add_i32 s55, s55, s35
	v_lshl_add_u64 v[206:207], s[28:29], 0, v[134:135]
	s_mov_b32 m0, s55
	ds_read_b128 v[210:213], v169 offset:49152
	ds_read_b128 v[214:217], v169 offset:50176
	ds_read_b128 v[218:221], v169 offset:51200
	ds_read_b128 v[222:225], v169 offset:52224
	ds_read_b128 v[226:229], v169 offset:53248
	ds_read_b128 v[230:233], v169 offset:54272
	ds_read_b128 v[234:237], v169 offset:55296
	ds_read_b128 v[238:241], v169 offset:56320
	global_load_lds_dwordx4 v[206:207], off
	s_add_i32 m0, s55, 0x2000
	s_add_u32 s26, s26, 0xc000
	v_lshl_add_u64 v[206:207], s[28:29], 0, v[130:131]
	s_addc_u32 s27, s27, 0
	s_add_i32 s28, s56, s35
	global_load_lds_dwordx4 v[206:207], off
	v_lshl_add_u64 v[206:207], s[26:27], 0, v[134:135]
	s_mov_b32 m0, s28
	v_lshl_add_u64 v[164:165], v[164:165], 0, s[6:7]
	global_load_lds_dwordx4 v[206:207], off
	v_lshl_add_u64 v[206:207], s[26:27], 0, v[130:131]
	s_add_i32 m0, s28, 0x2000
	s_nop 0
	global_load_lds_dwordx4 v[206:207], off
	s_mov_b32 m0, s45
	s_nop 0
	global_load_lds_dwordx4 v[164:165], off
	v_lshl_add_u64 v[164:165], v[204:205], 0, s[6:7]
	s_mov_b32 m0, s46
	s_nop 0
	global_load_lds_dwordx4 v[164:165], off
	s_waitcnt vmcnt(8)
	s_waitcnt lgkmcnt(0)
	s_barrier
	s_setprio 1
	s_waitcnt lgkmcnt(0)
	v_mfma_f32_16x16x32_bf16 v[60:63], v[170:173], v[210:213], v[60:63]
	v_mfma_f32_16x16x32_bf16 v[52:55], v[178:181], v[210:213], v[52:55]
	v_mfma_f32_16x16x32_bf16 v[44:47], v[170:173], v[218:221], v[44:47]
	v_mfma_f32_16x16x32_bf16 v[36:39], v[178:181], v[218:221], v[36:39]
	v_mfma_f32_16x16x32_bf16 v[28:31], v[170:173], v[226:229], v[28:31]
	v_mfma_f32_16x16x32_bf16 v[20:23], v[178:181], v[226:229], v[20:23]
	v_mfma_f32_16x16x32_bf16 v[12:15], v[170:173], v[234:237], v[12:15]
	v_mfma_f32_16x16x32_bf16 v[4:7], v[178:181], v[234:237], v[4:7]
	v_mfma_f32_16x16x32_bf16 v[60:63], v[174:177], v[214:217], v[60:63]
	v_mfma_f32_16x16x32_bf16 v[52:55], v[182:185], v[214:217], v[52:55]
	v_mfma_f32_16x16x32_bf16 v[44:47], v[174:177], v[222:225], v[44:47]
	v_mfma_f32_16x16x32_bf16 v[36:39], v[182:185], v[222:225], v[36:39]
	v_mfma_f32_16x16x32_bf16 v[28:31], v[174:177], v[230:233], v[28:31]
	v_mfma_f32_16x16x32_bf16 v[20:23], v[182:185], v[230:233], v[20:23]
	v_mfma_f32_16x16x32_bf16 v[12:15], v[174:177], v[238:241], v[12:15]
	v_mfma_f32_16x16x32_bf16 v[4:7], v[182:185], v[238:241], v[4:7]
	s_setprio 0
	s_setprio 1
	v_mfma_f32_16x16x32_bf16 v[56:59], v[186:189], v[210:213], v[56:59]
	v_mfma_f32_16x16x32_bf16 v[48:51], v[194:197], v[210:213], v[48:51]
	v_mfma_f32_16x16x32_bf16 v[40:43], v[186:189], v[218:221], v[40:43]
	v_mfma_f32_16x16x32_bf16 v[32:35], v[194:197], v[218:221], v[32:35]
	v_mfma_f32_16x16x32_bf16 v[24:27], v[186:189], v[226:229], v[24:27]
	v_mfma_f32_16x16x32_bf16 v[16:19], v[194:197], v[226:229], v[16:19]
	v_mfma_f32_16x16x32_bf16 v[8:11], v[186:189], v[234:237], v[8:11]
	v_mfma_f32_16x16x32_bf16 v[0:3], v[194:197], v[234:237], v[0:3]
	v_mfma_f32_16x16x32_bf16 v[56:59], v[190:193], v[214:217], v[56:59]
	v_mfma_f32_16x16x32_bf16 v[48:51], v[198:201], v[214:217], v[48:51]
	v_mfma_f32_16x16x32_bf16 v[40:43], v[190:193], v[222:225], v[40:43]
	v_mfma_f32_16x16x32_bf16 v[32:35], v[198:201], v[222:225], v[32:35]
	v_mfma_f32_16x16x32_bf16 v[24:27], v[190:193], v[230:233], v[24:27]
	v_mfma_f32_16x16x32_bf16 v[16:19], v[198:201], v[230:233], v[16:19]
	v_mfma_f32_16x16x32_bf16 v[8:11], v[190:193], v[238:241], v[8:11]
	v_mfma_f32_16x16x32_bf16 v[0:3], v[198:201], v[238:241], v[0:3]
	s_setprio 0
	s_barrier
	s_add_i32 s54, s54, 2
	s_add_u32 s52, s52, 0x10000
	s_addc_u32 s53, s53, 0
	s_add_u32 s24, s24, 0x100
	s_addc_u32 s25, s25, 0
	s_cmp_gt_u32 s54, 13
	s_cbranch_scc0 .LBB0_1253
	s_and_b64 vcc, exec, s[8:9]
	s_cbranch_vccz .LBB0_1256
	s_barrier

.LBB0_1481:
	v_add_u32_e32 v168, s61, v182
	v_add_u32_e32 v204, s62, v182
	ds_read_b128 v[156:159], v168
	ds_read_b128 v[160:163], v168 offset:1024
	ds_read_b128 v[164:167], v168 offset:2048
	ds_read_b128 v[168:171], v168 offset:3072
	ds_read_b128 v[172:175], v204
	ds_read_b128 v[176:179], v204 offset:1024
	ds_read_b128 v[212:215], v204 offset:2048
	ds_read_b128 v[216:219], v204 offset:3072
	s_add_u32 s38, s36, 0x4000
	s_addc_u32 s39, s37, 0
	s_cmp_eq_u32 s70, 40
	s_cselect_b32 s42, s0, s38
	s_cselect_b32 s43, s1, s39
	s_cselect_b32 s40, s34, s68
	s_cselect_b32 s41, s35, s69
	s_add_u32 s38, s42, 0x8000
	s_addc_u32 s39, s43, 0
	v_lshl_add_u64 v[204:205], s[36:37], 0, v[150:151]
	s_add_i32 m0, s48, 0xc000
	ds_read_b128 v[220:223], v199
	ds_read_b128 v[224:227], v199 offset:1024
	ds_read_b128 v[228:231], v199 offset:2048
	ds_read_b128 v[232:235], v199 offset:3072
	ds_read_b128 v[236:239], v199 offset:4096
	ds_read_b128 v[240:243], v199 offset:5120
	ds_read_b128 v[244:247], v199 offset:6144
	ds_read_b128 v[248:251], v199 offset:7168
	global_load_lds_dwordx4 v[204:205], off
	v_lshl_add_u64 v[204:205], s[36:37], 0, v[148:149]
	s_add_i32 m0, s48, 0xe000
	s_nop 0
	global_load_lds_dwordx4 v[204:205], off
	s_waitcnt vmcnt(8)
	s_waitcnt lgkmcnt(0)
	s_barrier
	s_setprio 1
	s_waitcnt lgkmcnt(0)
	v_mfma_f32_16x16x32_bf16 v[124:127], v[156:159], v[220:223], v[124:127]
	v_mfma_f32_16x16x32_bf16 v[120:123], v[164:167], v[220:223], v[120:123]
	v_mfma_f32_16x16x32_bf16 v[116:119], v[156:159], v[228:231], v[116:119]
	v_mfma_f32_16x16x32_bf16 v[112:115], v[164:167], v[228:231], v[112:115]
	v_mfma_f32_16x16x32_bf16 v[92:95], v[156:159], v[236:239], v[92:95]
	v_mfma_f32_16x16x32_bf16 v[88:91], v[164:167], v[236:239], v[88:91]
	v_mfma_f32_16x16x32_bf16 v[84:87], v[156:159], v[244:247], v[84:87]
	v_mfma_f32_16x16x32_bf16 v[80:83], v[164:167], v[244:247], v[80:83]
	v_mfma_f32_16x16x32_bf16 v[124:127], v[160:163], v[224:227], v[124:127]
	v_mfma_f32_16x16x32_bf16 v[120:123], v[168:171], v[224:227], v[120:123]
	v_mfma_f32_16x16x32_bf16 v[116:119], v[160:163], v[232:235], v[116:119]
	v_mfma_f32_16x16x32_bf16 v[112:115], v[168:171], v[232:235], v[112:115]
	v_mfma_f32_16x16x32_bf16 v[92:95], v[160:163], v[240:243], v[92:95]
	v_mfma_f32_16x16x32_bf16 v[88:91], v[168:171], v[240:243], v[88:91]
	v_mfma_f32_16x16x32_bf16 v[84:87], v[160:163], v[248:251], v[84:87]
	v_mfma_f32_16x16x32_bf16 v[80:83], v[168:171], v[248:251], v[80:83]
	s_setprio 0
	s_setprio 1
	v_mfma_f32_16x16x32_bf16 v[108:111], v[172:175], v[220:223], v[108:111]
	v_mfma_f32_16x16x32_bf16 v[104:107], v[212:215], v[220:223], v[104:107]
	v_mfma_f32_16x16x32_bf16 v[100:103], v[172:175], v[228:231], v[100:103]
	v_mfma_f32_16x16x32_bf16 v[96:99], v[212:215], v[228:231], v[96:99]
	v_mfma_f32_16x16x32_bf16 v[76:79], v[172:175], v[236:239], v[76:79]
	v_mfma_f32_16x16x32_bf16 v[72:75], v[212:215], v[236:239], v[72:75]
	v_mfma_f32_16x16x32_bf16 v[68:71], v[172:175], v[244:247], v[68:71]
	v_mfma_f32_16x16x32_bf16 v[64:67], v[212:215], v[244:247], v[64:67]
	v_mfma_f32_16x16x32_bf16 v[108:111], v[176:179], v[224:227], v[108:111]
	v_mfma_f32_16x16x32_bf16 v[104:107], v[216:219], v[224:227], v[104:107]
	v_mfma_f32_16x16x32_bf16 v[100:103], v[176:179], v[232:235], v[100:103]
	v_mfma_f32_16x16x32_bf16 v[96:99], v[216:219], v[232:235], v[96:99]
	v_mfma_f32_16x16x32_bf16 v[76:79], v[176:179], v[240:243], v[76:79]
	v_mfma_f32_16x16x32_bf16 v[72:75], v[216:219], v[240:243], v[72:75]
	v_mfma_f32_16x16x32_bf16 v[68:71], v[176:179], v[248:251], v[68:71]
	v_mfma_f32_16x16x32_bf16 v[64:67], v[216:219], v[248:251], v[64:67]
	s_setprio 0
	s_barrier
	s_add_i32 s71, s61, s47
	v_lshl_add_u64 v[204:205], s[40:41], 0, v[128:129]
	s_mov_b32 m0, s71
	ds_read_b128 v[220:223], v199 offset:16384
	ds_read_b128 v[224:227], v199 offset:17408
	ds_read_b128 v[228:231], v199 offset:18432
	ds_read_b128 v[232:235], v199 offset:19456
	ds_read_b128 v[236:239], v199 offset:20480
	ds_read_b128 v[240:243], v199 offset:21504
	ds_read_b128 v[244:247], v199 offset:22528
	ds_read_b128 v[248:251], v199 offset:23552
	global_load_lds_dwordx4 v[204:205], off
	s_add_i32 m0, s71, 0x2000
	s_add_u32 s72, s40, 0x4000
	v_lshl_add_u64 v[204:205], s[40:41], 0, v[130:131]
	s_addc_u32 s73, s41, 0
	s_add_i32 s71, s62, s47
	global_load_lds_dwordx4 v[204:205], off
	v_lshl_add_u64 v[204:205], s[72:73], 0, v[128:129]
	s_mov_b32 m0, s71
	s_nop 0
	global_load_lds_dwordx4 v[204:205], off
	v_lshl_add_u64 v[204:205], s[72:73], 0, v[130:131]
	s_add_i32 m0, s71, 0x2000
	s_nop 0
	global_load_lds_dwordx4 v[204:205], off
	v_lshl_add_u64 v[204:205], s[42:43], 0, v[128:129]
	v_lshl_add_u64 v[204:205], s[42:43], 0, v[130:131]
	s_waitcnt vmcnt(6)
	s_waitcnt lgkmcnt(0)
	s_barrier
	s_setprio 1
	s_waitcnt lgkmcnt(0)
	v_mfma_f32_16x16x32_bf16 v[60:63], v[156:159], v[220:223], v[60:63]
	v_mfma_f32_16x16x32_bf16 v[56:59], v[164:167], v[220:223], v[56:59]
	v_mfma_f32_16x16x32_bf16 v[52:55], v[156:159], v[228:231], v[52:55]
	v_mfma_f32_16x16x32_bf16 v[48:51], v[164:167], v[228:231], v[48:51]
	v_mfma_f32_16x16x32_bf16 v[28:31], v[156:159], v[236:239], v[28:31]
	v_mfma_f32_16x16x32_bf16 v[24:27], v[164:167], v[236:239], v[24:27]
	v_mfma_f32_16x16x32_bf16 v[20:23], v[156:159], v[244:247], v[20:23]
	v_mfma_f32_16x16x32_bf16 v[12:15], v[164:167], v[244:247], v[12:15]
	v_mfma_f32_16x16x32_bf16 v[60:63], v[160:163], v[224:227], v[60:63]
	v_mfma_f32_16x16x32_bf16 v[56:59], v[168:171], v[224:227], v[56:59]
	v_mfma_f32_16x16x32_bf16 v[52:55], v[160:163], v[232:235], v[52:55]
	v_mfma_f32_16x16x32_bf16 v[48:51], v[168:171], v[232:235], v[48:51]
	v_mfma_f32_16x16x32_bf16 v[28:31], v[160:163], v[240:243], v[28:31]
	v_mfma_f32_16x16x32_bf16 v[24:27], v[168:171], v[240:243], v[24:27]
	v_mfma_f32_16x16x32_bf16 v[20:23], v[160:163], v[248:251], v[20:23]
	v_mfma_f32_16x16x32_bf16 v[12:15], v[168:171], v[248:251], v[12:15]
	s_setprio 0
	s_setprio 1
	v_mfma_f32_16x16x32_bf16 v[44:47], v[172:175], v[220:223], v[44:47]
	v_mfma_f32_16x16x32_bf16 v[40:43], v[212:215], v[220:223], v[40:43]
	v_mfma_f32_16x16x32_bf16 v[36:39], v[172:175], v[228:231], v[36:39]
	v_mfma_f32_16x16x32_bf16 v[32:35], v[212:215], v[228:231], v[32:35]
	v_mfma_f32_16x16x32_bf16 v[16:19], v[172:175], v[236:239], v[16:19]
	v_mfma_f32_16x16x32_bf16 v[8:11], v[212:215], v[236:239], v[8:11]
	v_mfma_f32_16x16x32_bf16 v[4:7], v[172:175], v[244:247], v[4:7]
	v_mfma_f32_16x16x32_bf16 v[0:3], v[212:215], v[244:247], v[0:3]
	v_mfma_f32_16x16x32_bf16 v[44:47], v[176:179], v[224:227], v[44:47]
	v_mfma_f32_16x16x32_bf16 v[40:43], v[216:219], v[224:227], v[40:43]
	v_mfma_f32_16x16x32_bf16 v[36:39], v[176:179], v[232:235], v[36:39]
	v_mfma_f32_16x16x32_bf16 v[32:35], v[216:219], v[232:235], v[32:35]
	v_mfma_f32_16x16x32_bf16 v[16:19], v[176:179], v[240:243], v[16:19]
	v_mfma_f32_16x16x32_bf16 v[8:11], v[216:219], v[240:243], v[8:11]
	v_mfma_f32_16x16x32_bf16 v[4:7], v[176:179], v[248:251], v[4:7]
	v_mfma_f32_16x16x32_bf16 v[0:3], v[216:219], v[248:251], v[0:3]
	s_setprio 0
	s_barrier
	s_mov_b32 m0, s48
	s_nop 0
	global_load_lds_dwordx4 v128, s[42:43]
	s_mov_b32 m0, s49
	s_nop 0
	global_load_lds_dwordx4 v130, s[42:43]
	s_add_i32 s71, 0, 0x18000
	s_add_i32 s72, 0, 0x1c000
	v_add_u32_e32 v168, s71, v182
	v_add_u32_e32 v204, s72, v182
	ds_read_b128 v[156:159], v168
	ds_read_b128 v[160:163], v168 offset:1024
	ds_read_b128 v[164:167], v168 offset:2048
	ds_read_b128 v[168:171], v168 offset:3072
	ds_read_b128 v[172:175], v204
	ds_read_b128 v[176:179], v204 offset:1024
	ds_read_b128 v[212:215], v204 offset:2048
	ds_read_b128 v[216:219], v204 offset:3072
	s_add_u32 s42, s42, 0x4000
	s_addc_u32 s43, s43, 0
	s_mov_b32 m0, s50
	v_lshl_add_u64 v[204:205], s[42:43], 0, v[128:129]
	ds_read_b128 v[220:223], v199 offset:32768
	ds_read_b128 v[224:227], v199 offset:33792
	ds_read_b128 v[228:231], v199 offset:34816
	ds_read_b128 v[232:235], v199 offset:35840
	ds_read_b128 v[236:239], v199 offset:36864
	ds_read_b128 v[240:243], v199 offset:37888
	ds_read_b128 v[244:247], v199 offset:38912
	ds_read_b128 v[248:251], v199 offset:39936
	global_load_lds_dwordx4 v[204:205], off
	v_lshl_add_u64 v[204:205], s[42:43], 0, v[130:131]
	s_mov_b32 m0, s51
	s_nop 0
	global_load_lds_dwordx4 v[204:205], off
	s_waitcnt vmcnt(8)
	s_waitcnt lgkmcnt(0)
	s_barrier
	s_setprio 1
	s_waitcnt lgkmcnt(0)
	v_mfma_f32_16x16x32_bf16 v[124:127], v[156:159], v[220:223], v[124:127]
	v_mfma_f32_16x16x32_bf16 v[120:123], v[164:167], v[220:223], v[120:123]
	v_mfma_f32_16x16x32_bf16 v[116:119], v[156:159], v[228:231], v[116:119]
	v_mfma_f32_16x16x32_bf16 v[112:115], v[164:167], v[228:231], v[112:115]
	v_mfma_f32_16x16x32_bf16 v[92:95], v[156:159], v[236:239], v[92:95]
	v_mfma_f32_16x16x32_bf16 v[88:91], v[164:167], v[236:239], v[88:91]
	v_mfma_f32_16x16x32_bf16 v[84:87], v[156:159], v[244:247], v[84:87]
	v_mfma_f32_16x16x32_bf16 v[80:83], v[164:167], v[244:247], v[80:83]
	v_mfma_f32_16x16x32_bf16 v[124:127], v[160:163], v[224:227], v[124:127]
	v_mfma_f32_16x16x32_bf16 v[120:123], v[168:171], v[224:227], v[120:123]
	v_mfma_f32_16x16x32_bf16 v[116:119], v[160:163], v[232:235], v[116:119]
	v_mfma_f32_16x16x32_bf16 v[112:115], v[168:171], v[232:235], v[112:115]
	v_mfma_f32_16x16x32_bf16 v[92:95], v[160:163], v[240:243], v[92:95]
	v_mfma_f32_16x16x32_bf16 v[88:91], v[168:171], v[240:243], v[88:91]
	v_mfma_f32_16x16x32_bf16 v[84:87], v[160:163], v[248:251], v[84:87]
	v_mfma_f32_16x16x32_bf16 v[80:83], v[168:171], v[248:251], v[80:83]
	s_setprio 0
	s_setprio 1
	v_mfma_f32_16x16x32_bf16 v[108:111], v[172:175], v[220:223], v[108:111]
	v_mfma_f32_16x16x32_bf16 v[104:107], v[212:215], v[220:223], v[104:107]
	v_mfma_f32_16x16x32_bf16 v[100:103], v[172:175], v[228:231], v[100:103]
	v_mfma_f32_16x16x32_bf16 v[96:99], v[212:215], v[228:231], v[96:99]
	v_mfma_f32_16x16x32_bf16 v[76:79], v[172:175], v[236:239], v[76:79]
	v_mfma_f32_16x16x32_bf16 v[72:75], v[212:215], v[236:239], v[72:75]
	v_mfma_f32_16x16x32_bf16 v[68:71], v[172:175], v[244:247], v[68:71]
	v_mfma_f32_16x16x32_bf16 v[64:67], v[212:215], v[244:247], v[64:67]
	v_mfma_f32_16x16x32_bf16 v[108:111], v[176:179], v[224:227], v[108:111]
	v_mfma_f32_16x16x32_bf16 v[104:107], v[216:219], v[224:227], v[104:107]
	v_mfma_f32_16x16x32_bf16 v[100:103], v[176:179], v[232:235], v[100:103]
	v_mfma_f32_16x16x32_bf16 v[96:99], v[216:219], v[232:235], v[96:99]
	v_mfma_f32_16x16x32_bf16 v[76:79], v[176:179], v[240:243], v[76:79]
	v_mfma_f32_16x16x32_bf16 v[72:75], v[216:219], v[240:243], v[72:75]
	v_mfma_f32_16x16x32_bf16 v[68:71], v[176:179], v[248:251], v[68:71]
	v_mfma_f32_16x16x32_bf16 v[64:67], v[216:219], v[248:251], v[64:67]
	s_setprio 0
	s_barrier
	s_add_u32 s42, s40, 0x8000
	s_addc_u32 s43, s41, 0
	s_add_i32 s71, s71, s47
	v_lshl_add_u64 v[204:205], s[42:43], 0, v[128:129]
	s_mov_b32 m0, s71
	ds_read_b128 v[220:223], v199 offset:49152
	ds_read_b128 v[224:227], v199 offset:50176
	ds_read_b128 v[228:231], v199 offset:51200
	ds_read_b128 v[232:235], v199 offset:52224
	ds_read_b128 v[236:239], v199 offset:53248
	ds_read_b128 v[240:243], v199 offset:54272
	ds_read_b128 v[244:247], v199 offset:55296
	ds_read_b128 v[248:251], v199 offset:56320
	global_load_lds_dwordx4 v[204:205], off
	s_add_i32 m0, s71, 0x2000
	s_add_u32 s40, s40, 0xc000
	v_lshl_add_u64 v[204:205], s[42:43], 0, v[130:131]
	s_addc_u32 s41, s41, 0
	s_add_i32 s42, s72, s47
	global_load_lds_dwordx4 v[204:205], off
	v_lshl_add_u64 v[204:205], s[40:41], 0, v[128:129]
	s_mov_b32 m0, s42
	s_nop 0
	global_load_lds_dwordx4 v[204:205], off
	v_lshl_add_u64 v[204:205], s[40:41], 0, v[130:131]
	s_add_i32 m0, s42, 0x2000
	s_nop 0
	global_load_lds_dwordx4 v[204:205], off
	v_lshl_add_u64 v[204:205], s[38:39], 0, v[128:129]
	s_mov_b32 m0, s57
	s_nop 0
	global_load_lds_dwordx4 v[204:205], off
	v_lshl_add_u64 v[204:205], s[38:39], 0, v[130:131]
	s_mov_b32 m0, s58
	s_nop 0
	global_load_lds_dwordx4 v[204:205], off
	s_waitcnt vmcnt(8)
	s_waitcnt lgkmcnt(0)
	s_barrier
	s_setprio 1
	s_waitcnt lgkmcnt(0)
	v_mfma_f32_16x16x32_bf16 v[60:63], v[156:159], v[220:223], v[60:63]
	v_mfma_f32_16x16x32_bf16 v[56:59], v[164:167], v[220:223], v[56:59]
	v_mfma_f32_16x16x32_bf16 v[52:55], v[156:159], v[228:231], v[52:55]
	v_mfma_f32_16x16x32_bf16 v[48:51], v[164:167], v[228:231], v[48:51]
	v_mfma_f32_16x16x32_bf16 v[28:31], v[156:159], v[236:239], v[28:31]
	v_mfma_f32_16x16x32_bf16 v[24:27], v[164:167], v[236:239], v[24:27]
	v_mfma_f32_16x16x32_bf16 v[20:23], v[156:159], v[244:247], v[20:23]
	v_mfma_f32_16x16x32_bf16 v[12:15], v[164:167], v[244:247], v[12:15]
	v_mfma_f32_16x16x32_bf16 v[60:63], v[160:163], v[224:227], v[60:63]
	v_mfma_f32_16x16x32_bf16 v[56:59], v[168:171], v[224:227], v[56:59]
	v_mfma_f32_16x16x32_bf16 v[52:55], v[160:163], v[232:235], v[52:55]
	v_mfma_f32_16x16x32_bf16 v[48:51], v[168:171], v[232:235], v[48:51]
	v_mfma_f32_16x16x32_bf16 v[28:31], v[160:163], v[240:243], v[28:31]
	v_mfma_f32_16x16x32_bf16 v[24:27], v[168:171], v[240:243], v[24:27]
	v_mfma_f32_16x16x32_bf16 v[20:23], v[160:163], v[248:251], v[20:23]
	v_mfma_f32_16x16x32_bf16 v[12:15], v[168:171], v[248:251], v[12:15]
	s_setprio 0
	s_setprio 1
	v_mfma_f32_16x16x32_bf16 v[44:47], v[172:175], v[220:223], v[44:47]
	v_mfma_f32_16x16x32_bf16 v[40:43], v[212:215], v[220:223], v[40:43]
	v_mfma_f32_16x16x32_bf16 v[36:39], v[172:175], v[228:231], v[36:39]
	v_mfma_f32_16x16x32_bf16 v[32:35], v[212:215], v[228:231], v[32:35]
	v_mfma_f32_16x16x32_bf16 v[16:19], v[172:175], v[236:239], v[16:19]
	v_mfma_f32_16x16x32_bf16 v[8:11], v[212:215], v[236:239], v[8:11]
	v_mfma_f32_16x16x32_bf16 v[4:7], v[172:175], v[244:247], v[4:7]
	v_mfma_f32_16x16x32_bf16 v[0:3], v[212:215], v[244:247], v[0:3]
	v_mfma_f32_16x16x32_bf16 v[44:47], v[176:179], v[224:227], v[44:47]
	v_mfma_f32_16x16x32_bf16 v[40:43], v[216:219], v[224:227], v[40:43]
	v_mfma_f32_16x16x32_bf16 v[36:39], v[176:179], v[232:235], v[36:39]
	v_mfma_f32_16x16x32_bf16 v[32:35], v[216:219], v[232:235], v[32:35]
	v_mfma_f32_16x16x32_bf16 v[16:19], v[176:179], v[240:243], v[16:19]
	v_mfma_f32_16x16x32_bf16 v[8:11], v[216:219], v[240:243], v[8:11]
	v_mfma_f32_16x16x32_bf16 v[4:7], v[176:179], v[248:251], v[4:7]
	v_mfma_f32_16x16x32_bf16 v[0:3], v[216:219], v[248:251], v[0:3]
	s_setprio 0
	s_barrier
	s_add_i32 s70, s70, 2
	s_add_u32 s68, s68, 0x10000
	s_addc_u32 s69, s69, 0
	s_add_u32 s36, s36, 0x10000
	s_addc_u32 s37, s37, 0
	s_cmp_gt_u32 s70, 41
	s_cbranch_scc0 .LBB0_1481
	s_and_b64 vcc, exec, s[18:19]
	s_cbranch_vccz .LBB0_1484
	s_barrier

.LBB0_1563:
	ds_read_b128 v[168:171], v165
	ds_read_b128 v[172:175], v165 offset:1024
	ds_read_b128 v[176:179], v165 offset:2048
	ds_read_b128 v[180:183], v165 offset:3072
	ds_read_b128 v[184:187], v166
	ds_read_b128 v[188:191], v166 offset:1024
	ds_read_b128 v[192:195], v166 offset:2048
	ds_read_b128 v[196:199], v166 offset:3072
	s_add_u32 s22, s20, 0xfffc0080
	s_addc_u32 s23, s21, -1
	s_cmp_eq_u32 s49, 12
	s_cselect_b32 s25, s9, s23
	s_cselect_b32 s24, s45, s22
	s_cselect_b32 s23, s11, s48
	s_cselect_b32 s22, s46, s47
	v_lshl_add_u64 v[162:163], s[20:21], 0, v[156:157]
	s_add_i32 m0, s17, 0xc000
	ds_read_b128 v[210:213], v167
	ds_read_b128 v[214:217], v167 offset:1024
	ds_read_b128 v[218:221], v167 offset:2048
	ds_read_b128 v[222:225], v167 offset:3072
	ds_read_b128 v[226:229], v167 offset:4096
	ds_read_b128 v[230:233], v167 offset:5120
	ds_read_b128 v[234:237], v167 offset:6144
	ds_read_b128 v[238:241], v167 offset:7168
	global_load_lds_dwordx4 v[162:163], off
	v_lshl_add_u64 v[162:163], s[20:21], 0, v[154:155]
	s_add_i32 m0, s17, 0xe000
	s_nop 0
	global_load_lds_dwordx4 v[162:163], off
	s_waitcnt vmcnt(8)
	s_waitcnt lgkmcnt(0)
	s_barrier
	s_setprio 1
	s_waitcnt lgkmcnt(0)
	v_mfma_f32_16x16x32_bf16 v[124:127], v[168:171], v[210:213], v[124:127]
	v_mfma_f32_16x16x32_bf16 v[116:119], v[176:179], v[210:213], v[116:119]
	v_mfma_f32_16x16x32_bf16 v[108:111], v[168:171], v[218:221], v[108:111]
	v_mfma_f32_16x16x32_bf16 v[100:103], v[176:179], v[218:221], v[100:103]
	v_mfma_f32_16x16x32_bf16 v[92:95], v[168:171], v[226:229], v[92:95]
	v_mfma_f32_16x16x32_bf16 v[84:87], v[176:179], v[226:229], v[84:87]
	v_mfma_f32_16x16x32_bf16 v[76:79], v[168:171], v[234:237], v[76:79]
	v_mfma_f32_16x16x32_bf16 v[68:71], v[176:179], v[234:237], v[68:71]
	v_mfma_f32_16x16x32_bf16 v[124:127], v[172:175], v[214:217], v[124:127]
	v_mfma_f32_16x16x32_bf16 v[116:119], v[180:183], v[214:217], v[116:119]
	v_mfma_f32_16x16x32_bf16 v[108:111], v[172:175], v[222:225], v[108:111]
	v_mfma_f32_16x16x32_bf16 v[100:103], v[180:183], v[222:225], v[100:103]
	v_mfma_f32_16x16x32_bf16 v[92:95], v[172:175], v[230:233], v[92:95]
	v_mfma_f32_16x16x32_bf16 v[84:87], v[180:183], v[230:233], v[84:87]
	v_mfma_f32_16x16x32_bf16 v[76:79], v[172:175], v[238:241], v[76:79]
	v_mfma_f32_16x16x32_bf16 v[68:71], v[180:183], v[238:241], v[68:71]
	s_setprio 0
	s_setprio 1
	v_mfma_f32_16x16x32_bf16 v[120:123], v[184:187], v[210:213], v[120:123]
	v_mfma_f32_16x16x32_bf16 v[112:115], v[192:195], v[210:213], v[112:115]
	v_mfma_f32_16x16x32_bf16 v[104:107], v[184:187], v[218:221], v[104:107]
	v_mfma_f32_16x16x32_bf16 v[96:99], v[192:195], v[218:221], v[96:99]
	v_mfma_f32_16x16x32_bf16 v[88:91], v[184:187], v[226:229], v[88:91]
	v_mfma_f32_16x16x32_bf16 v[80:83], v[192:195], v[226:229], v[80:83]
	v_mfma_f32_16x16x32_bf16 v[72:75], v[184:187], v[234:237], v[72:75]
	v_mfma_f32_16x16x32_bf16 v[64:67], v[192:195], v[234:237], v[64:67]
	v_mfma_f32_16x16x32_bf16 v[120:123], v[188:191], v[214:217], v[120:123]
	v_mfma_f32_16x16x32_bf16 v[112:115], v[196:199], v[214:217], v[112:115]
	v_mfma_f32_16x16x32_bf16 v[104:107], v[188:191], v[222:225], v[104:107]
	v_mfma_f32_16x16x32_bf16 v[96:99], v[196:199], v[222:225], v[96:99]
	v_mfma_f32_16x16x32_bf16 v[88:91], v[188:191], v[230:233], v[88:91]
	v_mfma_f32_16x16x32_bf16 v[80:83], v[196:199], v[230:233], v[80:83]
	v_mfma_f32_16x16x32_bf16 v[72:75], v[188:191], v[238:241], v[72:75]
	v_mfma_f32_16x16x32_bf16 v[64:67], v[196:199], v[238:241], v[64:67]
	s_setprio 0
	s_barrier
	s_add_i32 s50, s43, s33
	v_lshl_add_u64 v[162:163], s[22:23], 0, v[132:133]
	s_mov_b32 m0, s50
	ds_read_b128 v[210:213], v167 offset:16384
	ds_read_b128 v[214:217], v167 offset:17408
	ds_read_b128 v[218:221], v167 offset:18432
	ds_read_b128 v[222:225], v167 offset:19456
	ds_read_b128 v[226:229], v167 offset:20480
	ds_read_b128 v[230:233], v167 offset:21504
	ds_read_b128 v[234:237], v167 offset:22528
	ds_read_b128 v[238:241], v167 offset:23552
	global_load_lds_dwordx4 v[162:163], off
	s_add_i32 m0, s50, 0x2000
	s_add_u32 s50, s22, 0x4000
	v_lshl_add_u64 v[162:163], s[22:23], 0, v[128:129]
	s_addc_u32 s51, s23, 0
	s_add_i32 s52, s44, s33
	global_load_lds_dwordx4 v[162:163], off
	v_lshl_add_u64 v[162:163], s[50:51], 0, v[132:133]
	s_mov_b32 m0, s52
	v_lshl_add_u64 v[200:201], s[24:25], 0, v[130:131]
	global_load_lds_dwordx4 v[162:163], off
	v_lshl_add_u64 v[162:163], s[50:51], 0, v[128:129]
	s_add_i32 m0, s52, 0x2000
	s_nop 0
	global_load_lds_dwordx4 v[162:163], off
	v_lshl_add_u64 v[162:163], s[24:25], 0, v[134:135]
	s_waitcnt vmcnt(6)
	s_waitcnt lgkmcnt(0)
	s_barrier
	s_setprio 1
	s_waitcnt lgkmcnt(0)
	v_mfma_f32_16x16x32_bf16 v[60:63], v[168:171], v[210:213], v[60:63]
	v_mfma_f32_16x16x32_bf16 v[52:55], v[176:179], v[210:213], v[52:55]
	v_mfma_f32_16x16x32_bf16 v[44:47], v[168:171], v[218:221], v[44:47]
	v_mfma_f32_16x16x32_bf16 v[36:39], v[176:179], v[218:221], v[36:39]
	v_mfma_f32_16x16x32_bf16 v[28:31], v[168:171], v[226:229], v[28:31]
	v_mfma_f32_16x16x32_bf16 v[20:23], v[176:179], v[226:229], v[20:23]
	v_mfma_f32_16x16x32_bf16 v[12:15], v[168:171], v[234:237], v[12:15]
	v_mfma_f32_16x16x32_bf16 v[4:7], v[176:179], v[234:237], v[4:7]
	v_mfma_f32_16x16x32_bf16 v[60:63], v[172:175], v[214:217], v[60:63]
	v_mfma_f32_16x16x32_bf16 v[52:55], v[180:183], v[214:217], v[52:55]
	v_mfma_f32_16x16x32_bf16 v[44:47], v[172:175], v[222:225], v[44:47]
	v_mfma_f32_16x16x32_bf16 v[36:39], v[180:183], v[222:225], v[36:39]
	v_mfma_f32_16x16x32_bf16 v[28:31], v[172:175], v[230:233], v[28:31]
	v_mfma_f32_16x16x32_bf16 v[20:23], v[180:183], v[230:233], v[20:23]
	v_mfma_f32_16x16x32_bf16 v[12:15], v[172:175], v[238:241], v[12:15]
	v_mfma_f32_16x16x32_bf16 v[4:7], v[180:183], v[238:241], v[4:7]
	s_setprio 0
	s_setprio 1
	v_mfma_f32_16x16x32_bf16 v[56:59], v[184:187], v[210:213], v[56:59]
	v_mfma_f32_16x16x32_bf16 v[48:51], v[192:195], v[210:213], v[48:51]
	v_mfma_f32_16x16x32_bf16 v[40:43], v[184:187], v[218:221], v[40:43]
	v_mfma_f32_16x16x32_bf16 v[32:35], v[192:195], v[218:221], v[32:35]
	v_mfma_f32_16x16x32_bf16 v[24:27], v[184:187], v[226:229], v[24:27]
	v_mfma_f32_16x16x32_bf16 v[16:19], v[192:195], v[226:229], v[16:19]
	v_mfma_f32_16x16x32_bf16 v[8:11], v[184:187], v[234:237], v[8:11]
	v_mfma_f32_16x16x32_bf16 v[0:3], v[192:195], v[234:237], v[0:3]
	v_mfma_f32_16x16x32_bf16 v[56:59], v[188:191], v[214:217], v[56:59]
	v_mfma_f32_16x16x32_bf16 v[48:51], v[196:199], v[214:217], v[48:51]
	v_mfma_f32_16x16x32_bf16 v[40:43], v[188:191], v[222:225], v[40:43]
	v_mfma_f32_16x16x32_bf16 v[32:35], v[196:199], v[222:225], v[32:35]
	v_mfma_f32_16x16x32_bf16 v[24:27], v[188:191], v[230:233], v[24:27]
	v_mfma_f32_16x16x32_bf16 v[16:19], v[196:199], v[230:233], v[16:19]
	v_mfma_f32_16x16x32_bf16 v[8:11], v[188:191], v[238:241], v[8:11]
	v_mfma_f32_16x16x32_bf16 v[0:3], v[196:199], v[238:241], v[0:3]
	s_setprio 0
	s_barrier
	s_mov_b32 m0, s17
	s_nop 0
	global_load_lds_dwordx4 v134, s[24:25]
	s_mov_b32 m0, s19
	s_nop 0
	global_load_lds_dwordx4 v130, s[24:25]
	s_add_i32 s50, 0, 0x18000
	s_add_i32 s51, 0, 0x1c000
	v_add_u32_e32 v180, s50, v164
	v_add_u32_e32 v196, s51, v164
	ds_read_b128 v[168:171], v180
	ds_read_b128 v[172:175], v180 offset:1024
	ds_read_b128 v[176:179], v180 offset:2048
	ds_read_b128 v[180:183], v180 offset:3072
	ds_read_b128 v[184:187], v196
	ds_read_b128 v[188:191], v196 offset:1024
	ds_read_b128 v[192:195], v196 offset:2048
	ds_read_b128 v[196:199], v196 offset:3072
	s_add_u32 s24, s24, 0x40000
	s_addc_u32 s25, s25, 0
	s_mov_b32 m0, s36
	v_lshl_add_u64 v[204:205], s[24:25], 0, v[134:135]
	ds_read_b128 v[210:213], v167 offset:32768
	ds_read_b128 v[214:217], v167 offset:33792
	ds_read_b128 v[218:221], v167 offset:34816
	ds_read_b128 v[222:225], v167 offset:35840
	ds_read_b128 v[226:229], v167 offset:36864
	ds_read_b128 v[230:233], v167 offset:37888
	ds_read_b128 v[234:237], v167 offset:38912
	ds_read_b128 v[238:241], v167 offset:39936
	global_load_lds_dwordx4 v[204:205], off
	v_lshl_add_u64 v[204:205], s[24:25], 0, v[130:131]
	s_mov_b32 m0, s37
	s_nop 0
	global_load_lds_dwordx4 v[204:205], off
	s_waitcnt vmcnt(8)
	s_waitcnt lgkmcnt(0)
	s_barrier
	s_setprio 1
	s_waitcnt lgkmcnt(0)
	v_mfma_f32_16x16x32_bf16 v[124:127], v[168:171], v[210:213], v[124:127]
	v_mfma_f32_16x16x32_bf16 v[116:119], v[176:179], v[210:213], v[116:119]
	v_mfma_f32_16x16x32_bf16 v[108:111], v[168:171], v[218:221], v[108:111]
	v_mfma_f32_16x16x32_bf16 v[100:103], v[176:179], v[218:221], v[100:103]
	v_mfma_f32_16x16x32_bf16 v[92:95], v[168:171], v[226:229], v[92:95]
	v_mfma_f32_16x16x32_bf16 v[84:87], v[176:179], v[226:229], v[84:87]
	v_mfma_f32_16x16x32_bf16 v[76:79], v[168:171], v[234:237], v[76:79]
	v_mfma_f32_16x16x32_bf16 v[68:71], v[176:179], v[234:237], v[68:71]
	v_mfma_f32_16x16x32_bf16 v[124:127], v[172:175], v[214:217], v[124:127]
	v_mfma_f32_16x16x32_bf16 v[116:119], v[180:183], v[214:217], v[116:119]
	v_mfma_f32_16x16x32_bf16 v[108:111], v[172:175], v[222:225], v[108:111]
	v_mfma_f32_16x16x32_bf16 v[100:103], v[180:183], v[222:225], v[100:103]
	v_mfma_f32_16x16x32_bf16 v[92:95], v[172:175], v[230:233], v[92:95]
	v_mfma_f32_16x16x32_bf16 v[84:87], v[180:183], v[230:233], v[84:87]
	v_mfma_f32_16x16x32_bf16 v[76:79], v[172:175], v[238:241], v[76:79]
	v_mfma_f32_16x16x32_bf16 v[68:71], v[180:183], v[238:241], v[68:71]
	s_setprio 0
	s_setprio 1
	v_mfma_f32_16x16x32_bf16 v[120:123], v[184:187], v[210:213], v[120:123]
	v_mfma_f32_16x16x32_bf16 v[112:115], v[192:195], v[210:213], v[112:115]
	v_mfma_f32_16x16x32_bf16 v[104:107], v[184:187], v[218:221], v[104:107]
	v_mfma_f32_16x16x32_bf16 v[96:99], v[192:195], v[218:221], v[96:99]
	v_mfma_f32_16x16x32_bf16 v[88:91], v[184:187], v[226:229], v[88:91]
	v_mfma_f32_16x16x32_bf16 v[80:83], v[192:195], v[226:229], v[80:83]
	v_mfma_f32_16x16x32_bf16 v[72:75], v[184:187], v[234:237], v[72:75]
	v_mfma_f32_16x16x32_bf16 v[64:67], v[192:195], v[234:237], v[64:67]
	v_mfma_f32_16x16x32_bf16 v[120:123], v[188:191], v[214:217], v[120:123]
	v_mfma_f32_16x16x32_bf16 v[112:115], v[196:199], v[214:217], v[112:115]
	v_mfma_f32_16x16x32_bf16 v[104:107], v[188:191], v[222:225], v[104:107]
	v_mfma_f32_16x16x32_bf16 v[96:99], v[196:199], v[222:225], v[96:99]
	v_mfma_f32_16x16x32_bf16 v[88:91], v[188:191], v[230:233], v[88:91]
	v_mfma_f32_16x16x32_bf16 v[80:83], v[196:199], v[230:233], v[80:83]
	v_mfma_f32_16x16x32_bf16 v[72:75], v[188:191], v[238:241], v[72:75]
	v_mfma_f32_16x16x32_bf16 v[64:67], v[196:199], v[238:241], v[64:67]
	s_setprio 0
	s_barrier
	s_add_u32 s24, s22, 0x8000
	s_addc_u32 s25, s23, 0
	s_add_i32 s50, s50, s33
	v_lshl_add_u64 v[204:205], s[24:25], 0, v[132:133]
	s_mov_b32 m0, s50
	ds_read_b128 v[210:213], v167 offset:49152
	ds_read_b128 v[214:217], v167 offset:50176
	ds_read_b128 v[218:221], v167 offset:51200
	ds_read_b128 v[222:225], v167 offset:52224
	ds_read_b128 v[226:229], v167 offset:53248
	ds_read_b128 v[230:233], v167 offset:54272
	ds_read_b128 v[234:237], v167 offset:55296
	ds_read_b128 v[238:241], v167 offset:56320
	global_load_lds_dwordx4 v[204:205], off
	s_add_i32 m0, s50, 0x2000
	s_add_u32 s22, s22, 0xc000
	v_lshl_add_u64 v[204:205], s[24:25], 0, v[128:129]
	s_addc_u32 s23, s23, 0
	s_add_i32 s24, s51, s33
	global_load_lds_dwordx4 v[204:205], off
	v_lshl_add_u64 v[204:205], s[22:23], 0, v[132:133]
	s_mov_b32 m0, s24
	v_lshl_add_u64 v[162:163], v[162:163], 0, s[4:5]
	global_load_lds_dwordx4 v[204:205], off
	v_lshl_add_u64 v[204:205], s[22:23], 0, v[128:129]
	s_add_i32 m0, s24, 0x2000
	s_nop 0
	global_load_lds_dwordx4 v[204:205], off
	s_mov_b32 m0, s40
	s_nop 0
	global_load_lds_dwordx4 v[162:163], off
	v_lshl_add_u64 v[162:163], v[200:201], 0, s[4:5]
	s_mov_b32 m0, s41
	s_nop 0
	global_load_lds_dwordx4 v[162:163], off
	s_waitcnt vmcnt(8)
	s_waitcnt lgkmcnt(0)
	s_barrier
	s_setprio 1
	s_waitcnt lgkmcnt(0)
	v_mfma_f32_16x16x32_bf16 v[60:63], v[168:171], v[210:213], v[60:63]
	v_mfma_f32_16x16x32_bf16 v[52:55], v[176:179], v[210:213], v[52:55]
	v_mfma_f32_16x16x32_bf16 v[44:47], v[168:171], v[218:221], v[44:47]
	v_mfma_f32_16x16x32_bf16 v[36:39], v[176:179], v[218:221], v[36:39]
	v_mfma_f32_16x16x32_bf16 v[28:31], v[168:171], v[226:229], v[28:31]
	v_mfma_f32_16x16x32_bf16 v[20:23], v[176:179], v[226:229], v[20:23]
	v_mfma_f32_16x16x32_bf16 v[12:15], v[168:171], v[234:237], v[12:15]
	v_mfma_f32_16x16x32_bf16 v[4:7], v[176:179], v[234:237], v[4:7]
	v_mfma_f32_16x16x32_bf16 v[60:63], v[172:175], v[214:217], v[60:63]
	v_mfma_f32_16x16x32_bf16 v[52:55], v[180:183], v[214:217], v[52:55]
	v_mfma_f32_16x16x32_bf16 v[44:47], v[172:175], v[222:225], v[44:47]
	v_mfma_f32_16x16x32_bf16 v[36:39], v[180:183], v[222:225], v[36:39]
	v_mfma_f32_16x16x32_bf16 v[28:31], v[172:175], v[230:233], v[28:31]
	v_mfma_f32_16x16x32_bf16 v[20:23], v[180:183], v[230:233], v[20:23]
	v_mfma_f32_16x16x32_bf16 v[12:15], v[172:175], v[238:241], v[12:15]
	v_mfma_f32_16x16x32_bf16 v[4:7], v[180:183], v[238:241], v[4:7]
	s_setprio 0
	s_setprio 1
	v_mfma_f32_16x16x32_bf16 v[56:59], v[184:187], v[210:213], v[56:59]
	v_mfma_f32_16x16x32_bf16 v[48:51], v[192:195], v[210:213], v[48:51]
	v_mfma_f32_16x16x32_bf16 v[40:43], v[184:187], v[218:221], v[40:43]
	v_mfma_f32_16x16x32_bf16 v[32:35], v[192:195], v[218:221], v[32:35]
	v_mfma_f32_16x16x32_bf16 v[24:27], v[184:187], v[226:229], v[24:27]
	v_mfma_f32_16x16x32_bf16 v[16:19], v[192:195], v[226:229], v[16:19]
	v_mfma_f32_16x16x32_bf16 v[8:11], v[184:187], v[234:237], v[8:11]
	v_mfma_f32_16x16x32_bf16 v[0:3], v[192:195], v[234:237], v[0:3]
	v_mfma_f32_16x16x32_bf16 v[56:59], v[188:191], v[214:217], v[56:59]
	v_mfma_f32_16x16x32_bf16 v[48:51], v[196:199], v[214:217], v[48:51]
	v_mfma_f32_16x16x32_bf16 v[40:43], v[188:191], v[222:225], v[40:43]
	v_mfma_f32_16x16x32_bf16 v[32:35], v[196:199], v[222:225], v[32:35]
	v_mfma_f32_16x16x32_bf16 v[24:27], v[188:191], v[230:233], v[24:27]
	v_mfma_f32_16x16x32_bf16 v[16:19], v[196:199], v[230:233], v[16:19]
	v_mfma_f32_16x16x32_bf16 v[8:11], v[188:191], v[238:241], v[8:11]
	v_mfma_f32_16x16x32_bf16 v[0:3], v[196:199], v[238:241], v[0:3]
	s_setprio 0
	s_barrier
	s_add_i32 s49, s49, 2
	s_add_u32 s47, s47, 0x10000
	s_addc_u32 s48, s48, 0
	s_add_u32 s20, s20, 0x100
	s_addc_u32 s21, s21, 0
	s_cmp_gt_u32 s49, 13
	s_cbranch_scc0 .LBB0_1563
	s_and_b64 vcc, exec, s[6:7]
	s_cbranch_vccz .LBB0_1566
	s_barrier

.LBB0_1645:
	v_add_u32_e32 v168, s69, v182
	v_add_u32_e32 v204, s70, v182
	ds_read_b128 v[156:159], v168
	ds_read_b128 v[160:163], v168 offset:1024
	ds_read_b128 v[164:167], v168 offset:2048
	ds_read_b128 v[168:171], v168 offset:3072
	ds_read_b128 v[172:175], v204
	ds_read_b128 v[176:179], v204 offset:1024
	ds_read_b128 v[212:215], v204 offset:2048
	ds_read_b128 v[216:219], v204 offset:3072
	s_add_u32 s38, s36, 0x4000
	s_addc_u32 s39, s37, 0
	s_cmp_eq_u32 s47, 40
	s_cselect_b32 s42, s0, s38
	s_cselect_b32 s43, s1, s39
	s_cselect_b32 s40, s34, s45
	s_cselect_b32 s41, s35, s46
	s_add_u32 s38, s42, 0x8000
	s_addc_u32 s39, s43, 0
	v_lshl_add_u64 v[204:205], s[36:37], 0, v[150:151]
	s_add_i32 m0, s56, 0xc000
	ds_read_b128 v[220:223], v199
	ds_read_b128 v[224:227], v199 offset:1024
	ds_read_b128 v[228:231], v199 offset:2048
	ds_read_b128 v[232:235], v199 offset:3072
	ds_read_b128 v[236:239], v199 offset:4096
	ds_read_b128 v[240:243], v199 offset:5120
	ds_read_b128 v[244:247], v199 offset:6144
	ds_read_b128 v[248:251], v199 offset:7168
	global_load_lds_dwordx4 v[204:205], off
	v_lshl_add_u64 v[204:205], s[36:37], 0, v[148:149]
	s_add_i32 m0, s56, 0xe000
	s_nop 0
	global_load_lds_dwordx4 v[204:205], off
	s_waitcnt vmcnt(8)
	s_waitcnt lgkmcnt(0)
	s_barrier
	s_setprio 1
	s_waitcnt lgkmcnt(0)
	v_mfma_f32_16x16x32_bf16 v[124:127], v[156:159], v[220:223], v[124:127]
	v_mfma_f32_16x16x32_bf16 v[120:123], v[164:167], v[220:223], v[120:123]
	v_mfma_f32_16x16x32_bf16 v[116:119], v[156:159], v[228:231], v[116:119]
	v_mfma_f32_16x16x32_bf16 v[112:115], v[164:167], v[228:231], v[112:115]
	v_mfma_f32_16x16x32_bf16 v[92:95], v[156:159], v[236:239], v[92:95]
	v_mfma_f32_16x16x32_bf16 v[88:91], v[164:167], v[236:239], v[88:91]
	v_mfma_f32_16x16x32_bf16 v[84:87], v[156:159], v[244:247], v[84:87]
	v_mfma_f32_16x16x32_bf16 v[80:83], v[164:167], v[244:247], v[80:83]
	v_mfma_f32_16x16x32_bf16 v[124:127], v[160:163], v[224:227], v[124:127]
	v_mfma_f32_16x16x32_bf16 v[120:123], v[168:171], v[224:227], v[120:123]
	v_mfma_f32_16x16x32_bf16 v[116:119], v[160:163], v[232:235], v[116:119]
	v_mfma_f32_16x16x32_bf16 v[112:115], v[168:171], v[232:235], v[112:115]
	v_mfma_f32_16x16x32_bf16 v[92:95], v[160:163], v[240:243], v[92:95]
	v_mfma_f32_16x16x32_bf16 v[88:91], v[168:171], v[240:243], v[88:91]
	v_mfma_f32_16x16x32_bf16 v[84:87], v[160:163], v[248:251], v[84:87]
	v_mfma_f32_16x16x32_bf16 v[80:83], v[168:171], v[248:251], v[80:83]
	s_setprio 0
	s_setprio 1
	v_mfma_f32_16x16x32_bf16 v[108:111], v[172:175], v[220:223], v[108:111]
	v_mfma_f32_16x16x32_bf16 v[104:107], v[212:215], v[220:223], v[104:107]
	v_mfma_f32_16x16x32_bf16 v[100:103], v[172:175], v[228:231], v[100:103]
	v_mfma_f32_16x16x32_bf16 v[96:99], v[212:215], v[228:231], v[96:99]
	v_mfma_f32_16x16x32_bf16 v[76:79], v[172:175], v[236:239], v[76:79]
	v_mfma_f32_16x16x32_bf16 v[72:75], v[212:215], v[236:239], v[72:75]
	v_mfma_f32_16x16x32_bf16 v[68:71], v[172:175], v[244:247], v[68:71]
	v_mfma_f32_16x16x32_bf16 v[64:67], v[212:215], v[244:247], v[64:67]
	v_mfma_f32_16x16x32_bf16 v[108:111], v[176:179], v[224:227], v[108:111]
	v_mfma_f32_16x16x32_bf16 v[104:107], v[216:219], v[224:227], v[104:107]
	v_mfma_f32_16x16x32_bf16 v[100:103], v[176:179], v[232:235], v[100:103]
	v_mfma_f32_16x16x32_bf16 v[96:99], v[216:219], v[232:235], v[96:99]
	v_mfma_f32_16x16x32_bf16 v[76:79], v[176:179], v[240:243], v[76:79]
	v_mfma_f32_16x16x32_bf16 v[72:75], v[216:219], v[240:243], v[72:75]
	v_mfma_f32_16x16x32_bf16 v[68:71], v[176:179], v[248:251], v[68:71]
	v_mfma_f32_16x16x32_bf16 v[64:67], v[216:219], v[248:251], v[64:67]
	s_setprio 0
	s_barrier
	s_add_i32 s48, s69, s55
	v_lshl_add_u64 v[204:205], s[40:41], 0, v[128:129]
	s_mov_b32 m0, s48
	ds_read_b128 v[220:223], v199 offset:16384
	ds_read_b128 v[224:227], v199 offset:17408
	ds_read_b128 v[228:231], v199 offset:18432
	ds_read_b128 v[232:235], v199 offset:19456
	ds_read_b128 v[236:239], v199 offset:20480
	ds_read_b128 v[240:243], v199 offset:21504
	ds_read_b128 v[244:247], v199 offset:22528
	ds_read_b128 v[248:251], v199 offset:23552
	global_load_lds_dwordx4 v[204:205], off
	s_add_i32 m0, s48, 0x2000
	s_add_u32 s48, s40, 0x4000
	v_lshl_add_u64 v[204:205], s[40:41], 0, v[130:131]
	s_addc_u32 s49, s41, 0
	s_add_i32 s50, s70, s55
	global_load_lds_dwordx4 v[204:205], off
	v_lshl_add_u64 v[204:205], s[48:49], 0, v[128:129]
	s_mov_b32 m0, s50
	s_nop 0
	global_load_lds_dwordx4 v[204:205], off
	v_lshl_add_u64 v[204:205], s[48:49], 0, v[130:131]
	s_add_i32 m0, s50, 0x2000
	s_nop 0
	global_load_lds_dwordx4 v[204:205], off
	v_lshl_add_u64 v[204:205], s[42:43], 0, v[128:129]
	v_lshl_add_u64 v[204:205], s[42:43], 0, v[130:131]
	s_waitcnt vmcnt(6)
	s_waitcnt lgkmcnt(0)
	s_barrier
	s_setprio 1
	s_waitcnt lgkmcnt(0)
	v_mfma_f32_16x16x32_bf16 v[60:63], v[156:159], v[220:223], v[60:63]
	v_mfma_f32_16x16x32_bf16 v[56:59], v[164:167], v[220:223], v[56:59]
	v_mfma_f32_16x16x32_bf16 v[52:55], v[156:159], v[228:231], v[52:55]
	v_mfma_f32_16x16x32_bf16 v[48:51], v[164:167], v[228:231], v[48:51]
	v_mfma_f32_16x16x32_bf16 v[28:31], v[156:159], v[236:239], v[28:31]
	v_mfma_f32_16x16x32_bf16 v[24:27], v[164:167], v[236:239], v[24:27]
	v_mfma_f32_16x16x32_bf16 v[20:23], v[156:159], v[244:247], v[20:23]
	v_mfma_f32_16x16x32_bf16 v[12:15], v[164:167], v[244:247], v[12:15]
	v_mfma_f32_16x16x32_bf16 v[60:63], v[160:163], v[224:227], v[60:63]
	v_mfma_f32_16x16x32_bf16 v[56:59], v[168:171], v[224:227], v[56:59]
	v_mfma_f32_16x16x32_bf16 v[52:55], v[160:163], v[232:235], v[52:55]
	v_mfma_f32_16x16x32_bf16 v[48:51], v[168:171], v[232:235], v[48:51]
	v_mfma_f32_16x16x32_bf16 v[28:31], v[160:163], v[240:243], v[28:31]
	v_mfma_f32_16x16x32_bf16 v[24:27], v[168:171], v[240:243], v[24:27]
	v_mfma_f32_16x16x32_bf16 v[20:23], v[160:163], v[248:251], v[20:23]
	v_mfma_f32_16x16x32_bf16 v[12:15], v[168:171], v[248:251], v[12:15]
	s_setprio 0
	s_setprio 1
	v_mfma_f32_16x16x32_bf16 v[44:47], v[172:175], v[220:223], v[44:47]
	v_mfma_f32_16x16x32_bf16 v[40:43], v[212:215], v[220:223], v[40:43]
	v_mfma_f32_16x16x32_bf16 v[36:39], v[172:175], v[228:231], v[36:39]
	v_mfma_f32_16x16x32_bf16 v[32:35], v[212:215], v[228:231], v[32:35]
	v_mfma_f32_16x16x32_bf16 v[16:19], v[172:175], v[236:239], v[16:19]
	v_mfma_f32_16x16x32_bf16 v[8:11], v[212:215], v[236:239], v[8:11]
	v_mfma_f32_16x16x32_bf16 v[4:7], v[172:175], v[244:247], v[4:7]
	v_mfma_f32_16x16x32_bf16 v[0:3], v[212:215], v[244:247], v[0:3]
	v_mfma_f32_16x16x32_bf16 v[44:47], v[176:179], v[224:227], v[44:47]
	v_mfma_f32_16x16x32_bf16 v[40:43], v[216:219], v[224:227], v[40:43]
	v_mfma_f32_16x16x32_bf16 v[36:39], v[176:179], v[232:235], v[36:39]
	v_mfma_f32_16x16x32_bf16 v[32:35], v[216:219], v[232:235], v[32:35]
	v_mfma_f32_16x16x32_bf16 v[16:19], v[176:179], v[240:243], v[16:19]
	v_mfma_f32_16x16x32_bf16 v[8:11], v[216:219], v[240:243], v[8:11]
	v_mfma_f32_16x16x32_bf16 v[4:7], v[176:179], v[248:251], v[4:7]
	v_mfma_f32_16x16x32_bf16 v[0:3], v[216:219], v[248:251], v[0:3]
	s_setprio 0
	s_barrier
	s_mov_b32 m0, s56
	s_nop 0
	global_load_lds_dwordx4 v128, s[42:43]
	s_mov_b32 m0, s57
	s_nop 0
	global_load_lds_dwordx4 v130, s[42:43]
	s_add_i32 s48, 0, 0x18000
	s_add_i32 s49, 0, 0x1c000
	v_add_u32_e32 v168, s48, v182
	v_add_u32_e32 v204, s49, v182
	ds_read_b128 v[156:159], v168
	ds_read_b128 v[160:163], v168 offset:1024
	ds_read_b128 v[164:167], v168 offset:2048
	ds_read_b128 v[168:171], v168 offset:3072
	ds_read_b128 v[172:175], v204
	ds_read_b128 v[176:179], v204 offset:1024
	ds_read_b128 v[212:215], v204 offset:2048
	ds_read_b128 v[216:219], v204 offset:3072
	s_add_u32 s42, s42, 0x4000
	s_addc_u32 s43, s43, 0
	s_mov_b32 m0, s58
	v_lshl_add_u64 v[204:205], s[42:43], 0, v[128:129]
	ds_read_b128 v[220:223], v199 offset:32768
	ds_read_b128 v[224:227], v199 offset:33792
	ds_read_b128 v[228:231], v199 offset:34816
	ds_read_b128 v[232:235], v199 offset:35840
	ds_read_b128 v[236:239], v199 offset:36864
	ds_read_b128 v[240:243], v199 offset:37888
	ds_read_b128 v[244:247], v199 offset:38912
	ds_read_b128 v[248:251], v199 offset:39936
	global_load_lds_dwordx4 v[204:205], off
	v_lshl_add_u64 v[204:205], s[42:43], 0, v[130:131]
	s_mov_b32 m0, s59
	s_nop 0
	global_load_lds_dwordx4 v[204:205], off
	s_waitcnt vmcnt(8)
	s_waitcnt lgkmcnt(0)
	s_barrier
	s_setprio 1
	s_waitcnt lgkmcnt(0)
	v_mfma_f32_16x16x32_bf16 v[124:127], v[156:159], v[220:223], v[124:127]
	v_mfma_f32_16x16x32_bf16 v[120:123], v[164:167], v[220:223], v[120:123]
	v_mfma_f32_16x16x32_bf16 v[116:119], v[156:159], v[228:231], v[116:119]
	v_mfma_f32_16x16x32_bf16 v[112:115], v[164:167], v[228:231], v[112:115]
	v_mfma_f32_16x16x32_bf16 v[92:95], v[156:159], v[236:239], v[92:95]
	v_mfma_f32_16x16x32_bf16 v[88:91], v[164:167], v[236:239], v[88:91]
	v_mfma_f32_16x16x32_bf16 v[84:87], v[156:159], v[244:247], v[84:87]
	v_mfma_f32_16x16x32_bf16 v[80:83], v[164:167], v[244:247], v[80:83]
	v_mfma_f32_16x16x32_bf16 v[124:127], v[160:163], v[224:227], v[124:127]
	v_mfma_f32_16x16x32_bf16 v[120:123], v[168:171], v[224:227], v[120:123]
	v_mfma_f32_16x16x32_bf16 v[116:119], v[160:163], v[232:235], v[116:119]
	v_mfma_f32_16x16x32_bf16 v[112:115], v[168:171], v[232:235], v[112:115]
	v_mfma_f32_16x16x32_bf16 v[92:95], v[160:163], v[240:243], v[92:95]
	v_mfma_f32_16x16x32_bf16 v[88:91], v[168:171], v[240:243], v[88:91]
	v_mfma_f32_16x16x32_bf16 v[84:87], v[160:163], v[248:251], v[84:87]
	v_mfma_f32_16x16x32_bf16 v[80:83], v[168:171], v[248:251], v[80:83]
	s_setprio 0
	s_setprio 1
	v_mfma_f32_16x16x32_bf16 v[108:111], v[172:175], v[220:223], v[108:111]
	v_mfma_f32_16x16x32_bf16 v[104:107], v[212:215], v[220:223], v[104:107]
	v_mfma_f32_16x16x32_bf16 v[100:103], v[172:175], v[228:231], v[100:103]
	v_mfma_f32_16x16x32_bf16 v[96:99], v[212:215], v[228:231], v[96:99]
	v_mfma_f32_16x16x32_bf16 v[76:79], v[172:175], v[236:239], v[76:79]
	v_mfma_f32_16x16x32_bf16 v[72:75], v[212:215], v[236:239], v[72:75]
	v_mfma_f32_16x16x32_bf16 v[68:71], v[172:175], v[244:247], v[68:71]
	v_mfma_f32_16x16x32_bf16 v[64:67], v[212:215], v[244:247], v[64:67]
	v_mfma_f32_16x16x32_bf16 v[108:111], v[176:179], v[224:227], v[108:111]
	v_mfma_f32_16x16x32_bf16 v[104:107], v[216:219], v[224:227], v[104:107]
	v_mfma_f32_16x16x32_bf16 v[100:103], v[176:179], v[232:235], v[100:103]
	v_mfma_f32_16x16x32_bf16 v[96:99], v[216:219], v[232:235], v[96:99]
	v_mfma_f32_16x16x32_bf16 v[76:79], v[176:179], v[240:243], v[76:79]
	v_mfma_f32_16x16x32_bf16 v[72:75], v[216:219], v[240:243], v[72:75]
	v_mfma_f32_16x16x32_bf16 v[68:71], v[176:179], v[248:251], v[68:71]
	v_mfma_f32_16x16x32_bf16 v[64:67], v[216:219], v[248:251], v[64:67]
	s_setprio 0
	s_barrier
	s_add_u32 s42, s40, 0x8000
	s_addc_u32 s43, s41, 0
	s_add_i32 s48, s48, s55
	v_lshl_add_u64 v[204:205], s[42:43], 0, v[128:129]
	s_mov_b32 m0, s48
	ds_read_b128 v[220:223], v199 offset:49152
	ds_read_b128 v[224:227], v199 offset:50176
	ds_read_b128 v[228:231], v199 offset:51200
	ds_read_b128 v[232:235], v199 offset:52224
	ds_read_b128 v[236:239], v199 offset:53248
	ds_read_b128 v[240:243], v199 offset:54272
	ds_read_b128 v[244:247], v199 offset:55296
	ds_read_b128 v[248:251], v199 offset:56320
	global_load_lds_dwordx4 v[204:205], off
	s_add_i32 m0, s48, 0x2000
	s_add_u32 s40, s40, 0xc000
	v_lshl_add_u64 v[204:205], s[42:43], 0, v[130:131]
	s_addc_u32 s41, s41, 0
	s_add_i32 s42, s49, s55
	global_load_lds_dwordx4 v[204:205], off
	v_lshl_add_u64 v[204:205], s[40:41], 0, v[128:129]
	s_mov_b32 m0, s42
	s_nop 0
	global_load_lds_dwordx4 v[204:205], off
	v_lshl_add_u64 v[204:205], s[40:41], 0, v[130:131]
	s_add_i32 m0, s42, 0x2000
	s_nop 0
	global_load_lds_dwordx4 v[204:205], off
	v_lshl_add_u64 v[204:205], s[38:39], 0, v[128:129]
	s_mov_b32 m0, s65
	s_nop 0
	global_load_lds_dwordx4 v[204:205], off
	v_lshl_add_u64 v[204:205], s[38:39], 0, v[130:131]
	s_mov_b32 m0, s66
	s_nop 0
	global_load_lds_dwordx4 v[204:205], off
	s_waitcnt vmcnt(8)
	s_waitcnt lgkmcnt(0)
	s_barrier
	s_setprio 1
	s_waitcnt lgkmcnt(0)
	v_mfma_f32_16x16x32_bf16 v[60:63], v[156:159], v[220:223], v[60:63]
	v_mfma_f32_16x16x32_bf16 v[56:59], v[164:167], v[220:223], v[56:59]
	v_mfma_f32_16x16x32_bf16 v[52:55], v[156:159], v[228:231], v[52:55]
	v_mfma_f32_16x16x32_bf16 v[48:51], v[164:167], v[228:231], v[48:51]
	v_mfma_f32_16x16x32_bf16 v[28:31], v[156:159], v[236:239], v[28:31]
	v_mfma_f32_16x16x32_bf16 v[24:27], v[164:167], v[236:239], v[24:27]
	v_mfma_f32_16x16x32_bf16 v[20:23], v[156:159], v[244:247], v[20:23]
	v_mfma_f32_16x16x32_bf16 v[12:15], v[164:167], v[244:247], v[12:15]
	v_mfma_f32_16x16x32_bf16 v[60:63], v[160:163], v[224:227], v[60:63]
	v_mfma_f32_16x16x32_bf16 v[56:59], v[168:171], v[224:227], v[56:59]
	v_mfma_f32_16x16x32_bf16 v[52:55], v[160:163], v[232:235], v[52:55]
	v_mfma_f32_16x16x32_bf16 v[48:51], v[168:171], v[232:235], v[48:51]
	v_mfma_f32_16x16x32_bf16 v[28:31], v[160:163], v[240:243], v[28:31]
	v_mfma_f32_16x16x32_bf16 v[24:27], v[168:171], v[240:243], v[24:27]
	v_mfma_f32_16x16x32_bf16 v[20:23], v[160:163], v[248:251], v[20:23]
	v_mfma_f32_16x16x32_bf16 v[12:15], v[168:171], v[248:251], v[12:15]
	s_setprio 0
	s_setprio 1
	v_mfma_f32_16x16x32_bf16 v[44:47], v[172:175], v[220:223], v[44:47]
	v_mfma_f32_16x16x32_bf16 v[40:43], v[212:215], v[220:223], v[40:43]
	v_mfma_f32_16x16x32_bf16 v[36:39], v[172:175], v[228:231], v[36:39]
	v_mfma_f32_16x16x32_bf16 v[32:35], v[212:215], v[228:231], v[32:35]
	v_mfma_f32_16x16x32_bf16 v[16:19], v[172:175], v[236:239], v[16:19]
	v_mfma_f32_16x16x32_bf16 v[8:11], v[212:215], v[236:239], v[8:11]
	v_mfma_f32_16x16x32_bf16 v[4:7], v[172:175], v[244:247], v[4:7]
	v_mfma_f32_16x16x32_bf16 v[0:3], v[212:215], v[244:247], v[0:3]
	v_mfma_f32_16x16x32_bf16 v[44:47], v[176:179], v[224:227], v[44:47]
	v_mfma_f32_16x16x32_bf16 v[40:43], v[216:219], v[224:227], v[40:43]
	v_mfma_f32_16x16x32_bf16 v[36:39], v[176:179], v[232:235], v[36:39]
	v_mfma_f32_16x16x32_bf16 v[32:35], v[216:219], v[232:235], v[32:35]
	v_mfma_f32_16x16x32_bf16 v[16:19], v[176:179], v[240:243], v[16:19]
	v_mfma_f32_16x16x32_bf16 v[8:11], v[216:219], v[240:243], v[8:11]
	v_mfma_f32_16x16x32_bf16 v[4:7], v[176:179], v[248:251], v[4:7]
	v_mfma_f32_16x16x32_bf16 v[0:3], v[216:219], v[248:251], v[0:3]
	s_setprio 0
	s_barrier
	s_add_i32 s47, s47, 2
	s_add_u32 s45, s45, 0x10000
	s_addc_u32 s46, s46, 0
	s_add_u32 s36, s36, 0x10000
	s_addc_u32 s37, s37, 0
	s_cmp_gt_u32 s47, 41
	s_cbranch_scc0 .LBB0_1645
	s_and_b64 vcc, exec, s[2:3]
	s_cbranch_vccz .LBB0_1648
	s_barrier

.LBB0_1729:
	ds_read_b128 v[128:131], v210
	ds_read_b128 v[132:135], v210 offset:1024
	ds_read_b128 v[136:139], v210 offset:2048
	ds_read_b128 v[140:143], v210 offset:3072
	ds_read_b128 v[144:147], v211
	ds_read_b128 v[148:151], v211 offset:1024
	ds_read_b128 v[152:155], v211 offset:2048
	ds_read_b128 v[156:159], v211 offset:3072
	s_add_u32 s26, s6, 0xfffc0080
	s_addc_u32 s27, s7, -1
	s_cmp_eq_u32 s35, 12
	s_cselect_b32 s29, s1, s27
	s_cselect_b32 s28, s19, s26
	s_cselect_b32 s27, s21, s34
	s_cselect_b32 s26, s30, s31
	v_lshl_add_u64 v[198:199], s[6:7], 0, v[188:189]
	s_add_i32 m0, s42, 0xc000
	ds_read_b128 v[160:163], v212
	ds_read_b128 v[164:167], v212 offset:1024
	ds_read_b128 v[194:197], v212 offset:2048
	ds_read_b128 v[214:217], v212 offset:3072
	ds_read_b128 v[218:221], v212 offset:4096
	ds_read_b128 v[222:225], v212 offset:5120
	ds_read_b128 v[226:229], v212 offset:6144
	ds_read_b128 v[230:233], v212 offset:7168
	global_load_lds_dwordx4 v[198:199], off
	v_lshl_add_u64 v[198:199], s[6:7], 0, v[186:187]
	s_add_i32 m0, s42, 0xe000
	s_nop 0
	global_load_lds_dwordx4 v[198:199], off
	s_waitcnt vmcnt(8)
	s_waitcnt lgkmcnt(0)
	s_barrier
	s_setprio 1
	s_waitcnt lgkmcnt(0)
	v_mfma_f32_16x16x32_bf16 v[124:127], v[128:131], v[160:163], v[124:127]
	v_mfma_f32_16x16x32_bf16 v[120:123], v[136:139], v[160:163], v[120:123]
	v_mfma_f32_16x16x32_bf16 v[116:119], v[128:131], v[194:197], v[116:119]
	v_mfma_f32_16x16x32_bf16 v[112:115], v[136:139], v[194:197], v[112:115]
	v_mfma_f32_16x16x32_bf16 v[108:111], v[128:131], v[218:221], v[108:111]
	v_mfma_f32_16x16x32_bf16 v[104:107], v[136:139], v[218:221], v[104:107]
	v_mfma_f32_16x16x32_bf16 v[100:103], v[128:131], v[226:229], v[100:103]
	v_mfma_f32_16x16x32_bf16 v[96:99], v[136:139], v[226:229], v[96:99]
	v_mfma_f32_16x16x32_bf16 v[124:127], v[132:135], v[164:167], v[124:127]
	v_mfma_f32_16x16x32_bf16 v[120:123], v[140:143], v[164:167], v[120:123]
	v_mfma_f32_16x16x32_bf16 v[116:119], v[132:135], v[214:217], v[116:119]
	v_mfma_f32_16x16x32_bf16 v[112:115], v[140:143], v[214:217], v[112:115]
	v_mfma_f32_16x16x32_bf16 v[108:111], v[132:135], v[222:225], v[108:111]
	v_mfma_f32_16x16x32_bf16 v[104:107], v[140:143], v[222:225], v[104:107]
	v_mfma_f32_16x16x32_bf16 v[100:103], v[132:135], v[230:233], v[100:103]
	v_mfma_f32_16x16x32_bf16 v[96:99], v[140:143], v[230:233], v[96:99]
	s_setprio 0
	s_setprio 1
	v_mfma_f32_16x16x32_bf16 v[60:63], v[144:147], v[160:163], v[60:63]
	v_mfma_f32_16x16x32_bf16 v[56:59], v[152:155], v[160:163], v[56:59]
	v_mfma_f32_16x16x32_bf16 v[52:55], v[144:147], v[194:197], v[52:55]
	v_mfma_f32_16x16x32_bf16 v[48:51], v[152:155], v[194:197], v[48:51]
	v_mfma_f32_16x16x32_bf16 v[44:47], v[144:147], v[218:221], v[44:47]
	v_mfma_f32_16x16x32_bf16 v[40:43], v[152:155], v[218:221], v[40:43]
	v_mfma_f32_16x16x32_bf16 v[36:39], v[144:147], v[226:229], v[36:39]
	v_mfma_f32_16x16x32_bf16 v[32:35], v[152:155], v[226:229], v[32:35]
	v_mfma_f32_16x16x32_bf16 v[60:63], v[148:151], v[164:167], v[60:63]
	v_mfma_f32_16x16x32_bf16 v[56:59], v[156:159], v[164:167], v[56:59]
	v_mfma_f32_16x16x32_bf16 v[52:55], v[148:151], v[214:217], v[52:55]
	v_mfma_f32_16x16x32_bf16 v[48:51], v[156:159], v[214:217], v[48:51]
	v_mfma_f32_16x16x32_bf16 v[44:47], v[148:151], v[222:225], v[44:47]
	v_mfma_f32_16x16x32_bf16 v[40:43], v[156:159], v[222:225], v[40:43]
	v_mfma_f32_16x16x32_bf16 v[36:39], v[148:151], v[230:233], v[36:39]
	v_mfma_f32_16x16x32_bf16 v[32:35], v[156:159], v[230:233], v[32:35]
	s_setprio 0
	s_barrier
	s_add_i32 s61, s56, s41
	v_lshl_add_u64 v[198:199], s[26:27], 0, v[170:171]
	s_mov_b32 m0, s61
	ds_read_b128 v[160:163], v212 offset:16384
	ds_read_b128 v[164:167], v212 offset:17408
	ds_read_b128 v[194:197], v212 offset:18432
	ds_read_b128 v[214:217], v212 offset:19456
	ds_read_b128 v[218:221], v212 offset:20480
	ds_read_b128 v[222:225], v212 offset:21504
	ds_read_b128 v[226:229], v212 offset:22528
	ds_read_b128 v[230:233], v212 offset:23552
	global_load_lds_dwordx4 v[198:199], off
	s_add_i32 m0, s61, 0x2000
	s_add_u32 s62, s26, 0x4000
	v_lshl_add_u64 v[198:199], s[26:27], 0, v[174:175]
	s_addc_u32 s63, s27, 0
	s_add_i32 s61, s57, s41
	global_load_lds_dwordx4 v[198:199], off
	v_lshl_add_u64 v[198:199], s[62:63], 0, v[170:171]
	s_mov_b32 m0, s61
	v_lshl_add_u64 v[204:205], s[28:29], 0, v[172:173]
	global_load_lds_dwordx4 v[198:199], off
	v_lshl_add_u64 v[198:199], s[62:63], 0, v[174:175]
	s_add_i32 m0, s61, 0x2000
	s_nop 0
	global_load_lds_dwordx4 v[198:199], off
	v_lshl_add_u64 v[198:199], s[28:29], 0, v[168:169]
	s_waitcnt vmcnt(6)
	s_waitcnt lgkmcnt(0)
	s_barrier
	s_setprio 1
	s_waitcnt lgkmcnt(0)
	v_mfma_f32_16x16x32_bf16 v[92:95], v[128:131], v[160:163], v[92:95]
	v_mfma_f32_16x16x32_bf16 v[88:91], v[136:139], v[160:163], v[88:91]
	v_mfma_f32_16x16x32_bf16 v[84:87], v[128:131], v[194:197], v[84:87]
	v_mfma_f32_16x16x32_bf16 v[80:83], v[136:139], v[194:197], v[80:83]
	v_mfma_f32_16x16x32_bf16 v[76:79], v[128:131], v[218:221], v[76:79]
	v_mfma_f32_16x16x32_bf16 v[72:75], v[136:139], v[218:221], v[72:75]
	v_mfma_f32_16x16x32_bf16 v[68:71], v[128:131], v[226:229], v[68:71]
	v_mfma_f32_16x16x32_bf16 v[64:67], v[136:139], v[226:229], v[64:67]
	v_mfma_f32_16x16x32_bf16 v[92:95], v[132:135], v[164:167], v[92:95]
	v_mfma_f32_16x16x32_bf16 v[88:91], v[140:143], v[164:167], v[88:91]
	v_mfma_f32_16x16x32_bf16 v[84:87], v[132:135], v[214:217], v[84:87]
	v_mfma_f32_16x16x32_bf16 v[80:83], v[140:143], v[214:217], v[80:83]
	v_mfma_f32_16x16x32_bf16 v[76:79], v[132:135], v[222:225], v[76:79]
	v_mfma_f32_16x16x32_bf16 v[72:75], v[140:143], v[222:225], v[72:75]
	v_mfma_f32_16x16x32_bf16 v[68:71], v[132:135], v[230:233], v[68:71]
	v_mfma_f32_16x16x32_bf16 v[64:67], v[140:143], v[230:233], v[64:67]
	s_setprio 0
	s_setprio 1
	v_mfma_f32_16x16x32_bf16 v[28:31], v[144:147], v[160:163], v[28:31]
	v_mfma_f32_16x16x32_bf16 v[24:27], v[152:155], v[160:163], v[24:27]
	v_mfma_f32_16x16x32_bf16 v[20:23], v[144:147], v[194:197], v[20:23]
	v_mfma_f32_16x16x32_bf16 v[16:19], v[152:155], v[194:197], v[16:19]
	v_mfma_f32_16x16x32_bf16 v[12:15], v[144:147], v[218:221], v[12:15]
	v_mfma_f32_16x16x32_bf16 v[8:11], v[152:155], v[218:221], v[8:11]
	v_mfma_f32_16x16x32_bf16 v[4:7], v[144:147], v[226:229], v[4:7]
	v_mfma_f32_16x16x32_bf16 v[0:3], v[152:155], v[226:229], v[0:3]
	v_mfma_f32_16x16x32_bf16 v[28:31], v[148:151], v[164:167], v[28:31]
	v_mfma_f32_16x16x32_bf16 v[24:27], v[156:159], v[164:167], v[24:27]
	v_mfma_f32_16x16x32_bf16 v[20:23], v[148:151], v[214:217], v[20:23]
	v_mfma_f32_16x16x32_bf16 v[16:19], v[156:159], v[214:217], v[16:19]
	v_mfma_f32_16x16x32_bf16 v[12:15], v[148:151], v[222:225], v[12:15]
	v_mfma_f32_16x16x32_bf16 v[8:11], v[156:159], v[222:225], v[8:11]
	v_mfma_f32_16x16x32_bf16 v[4:7], v[148:151], v[230:233], v[4:7]
	v_mfma_f32_16x16x32_bf16 v[0:3], v[156:159], v[230:233], v[0:3]
	s_setprio 0
	s_barrier
	s_mov_b32 m0, s42
	s_nop 0
	global_load_lds_dwordx4 v168, s[28:29]
	s_mov_b32 m0, s43
	s_nop 0
	global_load_lds_dwordx4 v172, s[28:29]
	s_add_i32 s61, 0, 0x18000
	s_add_i32 s62, 0, 0x1c000
	v_add_u32_e32 v140, s61, v200
	v_add_u32_e32 v156, s62, v200
	ds_read_b128 v[128:131], v140
	ds_read_b128 v[132:135], v140 offset:1024
	ds_read_b128 v[136:139], v140 offset:2048
	ds_read_b128 v[140:143], v140 offset:3072
	ds_read_b128 v[144:147], v156
	ds_read_b128 v[148:151], v156 offset:1024
	ds_read_b128 v[152:155], v156 offset:2048
	ds_read_b128 v[156:159], v156 offset:3072
	s_add_u32 s28, s28, 0x40000
	s_addc_u32 s29, s29, 0
	s_mov_b32 m0, s44
	v_lshl_add_u64 v[206:207], s[28:29], 0, v[168:169]
	ds_read_b128 v[160:163], v212 offset:32768
	ds_read_b128 v[164:167], v212 offset:33792
	ds_read_b128 v[194:197], v212 offset:34816
	ds_read_b128 v[214:217], v212 offset:35840
	ds_read_b128 v[218:221], v212 offset:36864
	ds_read_b128 v[222:225], v212 offset:37888
	ds_read_b128 v[226:229], v212 offset:38912
	ds_read_b128 v[230:233], v212 offset:39936
	global_load_lds_dwordx4 v[206:207], off
	v_lshl_add_u64 v[206:207], s[28:29], 0, v[172:173]
	s_mov_b32 m0, s45
	s_nop 0
	global_load_lds_dwordx4 v[206:207], off
	s_waitcnt vmcnt(8)
	s_waitcnt lgkmcnt(0)
	s_barrier
	s_setprio 1
	s_waitcnt lgkmcnt(0)
	v_mfma_f32_16x16x32_bf16 v[124:127], v[128:131], v[160:163], v[124:127]
	v_mfma_f32_16x16x32_bf16 v[120:123], v[136:139], v[160:163], v[120:123]
	v_mfma_f32_16x16x32_bf16 v[116:119], v[128:131], v[194:197], v[116:119]
	v_mfma_f32_16x16x32_bf16 v[112:115], v[136:139], v[194:197], v[112:115]
	v_mfma_f32_16x16x32_bf16 v[108:111], v[128:131], v[218:221], v[108:111]
	v_mfma_f32_16x16x32_bf16 v[104:107], v[136:139], v[218:221], v[104:107]
	v_mfma_f32_16x16x32_bf16 v[100:103], v[128:131], v[226:229], v[100:103]
	v_mfma_f32_16x16x32_bf16 v[96:99], v[136:139], v[226:229], v[96:99]
	v_mfma_f32_16x16x32_bf16 v[124:127], v[132:135], v[164:167], v[124:127]
	v_mfma_f32_16x16x32_bf16 v[120:123], v[140:143], v[164:167], v[120:123]
	v_mfma_f32_16x16x32_bf16 v[116:119], v[132:135], v[214:217], v[116:119]
	v_mfma_f32_16x16x32_bf16 v[112:115], v[140:143], v[214:217], v[112:115]
	v_mfma_f32_16x16x32_bf16 v[108:111], v[132:135], v[222:225], v[108:111]
	v_mfma_f32_16x16x32_bf16 v[104:107], v[140:143], v[222:225], v[104:107]
	v_mfma_f32_16x16x32_bf16 v[100:103], v[132:135], v[230:233], v[100:103]
	v_mfma_f32_16x16x32_bf16 v[96:99], v[140:143], v[230:233], v[96:99]
	s_setprio 0
	s_setprio 1
	v_mfma_f32_16x16x32_bf16 v[60:63], v[144:147], v[160:163], v[60:63]
	v_mfma_f32_16x16x32_bf16 v[56:59], v[152:155], v[160:163], v[56:59]
	v_mfma_f32_16x16x32_bf16 v[52:55], v[144:147], v[194:197], v[52:55]
	v_mfma_f32_16x16x32_bf16 v[48:51], v[152:155], v[194:197], v[48:51]
	v_mfma_f32_16x16x32_bf16 v[44:47], v[144:147], v[218:221], v[44:47]
	v_mfma_f32_16x16x32_bf16 v[40:43], v[152:155], v[218:221], v[40:43]
	v_mfma_f32_16x16x32_bf16 v[36:39], v[144:147], v[226:229], v[36:39]
	v_mfma_f32_16x16x32_bf16 v[32:35], v[152:155], v[226:229], v[32:35]
	v_mfma_f32_16x16x32_bf16 v[60:63], v[148:151], v[164:167], v[60:63]
	v_mfma_f32_16x16x32_bf16 v[56:59], v[156:159], v[164:167], v[56:59]
	v_mfma_f32_16x16x32_bf16 v[52:55], v[148:151], v[214:217], v[52:55]
	v_mfma_f32_16x16x32_bf16 v[48:51], v[156:159], v[214:217], v[48:51]
	v_mfma_f32_16x16x32_bf16 v[44:47], v[148:151], v[222:225], v[44:47]
	v_mfma_f32_16x16x32_bf16 v[40:43], v[156:159], v[222:225], v[40:43]
	v_mfma_f32_16x16x32_bf16 v[36:39], v[148:151], v[230:233], v[36:39]
	v_mfma_f32_16x16x32_bf16 v[32:35], v[156:159], v[230:233], v[32:35]
	s_setprio 0
	s_barrier
	s_add_u32 s28, s26, 0x8000
	s_addc_u32 s29, s27, 0
	s_add_i32 s61, s61, s41
	v_lshl_add_u64 v[206:207], s[28:29], 0, v[170:171]
	s_mov_b32 m0, s61
	ds_read_b128 v[160:163], v212 offset:49152
	ds_read_b128 v[164:167], v212 offset:50176
	ds_read_b128 v[194:197], v212 offset:51200
	ds_read_b128 v[214:217], v212 offset:52224
	ds_read_b128 v[218:221], v212 offset:53248
	ds_read_b128 v[222:225], v212 offset:54272
	ds_read_b128 v[226:229], v212 offset:55296
	ds_read_b128 v[230:233], v212 offset:56320
	global_load_lds_dwordx4 v[206:207], off
	s_add_i32 m0, s61, 0x2000
	s_add_u32 s26, s26, 0xc000
	v_lshl_add_u64 v[206:207], s[28:29], 0, v[174:175]
	s_addc_u32 s27, s27, 0
	s_add_i32 s28, s62, s41
	global_load_lds_dwordx4 v[206:207], off
	v_lshl_add_u64 v[206:207], s[26:27], 0, v[170:171]
	s_mov_b32 m0, s28
	v_lshl_add_u64 v[198:199], v[198:199], 0, s[12:13]
	global_load_lds_dwordx4 v[206:207], off
	v_lshl_add_u64 v[206:207], s[26:27], 0, v[174:175]
	s_add_i32 m0, s28, 0x2000
	s_nop 0
	global_load_lds_dwordx4 v[206:207], off
	s_mov_b32 m0, s50
	s_nop 0
	global_load_lds_dwordx4 v[198:199], off
	v_lshl_add_u64 v[198:199], v[204:205], 0, s[12:13]
	s_mov_b32 m0, s51
	s_nop 0
	global_load_lds_dwordx4 v[198:199], off
	s_waitcnt vmcnt(8)
	s_waitcnt lgkmcnt(0)
	s_barrier
	s_setprio 1
	s_waitcnt lgkmcnt(0)
	v_mfma_f32_16x16x32_bf16 v[92:95], v[128:131], v[160:163], v[92:95]
	v_mfma_f32_16x16x32_bf16 v[88:91], v[136:139], v[160:163], v[88:91]
	v_mfma_f32_16x16x32_bf16 v[84:87], v[128:131], v[194:197], v[84:87]
	v_mfma_f32_16x16x32_bf16 v[80:83], v[136:139], v[194:197], v[80:83]
	v_mfma_f32_16x16x32_bf16 v[76:79], v[128:131], v[218:221], v[76:79]
	v_mfma_f32_16x16x32_bf16 v[72:75], v[136:139], v[218:221], v[72:75]
	v_mfma_f32_16x16x32_bf16 v[68:71], v[128:131], v[226:229], v[68:71]
	v_mfma_f32_16x16x32_bf16 v[64:67], v[136:139], v[226:229], v[64:67]
	v_mfma_f32_16x16x32_bf16 v[92:95], v[132:135], v[164:167], v[92:95]
	v_mfma_f32_16x16x32_bf16 v[88:91], v[140:143], v[164:167], v[88:91]
	v_mfma_f32_16x16x32_bf16 v[84:87], v[132:135], v[214:217], v[84:87]
	v_mfma_f32_16x16x32_bf16 v[80:83], v[140:143], v[214:217], v[80:83]
	v_mfma_f32_16x16x32_bf16 v[76:79], v[132:135], v[222:225], v[76:79]
	v_mfma_f32_16x16x32_bf16 v[72:75], v[140:143], v[222:225], v[72:75]
	v_mfma_f32_16x16x32_bf16 v[68:71], v[132:135], v[230:233], v[68:71]
	v_mfma_f32_16x16x32_bf16 v[64:67], v[140:143], v[230:233], v[64:67]
	s_setprio 0
	s_setprio 1
	v_mfma_f32_16x16x32_bf16 v[28:31], v[144:147], v[160:163], v[28:31]
	v_mfma_f32_16x16x32_bf16 v[24:27], v[152:155], v[160:163], v[24:27]
	v_mfma_f32_16x16x32_bf16 v[20:23], v[144:147], v[194:197], v[20:23]
	v_mfma_f32_16x16x32_bf16 v[16:19], v[152:155], v[194:197], v[16:19]
	v_mfma_f32_16x16x32_bf16 v[12:15], v[144:147], v[218:221], v[12:15]
	v_mfma_f32_16x16x32_bf16 v[8:11], v[152:155], v[218:221], v[8:11]
	v_mfma_f32_16x16x32_bf16 v[4:7], v[144:147], v[226:229], v[4:7]
	v_mfma_f32_16x16x32_bf16 v[0:3], v[152:155], v[226:229], v[0:3]
	v_mfma_f32_16x16x32_bf16 v[28:31], v[148:151], v[164:167], v[28:31]
	v_mfma_f32_16x16x32_bf16 v[24:27], v[156:159], v[164:167], v[24:27]
	v_mfma_f32_16x16x32_bf16 v[20:23], v[148:151], v[214:217], v[20:23]
	v_mfma_f32_16x16x32_bf16 v[16:19], v[156:159], v[214:217], v[16:19]
	v_mfma_f32_16x16x32_bf16 v[12:15], v[148:151], v[222:225], v[12:15]
	v_mfma_f32_16x16x32_bf16 v[8:11], v[156:159], v[222:225], v[8:11]
	v_mfma_f32_16x16x32_bf16 v[4:7], v[148:151], v[230:233], v[4:7]
	v_mfma_f32_16x16x32_bf16 v[0:3], v[156:159], v[230:233], v[0:3]
	s_setprio 0
	s_barrier
	s_add_i32 s35, s35, 2
	s_add_u32 s31, s31, 0x10000
	s_addc_u32 s34, s34, 0
	s_add_u32 s6, s6, 0x100
	s_addc_u32 s7, s7, 0
	s_cmp_gt_u32 s35, 13
	s_cbranch_scc0 .LBB0_1729
	s_and_b64 vcc, exec, s[14:15]
	s_cbranch_vccz .LBB0_1740
	s_barrier
	v_lshl_add_u32 v214, s0, 8, v179
	s_cmp_gt_i32 s2, 4
	s_mov_b64 s[0:1], -1
	s_cbranch_scc1 .LBB0_1741

.LBB0_2258:
	ds_read_b128 v[128:131], v170
	ds_read_b128 v[148:151], v170 offset:1024
	ds_read_b128 v[152:155], v170 offset:2048
	ds_read_b128 v[174:177], v170 offset:3072
	ds_read_b128 v[178:181], v171
	ds_read_b128 v[182:185], v171 offset:1024
	ds_read_b128 v[186:189], v171 offset:2048
	ds_read_b128 v[190:193], v171 offset:3072
	s_add_u32 s30, s28, 0xfffe0080
	s_addc_u32 s31, s29, -1
	s_cmp_eq_u32 s56, 4
	s_cselect_b32 s35, s17, s31
	s_cselect_b32 s34, s52, s30
	s_cselect_b32 s31, s19, s55
	s_cselect_b32 s30, s53, s54
	v_lshl_add_u64 v[204:205], s[28:29], 0, v[142:143]
	s_add_i32 m0, s25, 0xc000
	ds_read_b128 v[194:197], v172
	ds_read_b128 v[198:201], v172 offset:1024
	ds_read_b128 v[210:213], v172 offset:2048
	ds_read_b128 v[214:217], v172 offset:3072
	ds_read_b128 v[218:221], v172 offset:4096
	ds_read_b128 v[222:225], v172 offset:5120
	ds_read_b128 v[226:229], v172 offset:6144
	ds_read_b128 v[230:233], v172 offset:7168
	global_load_lds_dwordx4 v[204:205], off
	v_lshl_add_u64 v[204:205], s[28:29], 0, v[140:141]
	s_add_i32 m0, s25, 0xe000
	s_nop 0
	global_load_lds_dwordx4 v[204:205], off
	s_waitcnt vmcnt(8)
	s_waitcnt lgkmcnt(0)
	s_barrier
	s_setprio 1
	s_waitcnt lgkmcnt(0)
	v_mfma_f32_16x16x32_bf16 v[124:127], v[128:131], v[194:197], v[124:127]
	v_mfma_f32_16x16x32_bf16 v[120:123], v[152:155], v[194:197], v[120:123]
	v_mfma_f32_16x16x32_bf16 v[116:119], v[128:131], v[210:213], v[116:119]
	v_mfma_f32_16x16x32_bf16 v[112:115], v[152:155], v[210:213], v[112:115]
	v_mfma_f32_16x16x32_bf16 v[92:95], v[128:131], v[218:221], v[92:95]
	v_mfma_f32_16x16x32_bf16 v[88:91], v[152:155], v[218:221], v[88:91]
	v_mfma_f32_16x16x32_bf16 v[84:87], v[128:131], v[226:229], v[84:87]
	v_mfma_f32_16x16x32_bf16 v[72:75], v[152:155], v[226:229], v[72:75]
	v_mfma_f32_16x16x32_bf16 v[124:127], v[148:151], v[198:201], v[124:127]
	v_mfma_f32_16x16x32_bf16 v[120:123], v[174:177], v[198:201], v[120:123]
	v_mfma_f32_16x16x32_bf16 v[116:119], v[148:151], v[214:217], v[116:119]
	v_mfma_f32_16x16x32_bf16 v[112:115], v[174:177], v[214:217], v[112:115]
	v_mfma_f32_16x16x32_bf16 v[92:95], v[148:151], v[222:225], v[92:95]
	v_mfma_f32_16x16x32_bf16 v[88:91], v[174:177], v[222:225], v[88:91]
	v_mfma_f32_16x16x32_bf16 v[84:87], v[148:151], v[230:233], v[84:87]
	v_mfma_f32_16x16x32_bf16 v[72:75], v[174:177], v[230:233], v[72:75]
	s_setprio 0
	s_setprio 1
	v_mfma_f32_16x16x32_bf16 v[108:111], v[178:181], v[194:197], v[108:111]
	v_mfma_f32_16x16x32_bf16 v[104:107], v[186:189], v[194:197], v[104:107]
	v_mfma_f32_16x16x32_bf16 v[100:103], v[178:181], v[210:213], v[100:103]
	v_mfma_f32_16x16x32_bf16 v[96:99], v[186:189], v[210:213], v[96:99]
	v_mfma_f32_16x16x32_bf16 v[80:83], v[178:181], v[218:221], v[80:83]
	v_mfma_f32_16x16x32_bf16 v[76:79], v[186:189], v[218:221], v[76:79]
	v_mfma_f32_16x16x32_bf16 v[68:71], v[178:181], v[226:229], v[68:71]
	v_mfma_f32_16x16x32_bf16 v[64:67], v[186:189], v[226:229], v[64:67]
	v_mfma_f32_16x16x32_bf16 v[108:111], v[182:185], v[198:201], v[108:111]
	v_mfma_f32_16x16x32_bf16 v[104:107], v[190:193], v[198:201], v[104:107]
	v_mfma_f32_16x16x32_bf16 v[100:103], v[182:185], v[214:217], v[100:103]
	v_mfma_f32_16x16x32_bf16 v[96:99], v[190:193], v[214:217], v[96:99]
	v_mfma_f32_16x16x32_bf16 v[80:83], v[182:185], v[222:225], v[80:83]
	v_mfma_f32_16x16x32_bf16 v[76:79], v[190:193], v[222:225], v[76:79]
	v_mfma_f32_16x16x32_bf16 v[68:71], v[182:185], v[230:233], v[68:71]
	v_mfma_f32_16x16x32_bf16 v[64:67], v[190:193], v[230:233], v[64:67]
	s_setprio 0
	s_barrier
	s_add_i32 s57, s49, s42
	v_lshl_add_u64 v[204:205], s[30:31], 0, v[134:135]
	s_mov_b32 m0, s57
	ds_read_b128 v[194:197], v172 offset:16384
	ds_read_b128 v[198:201], v172 offset:17408
	ds_read_b128 v[210:213], v172 offset:18432
	ds_read_b128 v[214:217], v172 offset:19456
	ds_read_b128 v[218:221], v172 offset:20480
	ds_read_b128 v[222:225], v172 offset:21504
	ds_read_b128 v[226:229], v172 offset:22528
	ds_read_b128 v[230:233], v172 offset:23552
	global_load_lds_dwordx4 v[204:205], off
	s_add_i32 m0, s57, 0x2000
	s_add_u32 s58, s30, 0x4000
	v_lshl_add_u64 v[204:205], s[30:31], 0, v[138:139]
	s_addc_u32 s59, s31, 0
	s_add_i32 s57, s50, s42
	global_load_lds_dwordx4 v[204:205], off
	v_lshl_add_u64 v[204:205], s[58:59], 0, v[134:135]
	s_mov_b32 m0, s57
	v_lshl_add_u64 v[206:207], s[34:35], 0, v[136:137]
	global_load_lds_dwordx4 v[204:205], off
	v_lshl_add_u64 v[204:205], s[58:59], 0, v[138:139]
	s_add_i32 m0, s57, 0x2000
	s_nop 0
	global_load_lds_dwordx4 v[204:205], off
	v_lshl_add_u64 v[204:205], s[34:35], 0, v[132:133]
	s_waitcnt vmcnt(6)
	s_waitcnt lgkmcnt(0)
	s_barrier
	s_setprio 1
	s_waitcnt lgkmcnt(0)
	v_mfma_f32_16x16x32_bf16 v[60:63], v[128:131], v[194:197], v[60:63]
	v_mfma_f32_16x16x32_bf16 v[56:59], v[152:155], v[194:197], v[56:59]
	v_mfma_f32_16x16x32_bf16 v[48:51], v[128:131], v[210:213], v[48:51]
	v_mfma_f32_16x16x32_bf16 v[40:43], v[152:155], v[210:213], v[40:43]
	v_mfma_f32_16x16x32_bf16 v[32:35], v[128:131], v[218:221], v[32:35]
	v_mfma_f32_16x16x32_bf16 v[24:27], v[152:155], v[218:221], v[24:27]
	v_mfma_f32_16x16x32_bf16 v[16:19], v[128:131], v[226:229], v[16:19]
	v_mfma_f32_16x16x32_bf16 v[8:11], v[152:155], v[226:229], v[8:11]
	v_mfma_f32_16x16x32_bf16 v[60:63], v[148:151], v[198:201], v[60:63]
	v_mfma_f32_16x16x32_bf16 v[56:59], v[174:177], v[198:201], v[56:59]
	v_mfma_f32_16x16x32_bf16 v[48:51], v[148:151], v[214:217], v[48:51]
	v_mfma_f32_16x16x32_bf16 v[40:43], v[174:177], v[214:217], v[40:43]
	v_mfma_f32_16x16x32_bf16 v[32:35], v[148:151], v[222:225], v[32:35]
	v_mfma_f32_16x16x32_bf16 v[24:27], v[174:177], v[222:225], v[24:27]
	v_mfma_f32_16x16x32_bf16 v[16:19], v[148:151], v[230:233], v[16:19]
	v_mfma_f32_16x16x32_bf16 v[8:11], v[174:177], v[230:233], v[8:11]
	s_setprio 0
	s_setprio 1
	v_mfma_f32_16x16x32_bf16 v[52:55], v[178:181], v[194:197], v[52:55]
	v_mfma_f32_16x16x32_bf16 v[44:47], v[186:189], v[194:197], v[44:47]
	v_mfma_f32_16x16x32_bf16 v[36:39], v[178:181], v[210:213], v[36:39]
	v_mfma_f32_16x16x32_bf16 v[28:31], v[186:189], v[210:213], v[28:31]
	v_mfma_f32_16x16x32_bf16 v[20:23], v[178:181], v[218:221], v[20:23]
	v_mfma_f32_16x16x32_bf16 v[12:15], v[186:189], v[218:221], v[12:15]
	v_mfma_f32_16x16x32_bf16 v[4:7], v[178:181], v[226:229], v[4:7]
	v_mfma_f32_16x16x32_bf16 v[0:3], v[186:189], v[226:229], v[0:3]
	v_mfma_f32_16x16x32_bf16 v[52:55], v[182:185], v[198:201], v[52:55]
	v_mfma_f32_16x16x32_bf16 v[44:47], v[190:193], v[198:201], v[44:47]
	v_mfma_f32_16x16x32_bf16 v[36:39], v[182:185], v[214:217], v[36:39]
	v_mfma_f32_16x16x32_bf16 v[28:31], v[190:193], v[214:217], v[28:31]
	v_mfma_f32_16x16x32_bf16 v[20:23], v[182:185], v[222:225], v[20:23]
	v_mfma_f32_16x16x32_bf16 v[12:15], v[190:193], v[222:225], v[12:15]
	v_mfma_f32_16x16x32_bf16 v[4:7], v[182:185], v[230:233], v[4:7]
	v_mfma_f32_16x16x32_bf16 v[0:3], v[190:193], v[230:233], v[0:3]
	s_setprio 0
	s_barrier
	s_mov_b32 m0, s25
	s_nop 0
	global_load_lds_dwordx4 v132, s[34:35]
	s_mov_b32 m0, s27
	s_nop 0
	global_load_lds_dwordx4 v136, s[34:35]
	s_add_i32 s57, 0, 0x18000
	v_add_u32_e32 v173, s57, v168
	s_add_i32 s58, 0, 0x1c000
	ds_read_b128 v[128:131], v173
	ds_read_b128 v[148:151], v173 offset:1024
	ds_read_b128 v[152:155], v173 offset:2048
	ds_read_b128 v[174:177], v173 offset:3072
	v_add_u32_e32 v173, s58, v168
	ds_read_b128 v[178:181], v173
	ds_read_b128 v[182:185], v173 offset:1024
	ds_read_b128 v[186:189], v173 offset:2048
	ds_read_b128 v[190:193], v173 offset:3072
	s_add_u32 s34, s34, 0x20000
	s_addc_u32 s35, s35, 0
	s_mov_b32 m0, s43
	v_lshl_add_u64 v[234:235], s[34:35], 0, v[132:133]
	ds_read_b128 v[194:197], v172 offset:32768
	ds_read_b128 v[198:201], v172 offset:33792
	ds_read_b128 v[210:213], v172 offset:34816
	ds_read_b128 v[214:217], v172 offset:35840
	ds_read_b128 v[218:221], v172 offset:36864
	ds_read_b128 v[222:225], v172 offset:37888
	ds_read_b128 v[226:229], v172 offset:38912
	ds_read_b128 v[230:233], v172 offset:39936
	global_load_lds_dwordx4 v[234:235], off
	v_lshl_add_u64 v[234:235], s[34:35], 0, v[136:137]
	s_mov_b32 m0, s44
	s_nop 0
	global_load_lds_dwordx4 v[234:235], off
	s_waitcnt vmcnt(8)
	s_waitcnt lgkmcnt(0)
	s_barrier
	s_setprio 1
	s_waitcnt lgkmcnt(0)
	v_mfma_f32_16x16x32_bf16 v[124:127], v[128:131], v[194:197], v[124:127]
	v_mfma_f32_16x16x32_bf16 v[120:123], v[152:155], v[194:197], v[120:123]
	v_mfma_f32_16x16x32_bf16 v[116:119], v[128:131], v[210:213], v[116:119]
	v_mfma_f32_16x16x32_bf16 v[112:115], v[152:155], v[210:213], v[112:115]
	v_mfma_f32_16x16x32_bf16 v[92:95], v[128:131], v[218:221], v[92:95]
	v_mfma_f32_16x16x32_bf16 v[88:91], v[152:155], v[218:221], v[88:91]
	v_mfma_f32_16x16x32_bf16 v[84:87], v[128:131], v[226:229], v[84:87]
	v_mfma_f32_16x16x32_bf16 v[72:75], v[152:155], v[226:229], v[72:75]
	v_mfma_f32_16x16x32_bf16 v[124:127], v[148:151], v[198:201], v[124:127]
	v_mfma_f32_16x16x32_bf16 v[120:123], v[174:177], v[198:201], v[120:123]
	v_mfma_f32_16x16x32_bf16 v[116:119], v[148:151], v[214:217], v[116:119]
	v_mfma_f32_16x16x32_bf16 v[112:115], v[174:177], v[214:217], v[112:115]
	v_mfma_f32_16x16x32_bf16 v[92:95], v[148:151], v[222:225], v[92:95]
	v_mfma_f32_16x16x32_bf16 v[88:91], v[174:177], v[222:225], v[88:91]
	v_mfma_f32_16x16x32_bf16 v[84:87], v[148:151], v[230:233], v[84:87]
	v_mfma_f32_16x16x32_bf16 v[72:75], v[174:177], v[230:233], v[72:75]
	s_setprio 0
	s_setprio 1
	v_mfma_f32_16x16x32_bf16 v[108:111], v[178:181], v[194:197], v[108:111]
	v_mfma_f32_16x16x32_bf16 v[104:107], v[186:189], v[194:197], v[104:107]
	v_mfma_f32_16x16x32_bf16 v[100:103], v[178:181], v[210:213], v[100:103]
	v_mfma_f32_16x16x32_bf16 v[96:99], v[186:189], v[210:213], v[96:99]
	v_mfma_f32_16x16x32_bf16 v[80:83], v[178:181], v[218:221], v[80:83]
	v_mfma_f32_16x16x32_bf16 v[76:79], v[186:189], v[218:221], v[76:79]
	v_mfma_f32_16x16x32_bf16 v[68:71], v[178:181], v[226:229], v[68:71]
	v_mfma_f32_16x16x32_bf16 v[64:67], v[186:189], v[226:229], v[64:67]
	v_mfma_f32_16x16x32_bf16 v[108:111], v[182:185], v[198:201], v[108:111]
	v_mfma_f32_16x16x32_bf16 v[104:107], v[190:193], v[198:201], v[104:107]
	v_mfma_f32_16x16x32_bf16 v[100:103], v[182:185], v[214:217], v[100:103]
	v_mfma_f32_16x16x32_bf16 v[96:99], v[190:193], v[214:217], v[96:99]
	v_mfma_f32_16x16x32_bf16 v[80:83], v[182:185], v[222:225], v[80:83]
	v_mfma_f32_16x16x32_bf16 v[76:79], v[190:193], v[222:225], v[76:79]
	v_mfma_f32_16x16x32_bf16 v[68:71], v[182:185], v[230:233], v[68:71]
	v_mfma_f32_16x16x32_bf16 v[64:67], v[190:193], v[230:233], v[64:67]
	s_setprio 0
	s_barrier
	s_add_u32 s34, s30, 0x8000
	s_addc_u32 s35, s31, 0
	s_add_i32 s57, s57, s42
	v_lshl_add_u64 v[234:235], s[34:35], 0, v[134:135]
	s_mov_b32 m0, s57
	ds_read_b128 v[194:197], v172 offset:49152
	ds_read_b128 v[198:201], v172 offset:50176
	ds_read_b128 v[210:213], v172 offset:51200
	ds_read_b128 v[214:217], v172 offset:52224
	ds_read_b128 v[218:221], v172 offset:53248
	ds_read_b128 v[222:225], v172 offset:54272
	ds_read_b128 v[226:229], v172 offset:55296
	ds_read_b128 v[230:233], v172 offset:56320
	global_load_lds_dwordx4 v[234:235], off
	s_add_i32 m0, s57, 0x2000
	s_add_u32 s30, s30, 0xc000
	v_lshl_add_u64 v[234:235], s[34:35], 0, v[138:139]
	s_addc_u32 s31, s31, 0
	s_add_i32 s34, s58, s42
	global_load_lds_dwordx4 v[234:235], off
	v_lshl_add_u64 v[234:235], s[30:31], 0, v[134:135]
	s_mov_b32 m0, s34
	v_lshl_add_u64 v[204:205], v[204:205], 0, s[12:13]
	global_load_lds_dwordx4 v[234:235], off
	v_lshl_add_u64 v[234:235], s[30:31], 0, v[138:139]
	s_add_i32 m0, s34, 0x2000
	s_nop 0
	global_load_lds_dwordx4 v[234:235], off
	s_mov_b32 m0, s46
	s_nop 0
	global_load_lds_dwordx4 v[204:205], off
	v_lshl_add_u64 v[204:205], v[206:207], 0, s[12:13]
	s_mov_b32 m0, s47
	s_nop 0
	global_load_lds_dwordx4 v[204:205], off
	s_waitcnt vmcnt(8)
	s_waitcnt lgkmcnt(0)
	s_barrier
	s_setprio 1
	s_waitcnt lgkmcnt(0)
	v_mfma_f32_16x16x32_bf16 v[60:63], v[128:131], v[194:197], v[60:63]
	v_mfma_f32_16x16x32_bf16 v[56:59], v[152:155], v[194:197], v[56:59]
	v_mfma_f32_16x16x32_bf16 v[48:51], v[128:131], v[210:213], v[48:51]
	v_mfma_f32_16x16x32_bf16 v[40:43], v[152:155], v[210:213], v[40:43]
	v_mfma_f32_16x16x32_bf16 v[32:35], v[128:131], v[218:221], v[32:35]
	v_mfma_f32_16x16x32_bf16 v[24:27], v[152:155], v[218:221], v[24:27]
	v_mfma_f32_16x16x32_bf16 v[16:19], v[128:131], v[226:229], v[16:19]
	v_mfma_f32_16x16x32_bf16 v[8:11], v[152:155], v[226:229], v[8:11]
	v_mfma_f32_16x16x32_bf16 v[60:63], v[148:151], v[198:201], v[60:63]
	v_mfma_f32_16x16x32_bf16 v[56:59], v[174:177], v[198:201], v[56:59]
	v_mfma_f32_16x16x32_bf16 v[48:51], v[148:151], v[214:217], v[48:51]
	v_mfma_f32_16x16x32_bf16 v[40:43], v[174:177], v[214:217], v[40:43]
	v_mfma_f32_16x16x32_bf16 v[32:35], v[148:151], v[222:225], v[32:35]
	v_mfma_f32_16x16x32_bf16 v[24:27], v[174:177], v[222:225], v[24:27]
	v_mfma_f32_16x16x32_bf16 v[16:19], v[148:151], v[230:233], v[16:19]
	v_mfma_f32_16x16x32_bf16 v[8:11], v[174:177], v[230:233], v[8:11]
	s_setprio 0
	s_setprio 1
	v_mfma_f32_16x16x32_bf16 v[52:55], v[178:181], v[194:197], v[52:55]
	v_mfma_f32_16x16x32_bf16 v[44:47], v[186:189], v[194:197], v[44:47]
	v_mfma_f32_16x16x32_bf16 v[36:39], v[178:181], v[210:213], v[36:39]
	v_mfma_f32_16x16x32_bf16 v[28:31], v[186:189], v[210:213], v[28:31]
	v_mfma_f32_16x16x32_bf16 v[20:23], v[178:181], v[218:221], v[20:23]
	v_mfma_f32_16x16x32_bf16 v[12:15], v[186:189], v[218:221], v[12:15]
	v_mfma_f32_16x16x32_bf16 v[4:7], v[178:181], v[226:229], v[4:7]
	v_mfma_f32_16x16x32_bf16 v[0:3], v[186:189], v[226:229], v[0:3]
	v_mfma_f32_16x16x32_bf16 v[52:55], v[182:185], v[198:201], v[52:55]
	v_mfma_f32_16x16x32_bf16 v[44:47], v[190:193], v[198:201], v[44:47]
	v_mfma_f32_16x16x32_bf16 v[36:39], v[182:185], v[214:217], v[36:39]
	v_mfma_f32_16x16x32_bf16 v[28:31], v[190:193], v[214:217], v[28:31]
	v_mfma_f32_16x16x32_bf16 v[20:23], v[182:185], v[222:225], v[20:23]
	v_mfma_f32_16x16x32_bf16 v[12:15], v[190:193], v[222:225], v[12:15]
	v_mfma_f32_16x16x32_bf16 v[4:7], v[182:185], v[230:233], v[4:7]
	v_mfma_f32_16x16x32_bf16 v[0:3], v[190:193], v[230:233], v[0:3]
	s_setprio 0
	s_barrier
	s_add_i32 s56, s56, 2
	s_add_u32 s54, s54, 0x10000
	s_addc_u32 s55, s55, 0
	s_add_u32 s28, s28, 0x100
	s_addc_u32 s29, s29, 0
	s_cmp_gt_u32 s56, 5
	s_cbranch_scc0 .LBB0_2258
	s_and_b64 vcc, exec, s[14:15]
	s_cbranch_vccz .LBB0_2261
	s_barrier

.LBB0_2282:
	ds_read_b128 v[144:147], v155
	ds_read_b128 v[148:151], v155 offset:1024
	ds_read_b128 v[158:161], v155 offset:2048
	ds_read_b128 v[162:165], v155 offset:3072
	ds_read_b128 v[166:169], v156
	ds_read_b128 v[170:173], v156 offset:1024
	ds_read_b128 v[174:177], v156 offset:2048
	ds_read_b128 v[178:181], v156 offset:3072
	s_add_u32 s28, s26, 0xfffe0080
	s_addc_u32 s29, s27, -1
	s_cmp_eq_u32 s54, 4
	s_cselect_b32 s31, s15, s29
	s_cselect_b32 s30, s50, s28
	s_cselect_b32 s29, s17, s53
	s_cselect_b32 s28, s51, s52
	v_lshl_add_u64 v[204:205], s[26:27], 0, v[130:131]
	s_add_i32 m0, s23, 0xc000
	ds_read_b128 v[182:185], v157
	ds_read_b128 v[186:189], v157 offset:1024
	ds_read_b128 v[190:193], v157 offset:2048
	ds_read_b128 v[194:197], v157 offset:3072
	ds_read_b128 v[198:201], v157 offset:4096
	ds_read_b128 v[210:213], v157 offset:5120
	ds_read_b128 v[214:217], v157 offset:6144
	ds_read_b128 v[218:221], v157 offset:7168
	global_load_lds_dwordx4 v[204:205], off
	v_lshl_add_u64 v[204:205], s[26:27], 0, v[128:129]
	s_add_i32 m0, s23, 0xe000
	s_nop 0
	global_load_lds_dwordx4 v[204:205], off
	s_waitcnt vmcnt(8)
	s_waitcnt lgkmcnt(0)
	s_barrier
	s_setprio 1
	s_waitcnt lgkmcnt(0)
	v_mfma_f32_16x16x32_bf16 v[124:127], v[144:147], v[182:185], v[124:127]
	v_mfma_f32_16x16x32_bf16 v[120:123], v[158:161], v[182:185], v[120:123]
	v_mfma_f32_16x16x32_bf16 v[112:115], v[144:147], v[190:193], v[112:115]
	v_mfma_f32_16x16x32_bf16 v[104:107], v[158:161], v[190:193], v[104:107]
	v_mfma_f32_16x16x32_bf16 v[92:95], v[144:147], v[198:201], v[92:95]
	v_mfma_f32_16x16x32_bf16 v[88:91], v[158:161], v[198:201], v[88:91]
	v_mfma_f32_16x16x32_bf16 v[80:83], v[144:147], v[214:217], v[80:83]
	v_mfma_f32_16x16x32_bf16 v[72:75], v[158:161], v[214:217], v[72:75]
	v_mfma_f32_16x16x32_bf16 v[124:127], v[148:151], v[186:189], v[124:127]
	v_mfma_f32_16x16x32_bf16 v[120:123], v[162:165], v[186:189], v[120:123]
	v_mfma_f32_16x16x32_bf16 v[112:115], v[148:151], v[194:197], v[112:115]
	v_mfma_f32_16x16x32_bf16 v[104:107], v[162:165], v[194:197], v[104:107]
	v_mfma_f32_16x16x32_bf16 v[92:95], v[148:151], v[210:213], v[92:95]
	v_mfma_f32_16x16x32_bf16 v[88:91], v[162:165], v[210:213], v[88:91]
	v_mfma_f32_16x16x32_bf16 v[80:83], v[148:151], v[218:221], v[80:83]
	v_mfma_f32_16x16x32_bf16 v[72:75], v[162:165], v[218:221], v[72:75]
	s_setprio 0
	s_setprio 1
	v_mfma_f32_16x16x32_bf16 v[116:119], v[166:169], v[182:185], v[116:119]
	v_mfma_f32_16x16x32_bf16 v[108:111], v[174:177], v[182:185], v[108:111]
	v_mfma_f32_16x16x32_bf16 v[100:103], v[166:169], v[190:193], v[100:103]
	v_mfma_f32_16x16x32_bf16 v[96:99], v[174:177], v[190:193], v[96:99]
	v_mfma_f32_16x16x32_bf16 v[84:87], v[166:169], v[198:201], v[84:87]
	v_mfma_f32_16x16x32_bf16 v[76:79], v[174:177], v[198:201], v[76:79]
	v_mfma_f32_16x16x32_bf16 v[68:71], v[166:169], v[214:217], v[68:71]
	v_mfma_f32_16x16x32_bf16 v[64:67], v[174:177], v[214:217], v[64:67]
	v_mfma_f32_16x16x32_bf16 v[116:119], v[170:173], v[186:189], v[116:119]
	v_mfma_f32_16x16x32_bf16 v[108:111], v[178:181], v[186:189], v[108:111]
	v_mfma_f32_16x16x32_bf16 v[100:103], v[170:173], v[194:197], v[100:103]
	v_mfma_f32_16x16x32_bf16 v[96:99], v[178:181], v[194:197], v[96:99]
	v_mfma_f32_16x16x32_bf16 v[84:87], v[170:173], v[210:213], v[84:87]
	v_mfma_f32_16x16x32_bf16 v[76:79], v[178:181], v[210:213], v[76:79]
	v_mfma_f32_16x16x32_bf16 v[68:71], v[170:173], v[218:221], v[68:71]
	v_mfma_f32_16x16x32_bf16 v[64:67], v[178:181], v[218:221], v[64:67]
	s_setprio 0
	s_barrier
	s_add_i32 s55, s47, s40
	v_lshl_add_u64 v[204:205], s[28:29], 0, v[134:135]
	s_mov_b32 m0, s55
	ds_read_b128 v[182:185], v157 offset:16384
	ds_read_b128 v[186:189], v157 offset:17408
	ds_read_b128 v[190:193], v157 offset:18432
	ds_read_b128 v[194:197], v157 offset:19456
	ds_read_b128 v[198:201], v157 offset:20480
	ds_read_b128 v[210:213], v157 offset:21504
	ds_read_b128 v[214:217], v157 offset:22528
	ds_read_b128 v[218:221], v157 offset:23552
	global_load_lds_dwordx4 v[204:205], off
	s_add_i32 m0, s55, 0x2000
	s_add_u32 s56, s28, 0x4000
	v_lshl_add_u64 v[204:205], s[28:29], 0, v[138:139]
	s_addc_u32 s57, s29, 0
	s_add_i32 s55, s48, s40
	global_load_lds_dwordx4 v[204:205], off
	v_lshl_add_u64 v[204:205], s[56:57], 0, v[134:135]
	s_mov_b32 m0, s55
	v_lshl_add_u64 v[206:207], s[30:31], 0, v[136:137]
	global_load_lds_dwordx4 v[204:205], off
	v_lshl_add_u64 v[204:205], s[56:57], 0, v[138:139]
	s_add_i32 m0, s55, 0x2000
	s_nop 0
	global_load_lds_dwordx4 v[204:205], off
	v_lshl_add_u64 v[204:205], s[30:31], 0, v[132:133]
	s_waitcnt vmcnt(6)
	s_waitcnt lgkmcnt(0)
	s_barrier
	s_setprio 1
	s_waitcnt lgkmcnt(0)
	v_mfma_f32_16x16x32_bf16 v[60:63], v[144:147], v[182:185], v[60:63]
	v_mfma_f32_16x16x32_bf16 v[56:59], v[158:161], v[182:185], v[56:59]
	v_mfma_f32_16x16x32_bf16 v[48:51], v[144:147], v[190:193], v[48:51]
	v_mfma_f32_16x16x32_bf16 v[40:43], v[158:161], v[190:193], v[40:43]
	v_mfma_f32_16x16x32_bf16 v[28:31], v[144:147], v[198:201], v[28:31]
	v_mfma_f32_16x16x32_bf16 v[24:27], v[158:161], v[198:201], v[24:27]
	v_mfma_f32_16x16x32_bf16 v[16:19], v[144:147], v[214:217], v[16:19]
	v_mfma_f32_16x16x32_bf16 v[8:11], v[158:161], v[214:217], v[8:11]
	v_mfma_f32_16x16x32_bf16 v[60:63], v[148:151], v[186:189], v[60:63]
	v_mfma_f32_16x16x32_bf16 v[56:59], v[162:165], v[186:189], v[56:59]
	v_mfma_f32_16x16x32_bf16 v[48:51], v[148:151], v[194:197], v[48:51]
	v_mfma_f32_16x16x32_bf16 v[40:43], v[162:165], v[194:197], v[40:43]
	v_mfma_f32_16x16x32_bf16 v[28:31], v[148:151], v[210:213], v[28:31]
	v_mfma_f32_16x16x32_bf16 v[24:27], v[162:165], v[210:213], v[24:27]
	v_mfma_f32_16x16x32_bf16 v[16:19], v[148:151], v[218:221], v[16:19]
	v_mfma_f32_16x16x32_bf16 v[8:11], v[162:165], v[218:221], v[8:11]
	s_setprio 0
	s_setprio 1
	v_mfma_f32_16x16x32_bf16 v[52:55], v[166:169], v[182:185], v[52:55]
	v_mfma_f32_16x16x32_bf16 v[44:47], v[174:177], v[182:185], v[44:47]
	v_mfma_f32_16x16x32_bf16 v[36:39], v[166:169], v[190:193], v[36:39]
	v_mfma_f32_16x16x32_bf16 v[32:35], v[174:177], v[190:193], v[32:35]
	v_mfma_f32_16x16x32_bf16 v[20:23], v[166:169], v[198:201], v[20:23]
	v_mfma_f32_16x16x32_bf16 v[12:15], v[174:177], v[198:201], v[12:15]
	v_mfma_f32_16x16x32_bf16 v[4:7], v[166:169], v[214:217], v[4:7]
	v_mfma_f32_16x16x32_bf16 v[0:3], v[174:177], v[214:217], v[0:3]
	v_mfma_f32_16x16x32_bf16 v[52:55], v[170:173], v[186:189], v[52:55]
	v_mfma_f32_16x16x32_bf16 v[44:47], v[178:181], v[186:189], v[44:47]
	v_mfma_f32_16x16x32_bf16 v[36:39], v[170:173], v[194:197], v[36:39]
	v_mfma_f32_16x16x32_bf16 v[32:35], v[178:181], v[194:197], v[32:35]
	v_mfma_f32_16x16x32_bf16 v[20:23], v[170:173], v[210:213], v[20:23]
	v_mfma_f32_16x16x32_bf16 v[12:15], v[178:181], v[210:213], v[12:15]
	v_mfma_f32_16x16x32_bf16 v[4:7], v[170:173], v[218:221], v[4:7]
	v_mfma_f32_16x16x32_bf16 v[0:3], v[178:181], v[218:221], v[0:3]
	s_setprio 0
	s_barrier
	s_mov_b32 m0, s23
	s_nop 0
	global_load_lds_dwordx4 v132, s[30:31]
	s_mov_b32 m0, s25
	s_nop 0
	global_load_lds_dwordx4 v136, s[30:31]
	s_add_i32 s55, 0, 0x18000
	s_add_i32 s56, 0, 0x1c000
	v_add_u32_e32 v162, s55, v153
	v_add_u32_e32 v178, s56, v153
	ds_read_b128 v[144:147], v162
	ds_read_b128 v[148:151], v162 offset:1024
	ds_read_b128 v[158:161], v162 offset:2048
	ds_read_b128 v[162:165], v162 offset:3072
	ds_read_b128 v[166:169], v178
	ds_read_b128 v[170:173], v178 offset:1024
	ds_read_b128 v[174:177], v178 offset:2048
	ds_read_b128 v[178:181], v178 offset:3072
	s_add_u32 s30, s30, 0x20000
	s_addc_u32 s31, s31, 0
	s_mov_b32 m0, s41
	v_lshl_add_u64 v[222:223], s[30:31], 0, v[132:133]
	ds_read_b128 v[182:185], v157 offset:32768
	ds_read_b128 v[186:189], v157 offset:33792
	ds_read_b128 v[190:193], v157 offset:34816
	ds_read_b128 v[194:197], v157 offset:35840
	ds_read_b128 v[198:201], v157 offset:36864
	ds_read_b128 v[210:213], v157 offset:37888
	ds_read_b128 v[214:217], v157 offset:38912
	ds_read_b128 v[218:221], v157 offset:39936
	global_load_lds_dwordx4 v[222:223], off
	v_lshl_add_u64 v[222:223], s[30:31], 0, v[136:137]
	s_mov_b32 m0, s42
	s_nop 0
	global_load_lds_dwordx4 v[222:223], off
	s_waitcnt vmcnt(8)
	s_waitcnt lgkmcnt(0)
	s_barrier
	s_setprio 1
	s_waitcnt lgkmcnt(0)
	v_mfma_f32_16x16x32_bf16 v[124:127], v[144:147], v[182:185], v[124:127]
	v_mfma_f32_16x16x32_bf16 v[120:123], v[158:161], v[182:185], v[120:123]
	v_mfma_f32_16x16x32_bf16 v[112:115], v[144:147], v[190:193], v[112:115]
	v_mfma_f32_16x16x32_bf16 v[104:107], v[158:161], v[190:193], v[104:107]
	v_mfma_f32_16x16x32_bf16 v[92:95], v[144:147], v[198:201], v[92:95]
	v_mfma_f32_16x16x32_bf16 v[88:91], v[158:161], v[198:201], v[88:91]
	v_mfma_f32_16x16x32_bf16 v[80:83], v[144:147], v[214:217], v[80:83]
	v_mfma_f32_16x16x32_bf16 v[72:75], v[158:161], v[214:217], v[72:75]
	v_mfma_f32_16x16x32_bf16 v[124:127], v[148:151], v[186:189], v[124:127]
	v_mfma_f32_16x16x32_bf16 v[120:123], v[162:165], v[186:189], v[120:123]
	v_mfma_f32_16x16x32_bf16 v[112:115], v[148:151], v[194:197], v[112:115]
	v_mfma_f32_16x16x32_bf16 v[104:107], v[162:165], v[194:197], v[104:107]
	v_mfma_f32_16x16x32_bf16 v[92:95], v[148:151], v[210:213], v[92:95]
	v_mfma_f32_16x16x32_bf16 v[88:91], v[162:165], v[210:213], v[88:91]
	v_mfma_f32_16x16x32_bf16 v[80:83], v[148:151], v[218:221], v[80:83]
	v_mfma_f32_16x16x32_bf16 v[72:75], v[162:165], v[218:221], v[72:75]
	s_setprio 0
	s_setprio 1
	v_mfma_f32_16x16x32_bf16 v[116:119], v[166:169], v[182:185], v[116:119]
	v_mfma_f32_16x16x32_bf16 v[108:111], v[174:177], v[182:185], v[108:111]
	v_mfma_f32_16x16x32_bf16 v[100:103], v[166:169], v[190:193], v[100:103]
	v_mfma_f32_16x16x32_bf16 v[96:99], v[174:177], v[190:193], v[96:99]
	v_mfma_f32_16x16x32_bf16 v[84:87], v[166:169], v[198:201], v[84:87]
	v_mfma_f32_16x16x32_bf16 v[76:79], v[174:177], v[198:201], v[76:79]
	v_mfma_f32_16x16x32_bf16 v[68:71], v[166:169], v[214:217], v[68:71]
	v_mfma_f32_16x16x32_bf16 v[64:67], v[174:177], v[214:217], v[64:67]
	v_mfma_f32_16x16x32_bf16 v[116:119], v[170:173], v[186:189], v[116:119]
	v_mfma_f32_16x16x32_bf16 v[108:111], v[178:181], v[186:189], v[108:111]
	v_mfma_f32_16x16x32_bf16 v[100:103], v[170:173], v[194:197], v[100:103]
	v_mfma_f32_16x16x32_bf16 v[96:99], v[178:181], v[194:197], v[96:99]
	v_mfma_f32_16x16x32_bf16 v[84:87], v[170:173], v[210:213], v[84:87]
	v_mfma_f32_16x16x32_bf16 v[76:79], v[178:181], v[210:213], v[76:79]
	v_mfma_f32_16x16x32_bf16 v[68:71], v[170:173], v[218:221], v[68:71]
	v_mfma_f32_16x16x32_bf16 v[64:67], v[178:181], v[218:221], v[64:67]
	s_setprio 0
	s_barrier
	s_add_u32 s30, s28, 0x8000
	s_addc_u32 s31, s29, 0
	s_add_i32 s55, s55, s40
	v_lshl_add_u64 v[222:223], s[30:31], 0, v[134:135]
	s_mov_b32 m0, s55
	ds_read_b128 v[182:185], v157 offset:49152
	ds_read_b128 v[186:189], v157 offset:50176
	ds_read_b128 v[190:193], v157 offset:51200
	ds_read_b128 v[194:197], v157 offset:52224
	ds_read_b128 v[198:201], v157 offset:53248
	ds_read_b128 v[210:213], v157 offset:54272
	ds_read_b128 v[214:217], v157 offset:55296
	ds_read_b128 v[218:221], v157 offset:56320
	global_load_lds_dwordx4 v[222:223], off
	s_add_i32 m0, s55, 0x2000
	s_add_u32 s28, s28, 0xc000
	v_lshl_add_u64 v[222:223], s[30:31], 0, v[138:139]
	s_addc_u32 s29, s29, 0
	s_add_i32 s30, s56, s40
	global_load_lds_dwordx4 v[222:223], off
	v_lshl_add_u64 v[222:223], s[28:29], 0, v[134:135]
	s_mov_b32 m0, s30
	v_lshl_add_u64 v[204:205], v[204:205], 0, s[8:9]
	global_load_lds_dwordx4 v[222:223], off
	v_lshl_add_u64 v[222:223], s[28:29], 0, v[138:139]
	s_add_i32 m0, s30, 0x2000
	s_nop 0
	global_load_lds_dwordx4 v[222:223], off
	s_mov_b32 m0, s44
	s_nop 0
	global_load_lds_dwordx4 v[204:205], off
	v_lshl_add_u64 v[204:205], v[206:207], 0, s[8:9]
	s_mov_b32 m0, s45
	s_nop 0
	global_load_lds_dwordx4 v[204:205], off
	s_waitcnt vmcnt(8)
	s_waitcnt lgkmcnt(0)
	s_barrier
	s_setprio 1
	s_waitcnt lgkmcnt(0)
	v_mfma_f32_16x16x32_bf16 v[60:63], v[144:147], v[182:185], v[60:63]
	v_mfma_f32_16x16x32_bf16 v[56:59], v[158:161], v[182:185], v[56:59]
	v_mfma_f32_16x16x32_bf16 v[48:51], v[144:147], v[190:193], v[48:51]
	v_mfma_f32_16x16x32_bf16 v[40:43], v[158:161], v[190:193], v[40:43]
	v_mfma_f32_16x16x32_bf16 v[28:31], v[144:147], v[198:201], v[28:31]
	v_mfma_f32_16x16x32_bf16 v[24:27], v[158:161], v[198:201], v[24:27]
	v_mfma_f32_16x16x32_bf16 v[16:19], v[144:147], v[214:217], v[16:19]
	v_mfma_f32_16x16x32_bf16 v[8:11], v[158:161], v[214:217], v[8:11]
	v_mfma_f32_16x16x32_bf16 v[60:63], v[148:151], v[186:189], v[60:63]
	v_mfma_f32_16x16x32_bf16 v[56:59], v[162:165], v[186:189], v[56:59]
	v_mfma_f32_16x16x32_bf16 v[48:51], v[148:151], v[194:197], v[48:51]
	v_mfma_f32_16x16x32_bf16 v[40:43], v[162:165], v[194:197], v[40:43]
	v_mfma_f32_16x16x32_bf16 v[28:31], v[148:151], v[210:213], v[28:31]
	v_mfma_f32_16x16x32_bf16 v[24:27], v[162:165], v[210:213], v[24:27]
	v_mfma_f32_16x16x32_bf16 v[16:19], v[148:151], v[218:221], v[16:19]
	v_mfma_f32_16x16x32_bf16 v[8:11], v[162:165], v[218:221], v[8:11]
	s_setprio 0
	s_setprio 1
	v_mfma_f32_16x16x32_bf16 v[52:55], v[166:169], v[182:185], v[52:55]
	v_mfma_f32_16x16x32_bf16 v[44:47], v[174:177], v[182:185], v[44:47]
	v_mfma_f32_16x16x32_bf16 v[36:39], v[166:169], v[190:193], v[36:39]
	v_mfma_f32_16x16x32_bf16 v[32:35], v[174:177], v[190:193], v[32:35]
	v_mfma_f32_16x16x32_bf16 v[20:23], v[166:169], v[198:201], v[20:23]
	v_mfma_f32_16x16x32_bf16 v[12:15], v[174:177], v[198:201], v[12:15]
	v_mfma_f32_16x16x32_bf16 v[4:7], v[166:169], v[214:217], v[4:7]
	v_mfma_f32_16x16x32_bf16 v[0:3], v[174:177], v[214:217], v[0:3]
	v_mfma_f32_16x16x32_bf16 v[52:55], v[170:173], v[186:189], v[52:55]
	v_mfma_f32_16x16x32_bf16 v[44:47], v[178:181], v[186:189], v[44:47]
	v_mfma_f32_16x16x32_bf16 v[36:39], v[170:173], v[194:197], v[36:39]
	v_mfma_f32_16x16x32_bf16 v[32:35], v[178:181], v[194:197], v[32:35]
	v_mfma_f32_16x16x32_bf16 v[20:23], v[170:173], v[210:213], v[20:23]
	v_mfma_f32_16x16x32_bf16 v[12:15], v[178:181], v[210:213], v[12:15]
	v_mfma_f32_16x16x32_bf16 v[4:7], v[170:173], v[218:221], v[4:7]
	v_mfma_f32_16x16x32_bf16 v[0:3], v[178:181], v[218:221], v[0:3]
	s_setprio 0
	s_barrier
	s_add_i32 s54, s54, 2
	s_add_u32 s52, s52, 0x10000
	s_addc_u32 s53, s53, 0
	s_add_u32 s26, s26, 0x100
	s_addc_u32 s27, s27, 0
	s_cmp_gt_u32 s54, 5
	s_cbranch_scc0 .LBB0_2282
	s_and_b64 vcc, exec, s[10:11]
	s_cbranch_vccz .LBB0_2285
	s_barrier

.LBB0_2358:
	v_add_u32_e32 v168, s77, v182
	v_add_u32_e32 v204, s78, v182
	ds_read_b128 v[156:159], v168
	ds_read_b128 v[160:163], v168 offset:1024
	ds_read_b128 v[164:167], v168 offset:2048
	ds_read_b128 v[168:171], v168 offset:3072
	ds_read_b128 v[172:175], v204
	ds_read_b128 v[176:179], v204 offset:1024
	ds_read_b128 v[212:215], v204 offset:2048
	ds_read_b128 v[216:219], v204 offset:3072
	s_add_u32 s48, s46, 0xfffc0080
	s_addc_u32 s49, s47, -1
	s_cmp_eq_u32 s54, 12
	s_cselect_b32 s51, s35, s49
	s_cselect_b32 s50, s43, s48
	s_cselect_b32 s49, s37, s53
	s_cselect_b32 s48, s45, s52
	v_lshl_add_u64 v[204:205], s[46:47], 0, v[154:155]
	s_add_i32 m0, s65, 0xc000
	ds_read_b128 v[220:223], v199
	ds_read_b128 v[224:227], v199 offset:1024
	ds_read_b128 v[228:231], v199 offset:2048
	ds_read_b128 v[232:235], v199 offset:3072
	ds_read_b128 v[236:239], v199 offset:4096
	ds_read_b128 v[240:243], v199 offset:5120
	ds_read_b128 v[244:247], v199 offset:6144
	ds_read_b128 v[248:251], v199 offset:7168
	global_load_lds_dwordx4 v[204:205], off
	v_lshl_add_u64 v[204:205], s[46:47], 0, v[152:153]
	s_add_i32 m0, s65, 0xe000
	s_nop 0
	global_load_lds_dwordx4 v[204:205], off
	s_waitcnt vmcnt(8)
	s_waitcnt lgkmcnt(0)
	s_barrier
	s_setprio 1
	s_waitcnt lgkmcnt(0)
	v_mfma_f32_16x16x32_bf16 v[124:127], v[156:159], v[220:223], v[124:127]
	v_mfma_f32_16x16x32_bf16 v[120:123], v[164:167], v[220:223], v[120:123]
	v_mfma_f32_16x16x32_bf16 v[116:119], v[156:159], v[228:231], v[116:119]
	v_mfma_f32_16x16x32_bf16 v[112:115], v[164:167], v[228:231], v[112:115]
	v_mfma_f32_16x16x32_bf16 v[92:95], v[156:159], v[236:239], v[92:95]
	v_mfma_f32_16x16x32_bf16 v[88:91], v[164:167], v[236:239], v[88:91]
	v_mfma_f32_16x16x32_bf16 v[84:87], v[156:159], v[244:247], v[84:87]
	v_mfma_f32_16x16x32_bf16 v[80:83], v[164:167], v[244:247], v[80:83]
	v_mfma_f32_16x16x32_bf16 v[124:127], v[160:163], v[224:227], v[124:127]
	v_mfma_f32_16x16x32_bf16 v[120:123], v[168:171], v[224:227], v[120:123]
	v_mfma_f32_16x16x32_bf16 v[116:119], v[160:163], v[232:235], v[116:119]
	v_mfma_f32_16x16x32_bf16 v[112:115], v[168:171], v[232:235], v[112:115]
	v_mfma_f32_16x16x32_bf16 v[92:95], v[160:163], v[240:243], v[92:95]
	v_mfma_f32_16x16x32_bf16 v[88:91], v[168:171], v[240:243], v[88:91]
	v_mfma_f32_16x16x32_bf16 v[84:87], v[160:163], v[248:251], v[84:87]
	v_mfma_f32_16x16x32_bf16 v[80:83], v[168:171], v[248:251], v[80:83]
	s_setprio 0
	s_setprio 1
	v_mfma_f32_16x16x32_bf16 v[108:111], v[172:175], v[220:223], v[108:111]
	v_mfma_f32_16x16x32_bf16 v[104:107], v[212:215], v[220:223], v[104:107]
	v_mfma_f32_16x16x32_bf16 v[100:103], v[172:175], v[228:231], v[100:103]
	v_mfma_f32_16x16x32_bf16 v[96:99], v[212:215], v[228:231], v[96:99]
	v_mfma_f32_16x16x32_bf16 v[76:79], v[172:175], v[236:239], v[76:79]
	v_mfma_f32_16x16x32_bf16 v[72:75], v[212:215], v[236:239], v[72:75]
	v_mfma_f32_16x16x32_bf16 v[68:71], v[172:175], v[244:247], v[68:71]
	v_mfma_f32_16x16x32_bf16 v[64:67], v[212:215], v[244:247], v[64:67]
	v_mfma_f32_16x16x32_bf16 v[108:111], v[176:179], v[224:227], v[108:111]
	v_mfma_f32_16x16x32_bf16 v[104:107], v[216:219], v[224:227], v[104:107]
	v_mfma_f32_16x16x32_bf16 v[100:103], v[176:179], v[232:235], v[100:103]
	v_mfma_f32_16x16x32_bf16 v[96:99], v[216:219], v[232:235], v[96:99]
	v_mfma_f32_16x16x32_bf16 v[76:79], v[176:179], v[240:243], v[76:79]
	v_mfma_f32_16x16x32_bf16 v[72:75], v[216:219], v[240:243], v[72:75]
	v_mfma_f32_16x16x32_bf16 v[68:71], v[176:179], v[248:251], v[68:71]
	v_mfma_f32_16x16x32_bf16 v[64:67], v[216:219], v[248:251], v[64:67]
	s_setprio 0
	s_barrier
	s_add_i32 s55, s77, s64
	v_lshl_add_u64 v[204:205], s[48:49], 0, v[130:131]
	s_mov_b32 m0, s55
	ds_read_b128 v[220:223], v199 offset:16384
	ds_read_b128 v[224:227], v199 offset:17408
	ds_read_b128 v[228:231], v199 offset:18432
	ds_read_b128 v[232:235], v199 offset:19456
	ds_read_b128 v[236:239], v199 offset:20480
	ds_read_b128 v[240:243], v199 offset:21504
	ds_read_b128 v[244:247], v199 offset:22528
	ds_read_b128 v[248:251], v199 offset:23552
	global_load_lds_dwordx4 v[204:205], off
	s_add_i32 m0, s55, 0x2000
	s_add_u32 s56, s48, 0x4000
	v_lshl_add_u64 v[204:205], s[48:49], 0, v[134:135]
	s_addc_u32 s57, s49, 0
	s_add_i32 s55, s78, s64
	global_load_lds_dwordx4 v[204:205], off
	v_lshl_add_u64 v[204:205], s[56:57], 0, v[130:131]
	s_mov_b32 m0, s55
	v_lshl_add_u64 v[206:207], s[50:51], 0, v[132:133]
	global_load_lds_dwordx4 v[204:205], off
	v_lshl_add_u64 v[204:205], s[56:57], 0, v[134:135]
	s_add_i32 m0, s55, 0x2000
	s_nop 0
	global_load_lds_dwordx4 v[204:205], off
	v_lshl_add_u64 v[204:205], s[50:51], 0, v[128:129]
	s_waitcnt vmcnt(6)
	s_waitcnt lgkmcnt(0)
	s_barrier
	s_setprio 1
	s_waitcnt lgkmcnt(0)
	v_mfma_f32_16x16x32_bf16 v[60:63], v[156:159], v[220:223], v[60:63]
	v_mfma_f32_16x16x32_bf16 v[56:59], v[164:167], v[220:223], v[56:59]
	v_mfma_f32_16x16x32_bf16 v[52:55], v[156:159], v[228:231], v[52:55]
	v_mfma_f32_16x16x32_bf16 v[48:51], v[164:167], v[228:231], v[48:51]
	v_mfma_f32_16x16x32_bf16 v[28:31], v[156:159], v[236:239], v[28:31]
	v_mfma_f32_16x16x32_bf16 v[24:27], v[164:167], v[236:239], v[24:27]
	v_mfma_f32_16x16x32_bf16 v[20:23], v[156:159], v[244:247], v[20:23]
	v_mfma_f32_16x16x32_bf16 v[12:15], v[164:167], v[244:247], v[12:15]
	v_mfma_f32_16x16x32_bf16 v[60:63], v[160:163], v[224:227], v[60:63]
	v_mfma_f32_16x16x32_bf16 v[56:59], v[168:171], v[224:227], v[56:59]
	v_mfma_f32_16x16x32_bf16 v[52:55], v[160:163], v[232:235], v[52:55]
	v_mfma_f32_16x16x32_bf16 v[48:51], v[168:171], v[232:235], v[48:51]
	v_mfma_f32_16x16x32_bf16 v[28:31], v[160:163], v[240:243], v[28:31]
	v_mfma_f32_16x16x32_bf16 v[24:27], v[168:171], v[240:243], v[24:27]
	v_mfma_f32_16x16x32_bf16 v[20:23], v[160:163], v[248:251], v[20:23]
	v_mfma_f32_16x16x32_bf16 v[12:15], v[168:171], v[248:251], v[12:15]
	s_setprio 0
	s_setprio 1
	v_mfma_f32_16x16x32_bf16 v[44:47], v[172:175], v[220:223], v[44:47]
	v_mfma_f32_16x16x32_bf16 v[40:43], v[212:215], v[220:223], v[40:43]
	v_mfma_f32_16x16x32_bf16 v[36:39], v[172:175], v[228:231], v[36:39]
	v_mfma_f32_16x16x32_bf16 v[32:35], v[212:215], v[228:231], v[32:35]
	v_mfma_f32_16x16x32_bf16 v[16:19], v[172:175], v[236:239], v[16:19]
	v_mfma_f32_16x16x32_bf16 v[8:11], v[212:215], v[236:239], v[8:11]
	v_mfma_f32_16x16x32_bf16 v[4:7], v[172:175], v[244:247], v[4:7]
	v_mfma_f32_16x16x32_bf16 v[0:3], v[212:215], v[244:247], v[0:3]
	v_mfma_f32_16x16x32_bf16 v[44:47], v[176:179], v[224:227], v[44:47]
	v_mfma_f32_16x16x32_bf16 v[40:43], v[216:219], v[224:227], v[40:43]
	v_mfma_f32_16x16x32_bf16 v[36:39], v[176:179], v[232:235], v[36:39]
	v_mfma_f32_16x16x32_bf16 v[32:35], v[216:219], v[232:235], v[32:35]
	v_mfma_f32_16x16x32_bf16 v[16:19], v[176:179], v[240:243], v[16:19]
	v_mfma_f32_16x16x32_bf16 v[8:11], v[216:219], v[240:243], v[8:11]
	v_mfma_f32_16x16x32_bf16 v[4:7], v[176:179], v[248:251], v[4:7]
	v_mfma_f32_16x16x32_bf16 v[0:3], v[216:219], v[248:251], v[0:3]
	s_setprio 0
	s_barrier
	s_mov_b32 m0, s65
	s_nop 0
	global_load_lds_dwordx4 v128, s[50:51]
	s_mov_b32 m0, s66
	s_nop 0
	global_load_lds_dwordx4 v132, s[50:51]
	s_add_i32 s55, 0, 0x18000
	s_add_i32 s56, 0, 0x1c000
	v_add_u32_e32 v168, s55, v182
	v_add_u32_e32 v216, s56, v182
	ds_read_b128 v[156:159], v168
	ds_read_b128 v[160:163], v168 offset:1024
	ds_read_b128 v[164:167], v168 offset:2048
	ds_read_b128 v[168:171], v168 offset:3072
	ds_read_b128 v[172:175], v216
	ds_read_b128 v[176:179], v216 offset:1024
	ds_read_b128 v[212:215], v216 offset:2048
	ds_read_b128 v[216:219], v216 offset:3072
	s_add_u32 s50, s50, 0x40000
	s_addc_u32 s51, s51, 0
	s_mov_b32 m0, s67
	v_lshl_add_u64 v[252:253], s[50:51], 0, v[128:129]
	ds_read_b128 v[220:223], v199 offset:32768
	ds_read_b128 v[224:227], v199 offset:33792
	ds_read_b128 v[228:231], v199 offset:34816
	ds_read_b128 v[232:235], v199 offset:35840
	ds_read_b128 v[236:239], v199 offset:36864
	ds_read_b128 v[240:243], v199 offset:37888
	ds_read_b128 v[244:247], v199 offset:38912
	ds_read_b128 v[248:251], v199 offset:39936
	global_load_lds_dwordx4 v[252:253], off
	v_lshl_add_u64 v[252:253], s[50:51], 0, v[132:133]
	s_mov_b32 m0, s68
	s_nop 0
	global_load_lds_dwordx4 v[252:253], off
	s_waitcnt vmcnt(8)
	s_waitcnt lgkmcnt(0)
	s_barrier
	s_setprio 1
	s_waitcnt lgkmcnt(0)
	v_mfma_f32_16x16x32_bf16 v[124:127], v[156:159], v[220:223], v[124:127]
	v_mfma_f32_16x16x32_bf16 v[120:123], v[164:167], v[220:223], v[120:123]
	v_mfma_f32_16x16x32_bf16 v[116:119], v[156:159], v[228:231], v[116:119]
	v_mfma_f32_16x16x32_bf16 v[112:115], v[164:167], v[228:231], v[112:115]
	v_mfma_f32_16x16x32_bf16 v[92:95], v[156:159], v[236:239], v[92:95]
	v_mfma_f32_16x16x32_bf16 v[88:91], v[164:167], v[236:239], v[88:91]
	v_mfma_f32_16x16x32_bf16 v[84:87], v[156:159], v[244:247], v[84:87]
	v_mfma_f32_16x16x32_bf16 v[80:83], v[164:167], v[244:247], v[80:83]
	v_mfma_f32_16x16x32_bf16 v[124:127], v[160:163], v[224:227], v[124:127]
	v_mfma_f32_16x16x32_bf16 v[120:123], v[168:171], v[224:227], v[120:123]
	v_mfma_f32_16x16x32_bf16 v[116:119], v[160:163], v[232:235], v[116:119]
	v_mfma_f32_16x16x32_bf16 v[112:115], v[168:171], v[232:235], v[112:115]
	v_mfma_f32_16x16x32_bf16 v[92:95], v[160:163], v[240:243], v[92:95]
	v_mfma_f32_16x16x32_bf16 v[88:91], v[168:171], v[240:243], v[88:91]
	v_mfma_f32_16x16x32_bf16 v[84:87], v[160:163], v[248:251], v[84:87]
	v_mfma_f32_16x16x32_bf16 v[80:83], v[168:171], v[248:251], v[80:83]
	s_setprio 0
	s_setprio 1
	v_mfma_f32_16x16x32_bf16 v[108:111], v[172:175], v[220:223], v[108:111]
	v_mfma_f32_16x16x32_bf16 v[104:107], v[212:215], v[220:223], v[104:107]
	v_mfma_f32_16x16x32_bf16 v[100:103], v[172:175], v[228:231], v[100:103]
	v_mfma_f32_16x16x32_bf16 v[96:99], v[212:215], v[228:231], v[96:99]
	v_mfma_f32_16x16x32_bf16 v[76:79], v[172:175], v[236:239], v[76:79]
	v_mfma_f32_16x16x32_bf16 v[72:75], v[212:215], v[236:239], v[72:75]
	v_mfma_f32_16x16x32_bf16 v[68:71], v[172:175], v[244:247], v[68:71]
	v_mfma_f32_16x16x32_bf16 v[64:67], v[212:215], v[244:247], v[64:67]
	v_mfma_f32_16x16x32_bf16 v[108:111], v[176:179], v[224:227], v[108:111]
	v_mfma_f32_16x16x32_bf16 v[104:107], v[216:219], v[224:227], v[104:107]
	v_mfma_f32_16x16x32_bf16 v[100:103], v[176:179], v[232:235], v[100:103]
	v_mfma_f32_16x16x32_bf16 v[96:99], v[216:219], v[232:235], v[96:99]
	v_mfma_f32_16x16x32_bf16 v[76:79], v[176:179], v[240:243], v[76:79]
	v_mfma_f32_16x16x32_bf16 v[72:75], v[216:219], v[240:243], v[72:75]
	v_mfma_f32_16x16x32_bf16 v[68:71], v[176:179], v[248:251], v[68:71]
	v_mfma_f32_16x16x32_bf16 v[64:67], v[216:219], v[248:251], v[64:67]
	s_setprio 0
	s_barrier
	s_add_u32 s50, s48, 0x8000
	s_addc_u32 s51, s49, 0
	s_add_i32 s55, s55, s64
	v_lshl_add_u64 v[252:253], s[50:51], 0, v[130:131]
	s_mov_b32 m0, s55
	ds_read_b128 v[220:223], v199 offset:49152
	ds_read_b128 v[224:227], v199 offset:50176
	ds_read_b128 v[228:231], v199 offset:51200
	ds_read_b128 v[232:235], v199 offset:52224
	ds_read_b128 v[236:239], v199 offset:53248
	ds_read_b128 v[240:243], v199 offset:54272
	ds_read_b128 v[244:247], v199 offset:55296
	ds_read_b128 v[248:251], v199 offset:56320
	global_load_lds_dwordx4 v[252:253], off
	s_add_i32 m0, s55, 0x2000
	s_add_u32 s48, s48, 0xc000
	v_lshl_add_u64 v[252:253], s[50:51], 0, v[134:135]
	s_addc_u32 s49, s49, 0
	s_add_i32 s50, s56, s64
	global_load_lds_dwordx4 v[252:253], off
	v_lshl_add_u64 v[252:253], s[48:49], 0, v[130:131]
	s_mov_b32 m0, s50
	v_lshl_add_u64 v[204:205], v[204:205], 0, s[14:15]
	global_load_lds_dwordx4 v[252:253], off
	v_lshl_add_u64 v[252:253], s[48:49], 0, v[134:135]
	s_add_i32 m0, s50, 0x2000
	s_nop 0
	global_load_lds_dwordx4 v[252:253], off
	s_mov_b32 m0, s74
	s_nop 0
	global_load_lds_dwordx4 v[204:205], off
	v_lshl_add_u64 v[204:205], v[206:207], 0, s[14:15]
	s_mov_b32 m0, s75
	s_nop 0
	global_load_lds_dwordx4 v[204:205], off
	s_waitcnt vmcnt(8)
	s_waitcnt lgkmcnt(0)
	s_barrier
	s_setprio 1
	s_waitcnt lgkmcnt(0)
	v_mfma_f32_16x16x32_bf16 v[60:63], v[156:159], v[220:223], v[60:63]
	v_mfma_f32_16x16x32_bf16 v[56:59], v[164:167], v[220:223], v[56:59]
	v_mfma_f32_16x16x32_bf16 v[52:55], v[156:159], v[228:231], v[52:55]
	v_mfma_f32_16x16x32_bf16 v[48:51], v[164:167], v[228:231], v[48:51]
	v_mfma_f32_16x16x32_bf16 v[28:31], v[156:159], v[236:239], v[28:31]
	v_mfma_f32_16x16x32_bf16 v[24:27], v[164:167], v[236:239], v[24:27]
	v_mfma_f32_16x16x32_bf16 v[20:23], v[156:159], v[244:247], v[20:23]
	v_mfma_f32_16x16x32_bf16 v[12:15], v[164:167], v[244:247], v[12:15]
	v_mfma_f32_16x16x32_bf16 v[60:63], v[160:163], v[224:227], v[60:63]
	v_mfma_f32_16x16x32_bf16 v[56:59], v[168:171], v[224:227], v[56:59]
	v_mfma_f32_16x16x32_bf16 v[52:55], v[160:163], v[232:235], v[52:55]
	v_mfma_f32_16x16x32_bf16 v[48:51], v[168:171], v[232:235], v[48:51]
	v_mfma_f32_16x16x32_bf16 v[28:31], v[160:163], v[240:243], v[28:31]
	v_mfma_f32_16x16x32_bf16 v[24:27], v[168:171], v[240:243], v[24:27]
	v_mfma_f32_16x16x32_bf16 v[20:23], v[160:163], v[248:251], v[20:23]
	v_mfma_f32_16x16x32_bf16 v[12:15], v[168:171], v[248:251], v[12:15]
	s_setprio 0
	s_setprio 1
	v_mfma_f32_16x16x32_bf16 v[44:47], v[172:175], v[220:223], v[44:47]
	v_mfma_f32_16x16x32_bf16 v[40:43], v[212:215], v[220:223], v[40:43]
	v_mfma_f32_16x16x32_bf16 v[36:39], v[172:175], v[228:231], v[36:39]
	v_mfma_f32_16x16x32_bf16 v[32:35], v[212:215], v[228:231], v[32:35]
	v_mfma_f32_16x16x32_bf16 v[16:19], v[172:175], v[236:239], v[16:19]
	v_mfma_f32_16x16x32_bf16 v[8:11], v[212:215], v[236:239], v[8:11]
	v_mfma_f32_16x16x32_bf16 v[4:7], v[172:175], v[244:247], v[4:7]
	v_mfma_f32_16x16x32_bf16 v[0:3], v[212:215], v[244:247], v[0:3]
	v_mfma_f32_16x16x32_bf16 v[44:47], v[176:179], v[224:227], v[44:47]
	v_mfma_f32_16x16x32_bf16 v[40:43], v[216:219], v[224:227], v[40:43]
	v_mfma_f32_16x16x32_bf16 v[36:39], v[176:179], v[232:235], v[36:39]
	v_mfma_f32_16x16x32_bf16 v[32:35], v[216:219], v[232:235], v[32:35]
	v_mfma_f32_16x16x32_bf16 v[16:19], v[176:179], v[240:243], v[16:19]
	v_mfma_f32_16x16x32_bf16 v[8:11], v[216:219], v[240:243], v[8:11]
	v_mfma_f32_16x16x32_bf16 v[4:7], v[176:179], v[248:251], v[4:7]
	v_mfma_f32_16x16x32_bf16 v[0:3], v[216:219], v[248:251], v[0:3]
	s_setprio 0
	s_barrier
	s_add_i32 s54, s54, 2
	s_add_u32 s52, s52, 0x10000
	s_addc_u32 s53, s53, 0
	s_add_u32 s46, s46, 0x100
	s_addc_u32 s47, s47, 0
	s_cmp_gt_u32 s54, 13
	s_cbranch_scc0 .LBB0_2358
	s_and_b64 vcc, exec, s[16:17]
	s_cbranch_vccz .LBB0_2361
	s_barrier

.LBB0_2519:
	ds_read_b128 v[144:147], v178
	ds_read_b128 v[148:151], v178 offset:1024
	ds_read_b128 v[152:155], v178 offset:2048
	ds_read_b128 v[156:159], v178 offset:3072
	ds_read_b128 v[160:163], v179
	ds_read_b128 v[164:167], v179 offset:1024
	ds_read_b128 v[182:185], v179 offset:2048
	ds_read_b128 v[186:189], v179 offset:3072
	s_add_u32 s34, s30, 0x4000
	s_addc_u32 s35, s31, 0
	s_cmp_eq_u32 s64, 40
	s_cselect_b32 s38, s4, s34
	s_cselect_b32 s39, s5, s35
	s_cselect_b32 s36, s28, s62
	s_cselect_b32 s37, s29, s63
	s_add_u32 s34, s38, 0x8000
	s_addc_u32 s35, s39, 0
	v_lshl_add_u64 v[222:223], s[30:31], 0, v[138:139]
	s_add_i32 m0, s42, 0xc000
	ds_read_b128 v[190:193], v180
	ds_read_b128 v[194:197], v180 offset:1024
	ds_read_b128 v[198:201], v180 offset:2048
	ds_read_b128 v[202:205], v180 offset:3072
	ds_read_b128 v[206:209], v180 offset:4096
	ds_read_b128 v[210:213], v180 offset:5120
	ds_read_b128 v[214:217], v180 offset:6144
	ds_read_b128 v[218:221], v180 offset:7168
	global_load_lds_dwordx4 v[222:223], off
	v_lshl_add_u64 v[222:223], s[30:31], 0, v[136:137]
	s_add_i32 m0, s42, 0xe000
	s_nop 0
	global_load_lds_dwordx4 v[222:223], off
	s_waitcnt vmcnt(8)
	s_waitcnt lgkmcnt(0)
	s_barrier
	s_setprio 1
	s_waitcnt lgkmcnt(0)
	v_mfma_f32_16x16x32_bf16 v[124:127], v[144:147], v[190:193], v[124:127]
	v_mfma_f32_16x16x32_bf16 v[120:123], v[152:155], v[190:193], v[120:123]
	v_mfma_f32_16x16x32_bf16 v[116:119], v[144:147], v[198:201], v[116:119]
	v_mfma_f32_16x16x32_bf16 v[112:115], v[152:155], v[198:201], v[112:115]
	v_mfma_f32_16x16x32_bf16 v[92:95], v[144:147], v[206:209], v[92:95]
	v_mfma_f32_16x16x32_bf16 v[88:91], v[152:155], v[206:209], v[88:91]
	v_mfma_f32_16x16x32_bf16 v[84:87], v[144:147], v[214:217], v[84:87]
	v_mfma_f32_16x16x32_bf16 v[80:83], v[152:155], v[214:217], v[80:83]
	v_mfma_f32_16x16x32_bf16 v[124:127], v[148:151], v[194:197], v[124:127]
	v_mfma_f32_16x16x32_bf16 v[120:123], v[156:159], v[194:197], v[120:123]
	v_mfma_f32_16x16x32_bf16 v[116:119], v[148:151], v[202:205], v[116:119]
	v_mfma_f32_16x16x32_bf16 v[112:115], v[156:159], v[202:205], v[112:115]
	v_mfma_f32_16x16x32_bf16 v[92:95], v[148:151], v[210:213], v[92:95]
	v_mfma_f32_16x16x32_bf16 v[88:91], v[156:159], v[210:213], v[88:91]
	v_mfma_f32_16x16x32_bf16 v[84:87], v[148:151], v[218:221], v[84:87]
	v_mfma_f32_16x16x32_bf16 v[80:83], v[156:159], v[218:221], v[80:83]
	s_setprio 0
	s_setprio 1
	v_mfma_f32_16x16x32_bf16 v[108:111], v[160:163], v[190:193], v[108:111]
	v_mfma_f32_16x16x32_bf16 v[104:107], v[182:185], v[190:193], v[104:107]
	v_mfma_f32_16x16x32_bf16 v[100:103], v[160:163], v[198:201], v[100:103]
	v_mfma_f32_16x16x32_bf16 v[96:99], v[182:185], v[198:201], v[96:99]
	v_mfma_f32_16x16x32_bf16 v[76:79], v[160:163], v[206:209], v[76:79]
	v_mfma_f32_16x16x32_bf16 v[72:75], v[182:185], v[206:209], v[72:75]
	v_mfma_f32_16x16x32_bf16 v[68:71], v[160:163], v[214:217], v[68:71]
	v_mfma_f32_16x16x32_bf16 v[64:67], v[182:185], v[214:217], v[64:67]
	v_mfma_f32_16x16x32_bf16 v[108:111], v[164:167], v[194:197], v[108:111]
	v_mfma_f32_16x16x32_bf16 v[104:107], v[186:189], v[194:197], v[104:107]
	v_mfma_f32_16x16x32_bf16 v[100:103], v[164:167], v[202:205], v[100:103]
	v_mfma_f32_16x16x32_bf16 v[96:99], v[186:189], v[202:205], v[96:99]
	v_mfma_f32_16x16x32_bf16 v[76:79], v[164:167], v[210:213], v[76:79]
	v_mfma_f32_16x16x32_bf16 v[72:75], v[186:189], v[210:213], v[72:75]
	v_mfma_f32_16x16x32_bf16 v[68:71], v[164:167], v[218:221], v[68:71]
	v_mfma_f32_16x16x32_bf16 v[64:67], v[186:189], v[218:221], v[64:67]
	s_setprio 0
	s_barrier
	s_add_i32 s65, s55, s41
	v_lshl_add_u64 v[222:223], s[36:37], 0, v[128:129]
	s_mov_b32 m0, s65
	ds_read_b128 v[190:193], v180 offset:16384
	ds_read_b128 v[194:197], v180 offset:17408
	ds_read_b128 v[198:201], v180 offset:18432
	ds_read_b128 v[202:205], v180 offset:19456
	ds_read_b128 v[206:209], v180 offset:20480
	ds_read_b128 v[210:213], v180 offset:21504
	ds_read_b128 v[214:217], v180 offset:22528
	ds_read_b128 v[218:221], v180 offset:23552
	global_load_lds_dwordx4 v[222:223], off
	s_add_i32 m0, s65, 0x2000
	s_add_u32 s66, s36, 0x4000
	v_lshl_add_u64 v[222:223], s[36:37], 0, v[130:131]
	s_addc_u32 s67, s37, 0
	s_add_i32 s65, s56, s41
	global_load_lds_dwordx4 v[222:223], off
	v_lshl_add_u64 v[222:223], s[66:67], 0, v[128:129]
	s_mov_b32 m0, s65
	s_nop 0
	global_load_lds_dwordx4 v[222:223], off
	v_lshl_add_u64 v[222:223], s[66:67], 0, v[130:131]
	s_add_i32 m0, s65, 0x2000
	s_nop 0
	global_load_lds_dwordx4 v[222:223], off
	v_lshl_add_u64 v[222:223], s[38:39], 0, v[128:129]
	v_lshl_add_u64 v[222:223], s[38:39], 0, v[130:131]
	s_waitcnt vmcnt(6)
	s_waitcnt lgkmcnt(0)
	s_barrier
	s_setprio 1
	s_waitcnt lgkmcnt(0)
	v_mfma_f32_16x16x32_bf16 v[60:63], v[144:147], v[190:193], v[60:63]
	v_mfma_f32_16x16x32_bf16 v[56:59], v[152:155], v[190:193], v[56:59]
	v_mfma_f32_16x16x32_bf16 v[52:55], v[144:147], v[198:201], v[52:55]
	v_mfma_f32_16x16x32_bf16 v[48:51], v[152:155], v[198:201], v[48:51]
	v_mfma_f32_16x16x32_bf16 v[28:31], v[144:147], v[206:209], v[28:31]
	v_mfma_f32_16x16x32_bf16 v[24:27], v[152:155], v[206:209], v[24:27]
	v_mfma_f32_16x16x32_bf16 v[20:23], v[144:147], v[214:217], v[20:23]
	v_mfma_f32_16x16x32_bf16 v[12:15], v[152:155], v[214:217], v[12:15]
	v_mfma_f32_16x16x32_bf16 v[60:63], v[148:151], v[194:197], v[60:63]
	v_mfma_f32_16x16x32_bf16 v[56:59], v[156:159], v[194:197], v[56:59]
	v_mfma_f32_16x16x32_bf16 v[52:55], v[148:151], v[202:205], v[52:55]
	v_mfma_f32_16x16x32_bf16 v[48:51], v[156:159], v[202:205], v[48:51]
	v_mfma_f32_16x16x32_bf16 v[28:31], v[148:151], v[210:213], v[28:31]
	v_mfma_f32_16x16x32_bf16 v[24:27], v[156:159], v[210:213], v[24:27]
	v_mfma_f32_16x16x32_bf16 v[20:23], v[148:151], v[218:221], v[20:23]
	v_mfma_f32_16x16x32_bf16 v[12:15], v[156:159], v[218:221], v[12:15]
	s_setprio 0
	s_setprio 1
	v_mfma_f32_16x16x32_bf16 v[44:47], v[160:163], v[190:193], v[44:47]
	v_mfma_f32_16x16x32_bf16 v[40:43], v[182:185], v[190:193], v[40:43]
	v_mfma_f32_16x16x32_bf16 v[36:39], v[160:163], v[198:201], v[36:39]
	v_mfma_f32_16x16x32_bf16 v[32:35], v[182:185], v[198:201], v[32:35]
	v_mfma_f32_16x16x32_bf16 v[16:19], v[160:163], v[206:209], v[16:19]
	v_mfma_f32_16x16x32_bf16 v[8:11], v[182:185], v[206:209], v[8:11]
	v_mfma_f32_16x16x32_bf16 v[4:7], v[160:163], v[214:217], v[4:7]
	v_mfma_f32_16x16x32_bf16 v[0:3], v[182:185], v[214:217], v[0:3]
	v_mfma_f32_16x16x32_bf16 v[44:47], v[164:167], v[194:197], v[44:47]
	v_mfma_f32_16x16x32_bf16 v[40:43], v[186:189], v[194:197], v[40:43]
	v_mfma_f32_16x16x32_bf16 v[36:39], v[164:167], v[202:205], v[36:39]
	v_mfma_f32_16x16x32_bf16 v[32:35], v[186:189], v[202:205], v[32:35]
	v_mfma_f32_16x16x32_bf16 v[16:19], v[164:167], v[210:213], v[16:19]
	v_mfma_f32_16x16x32_bf16 v[8:11], v[186:189], v[210:213], v[8:11]
	v_mfma_f32_16x16x32_bf16 v[4:7], v[164:167], v[218:221], v[4:7]
	v_mfma_f32_16x16x32_bf16 v[0:3], v[186:189], v[218:221], v[0:3]
	s_setprio 0
	s_barrier
	s_mov_b32 m0, s42
	s_nop 0
	global_load_lds_dwordx4 v128, s[38:39]
	s_mov_b32 m0, s43
	s_nop 0
	global_load_lds_dwordx4 v130, s[38:39]
	s_add_i32 s65, 0, 0x18000
	s_add_i32 s66, 0, 0x1c000
	v_add_u32_e32 v156, s65, v170
	v_add_u32_e32 v186, s66, v170
	ds_read_b128 v[144:147], v156
	ds_read_b128 v[148:151], v156 offset:1024
	ds_read_b128 v[152:155], v156 offset:2048
	ds_read_b128 v[156:159], v156 offset:3072
	ds_read_b128 v[160:163], v186
	ds_read_b128 v[164:167], v186 offset:1024
	ds_read_b128 v[182:185], v186 offset:2048
	ds_read_b128 v[186:189], v186 offset:3072
	s_add_u32 s38, s38, 0x4000
	s_addc_u32 s39, s39, 0
	s_mov_b32 m0, s44
	v_lshl_add_u64 v[222:223], s[38:39], 0, v[128:129]
	ds_read_b128 v[190:193], v180 offset:32768
	ds_read_b128 v[194:197], v180 offset:33792
	ds_read_b128 v[198:201], v180 offset:34816
	ds_read_b128 v[202:205], v180 offset:35840
	ds_read_b128 v[206:209], v180 offset:36864
	ds_read_b128 v[210:213], v180 offset:37888
	ds_read_b128 v[214:217], v180 offset:38912
	ds_read_b128 v[218:221], v180 offset:39936
	global_load_lds_dwordx4 v[222:223], off
	v_lshl_add_u64 v[222:223], s[38:39], 0, v[130:131]
	s_mov_b32 m0, s45
	s_nop 0
	global_load_lds_dwordx4 v[222:223], off
	s_waitcnt vmcnt(8)
	s_waitcnt lgkmcnt(0)
	s_barrier
	s_setprio 1
	s_waitcnt lgkmcnt(0)
	v_mfma_f32_16x16x32_bf16 v[124:127], v[144:147], v[190:193], v[124:127]
	v_mfma_f32_16x16x32_bf16 v[120:123], v[152:155], v[190:193], v[120:123]
	v_mfma_f32_16x16x32_bf16 v[116:119], v[144:147], v[198:201], v[116:119]
	v_mfma_f32_16x16x32_bf16 v[112:115], v[152:155], v[198:201], v[112:115]
	v_mfma_f32_16x16x32_bf16 v[92:95], v[144:147], v[206:209], v[92:95]
	v_mfma_f32_16x16x32_bf16 v[88:91], v[152:155], v[206:209], v[88:91]
	v_mfma_f32_16x16x32_bf16 v[84:87], v[144:147], v[214:217], v[84:87]
	v_mfma_f32_16x16x32_bf16 v[80:83], v[152:155], v[214:217], v[80:83]
	v_mfma_f32_16x16x32_bf16 v[124:127], v[148:151], v[194:197], v[124:127]
	v_mfma_f32_16x16x32_bf16 v[120:123], v[156:159], v[194:197], v[120:123]
	v_mfma_f32_16x16x32_bf16 v[116:119], v[148:151], v[202:205], v[116:119]
	v_mfma_f32_16x16x32_bf16 v[112:115], v[156:159], v[202:205], v[112:115]
	v_mfma_f32_16x16x32_bf16 v[92:95], v[148:151], v[210:213], v[92:95]
	v_mfma_f32_16x16x32_bf16 v[88:91], v[156:159], v[210:213], v[88:91]
	v_mfma_f32_16x16x32_bf16 v[84:87], v[148:151], v[218:221], v[84:87]
	v_mfma_f32_16x16x32_bf16 v[80:83], v[156:159], v[218:221], v[80:83]
	s_setprio 0
	s_setprio 1
	v_mfma_f32_16x16x32_bf16 v[108:111], v[160:163], v[190:193], v[108:111]
	v_mfma_f32_16x16x32_bf16 v[104:107], v[182:185], v[190:193], v[104:107]
	v_mfma_f32_16x16x32_bf16 v[100:103], v[160:163], v[198:201], v[100:103]
	v_mfma_f32_16x16x32_bf16 v[96:99], v[182:185], v[198:201], v[96:99]
	v_mfma_f32_16x16x32_bf16 v[76:79], v[160:163], v[206:209], v[76:79]
	v_mfma_f32_16x16x32_bf16 v[72:75], v[182:185], v[206:209], v[72:75]
	v_mfma_f32_16x16x32_bf16 v[68:71], v[160:163], v[214:217], v[68:71]
	v_mfma_f32_16x16x32_bf16 v[64:67], v[182:185], v[214:217], v[64:67]
	v_mfma_f32_16x16x32_bf16 v[108:111], v[164:167], v[194:197], v[108:111]
	v_mfma_f32_16x16x32_bf16 v[104:107], v[186:189], v[194:197], v[104:107]
	v_mfma_f32_16x16x32_bf16 v[100:103], v[164:167], v[202:205], v[100:103]
	v_mfma_f32_16x16x32_bf16 v[96:99], v[186:189], v[202:205], v[96:99]
	v_mfma_f32_16x16x32_bf16 v[76:79], v[164:167], v[210:213], v[76:79]
	v_mfma_f32_16x16x32_bf16 v[72:75], v[186:189], v[210:213], v[72:75]
	v_mfma_f32_16x16x32_bf16 v[68:71], v[164:167], v[218:221], v[68:71]
	v_mfma_f32_16x16x32_bf16 v[64:67], v[186:189], v[218:221], v[64:67]
	s_setprio 0
	s_barrier
	s_add_u32 s38, s36, 0x8000
	s_addc_u32 s39, s37, 0
	s_add_i32 s65, s65, s41
	v_lshl_add_u64 v[222:223], s[38:39], 0, v[128:129]
	s_mov_b32 m0, s65
	ds_read_b128 v[190:193], v180 offset:49152
	ds_read_b128 v[194:197], v180 offset:50176
	ds_read_b128 v[198:201], v180 offset:51200
	ds_read_b128 v[202:205], v180 offset:52224
	ds_read_b128 v[206:209], v180 offset:53248
	ds_read_b128 v[210:213], v180 offset:54272
	ds_read_b128 v[214:217], v180 offset:55296
	ds_read_b128 v[218:221], v180 offset:56320
	global_load_lds_dwordx4 v[222:223], off
	s_add_i32 m0, s65, 0x2000
	s_add_u32 s36, s36, 0xc000
	v_lshl_add_u64 v[222:223], s[38:39], 0, v[130:131]
	s_addc_u32 s37, s37, 0
	s_add_i32 s38, s66, s41
	global_load_lds_dwordx4 v[222:223], off
	v_lshl_add_u64 v[222:223], s[36:37], 0, v[128:129]
	s_mov_b32 m0, s38
	s_nop 0
	global_load_lds_dwordx4 v[222:223], off
	v_lshl_add_u64 v[222:223], s[36:37], 0, v[130:131]
	s_add_i32 m0, s38, 0x2000
	s_nop 0
	global_load_lds_dwordx4 v[222:223], off
	v_lshl_add_u64 v[222:223], s[34:35], 0, v[128:129]
	s_mov_b32 m0, s51
	s_nop 0
	global_load_lds_dwordx4 v[222:223], off
	v_lshl_add_u64 v[222:223], s[34:35], 0, v[130:131]
	s_mov_b32 m0, s52
	s_nop 0
	global_load_lds_dwordx4 v[222:223], off
	s_waitcnt vmcnt(8)
	s_waitcnt lgkmcnt(0)
	s_barrier
	s_setprio 1
	s_waitcnt lgkmcnt(0)
	v_mfma_f32_16x16x32_bf16 v[60:63], v[144:147], v[190:193], v[60:63]
	v_mfma_f32_16x16x32_bf16 v[56:59], v[152:155], v[190:193], v[56:59]
	v_mfma_f32_16x16x32_bf16 v[52:55], v[144:147], v[198:201], v[52:55]
	v_mfma_f32_16x16x32_bf16 v[48:51], v[152:155], v[198:201], v[48:51]
	v_mfma_f32_16x16x32_bf16 v[28:31], v[144:147], v[206:209], v[28:31]
	v_mfma_f32_16x16x32_bf16 v[24:27], v[152:155], v[206:209], v[24:27]
	v_mfma_f32_16x16x32_bf16 v[20:23], v[144:147], v[214:217], v[20:23]
	v_mfma_f32_16x16x32_bf16 v[12:15], v[152:155], v[214:217], v[12:15]
	v_mfma_f32_16x16x32_bf16 v[60:63], v[148:151], v[194:197], v[60:63]
	v_mfma_f32_16x16x32_bf16 v[56:59], v[156:159], v[194:197], v[56:59]
	v_mfma_f32_16x16x32_bf16 v[52:55], v[148:151], v[202:205], v[52:55]
	v_mfma_f32_16x16x32_bf16 v[48:51], v[156:159], v[202:205], v[48:51]
	v_mfma_f32_16x16x32_bf16 v[28:31], v[148:151], v[210:213], v[28:31]
	v_mfma_f32_16x16x32_bf16 v[24:27], v[156:159], v[210:213], v[24:27]
	v_mfma_f32_16x16x32_bf16 v[20:23], v[148:151], v[218:221], v[20:23]
	v_mfma_f32_16x16x32_bf16 v[12:15], v[156:159], v[218:221], v[12:15]
	s_setprio 0
	s_setprio 1
	v_mfma_f32_16x16x32_bf16 v[44:47], v[160:163], v[190:193], v[44:47]
	v_mfma_f32_16x16x32_bf16 v[40:43], v[182:185], v[190:193], v[40:43]
	v_mfma_f32_16x16x32_bf16 v[36:39], v[160:163], v[198:201], v[36:39]
	v_mfma_f32_16x16x32_bf16 v[32:35], v[182:185], v[198:201], v[32:35]
	v_mfma_f32_16x16x32_bf16 v[16:19], v[160:163], v[206:209], v[16:19]
	v_mfma_f32_16x16x32_bf16 v[8:11], v[182:185], v[206:209], v[8:11]
	v_mfma_f32_16x16x32_bf16 v[4:7], v[160:163], v[214:217], v[4:7]
	v_mfma_f32_16x16x32_bf16 v[0:3], v[182:185], v[214:217], v[0:3]
	v_mfma_f32_16x16x32_bf16 v[44:47], v[164:167], v[194:197], v[44:47]
	v_mfma_f32_16x16x32_bf16 v[40:43], v[186:189], v[194:197], v[40:43]
	v_mfma_f32_16x16x32_bf16 v[36:39], v[164:167], v[202:205], v[36:39]
	v_mfma_f32_16x16x32_bf16 v[32:35], v[186:189], v[202:205], v[32:35]
	v_mfma_f32_16x16x32_bf16 v[16:19], v[164:167], v[210:213], v[16:19]
	v_mfma_f32_16x16x32_bf16 v[8:11], v[186:189], v[210:213], v[8:11]
	v_mfma_f32_16x16x32_bf16 v[4:7], v[164:167], v[218:221], v[4:7]
	v_mfma_f32_16x16x32_bf16 v[0:3], v[186:189], v[218:221], v[0:3]
	s_setprio 0
	s_barrier
	s_add_i32 s64, s64, 2
	s_add_u32 s62, s62, 0x10000
	s_addc_u32 s63, s63, 0
	s_add_u32 s30, s30, 0x10000
	s_addc_u32 s31, s31, 0
	s_cmp_gt_u32 s64, 41
	s_cbranch_scc0 .LBB0_2519
	s_and_b64 vcc, exec, s[14:15]
	s_cbranch_vccz .LBB0_2522
	s_barrier
